# strategy 7: GEMM K-loop LDS-DMA addressed as SGPR base + 32-bit VGPR offset (8 of 16 per-piece 64-bit VALU adds removed per iteration), on top of v35
# speedup vs baseline: 1.0134x; 1.0032x over previous
; #define PG8_STAGE(bufoff, gbase, voff) do { _Pragma("unroll") for (int _i = 0; _i < 2; ++_i) \
;         __builtin_amdgcn_global_load_lds((const unsigned*)((const char*)(gbase) + (voff)[_i]), (PG8_LAS unsigned*)(lds + (bufoff) + ldsw + _i * 8192), 16, 0, 0); } while (0)
; #define PG8_LDA(dst, b, h) do { _Pragma("unroll") for (int m = 0; m < 4; ++m) _Pragma("unroll") for (int k = 0; k < 2; ++k) dst[m][k] = *(const PG8_LAS bf16x8*)(lds + PG8_SA(b, h) + aoff + m * 2048 + k * 1024); } while (0)
; #define PG8_LDB(dst, b, h) do { _Pragma("unroll") for (int n = 0; n < 2; ++n) _Pragma("unroll") for (int k = 0; k < 2; ++k) dst[n][k] = *(const PG8_LAS bf16x8*)(lds + PG8_SB(b, h) + boff + n * 2048 + k * 1024); } while (0)
; #define PG8_MMA(ai, bj, At, Bt) do { __builtin_amdgcn_s_setprio(1); _Pragma("unroll") for (int m = 0; m < 4; ++m) _Pragma("unroll") for (int n = 0; n < 2; ++n) _Pragma("unroll") for (int k = 0; k < 2; ++k) \
;         acc[ai][bj][m][n] = __builtin_amdgcn_mfma_f32_16x16x32_bf16(Bt[n][k], At[m][k], acc[ai][bj][m][n], 0, 0, 0); __builtin_amdgcn_s_setprio(0); } while (0)
; #define PG8_WAIT_V(n) asm volatile("s_waitcnt vmcnt(" #n ")" ::: "memory")
; #define PG8_WAIT_L(n) asm volatile("s_waitcnt lgkmcnt(" #n ")" ::: "memory")
; #define PG8_BAR __builtin_amdgcn_s_barrier()
; #define PG8_SCHED __builtin_amdgcn_sched_barrier(0)
; template <class Epi, class Sched, bool ALIGN_EPI = false, bool SP2 = false>
; __device__ __forceinline__ void gemm_phase(PG8_LAS unsigned char* lds, const Gemm g, const Sched& S, const Epi& E) {
;     ...
;             PG8_LDB(B0, 0, 0); PG8_LDB(B1, 0, 1); PG8_SCHED; PG8_LDA(At, 0, 0); PG8_STAGE(PG8_SA(1, 1), a1 + hstep, voffA);
;             PG8_WAIT_V(8); PG8_WAIT_L(0); PG8_BAR; PG8_MMA(0, 0, At, B0); PG8_MMA(0, 1, At, B1); PG8_BAR; PG8_SCHED;
;             PG8_LDA(At, 0, 1); PG8_STAGE(PG8_SB(0, 0), b2, voffB); PG8_STAGE(PG8_SB(0, 1), b2 + hstep, voffB); PG8_STAGE(PG8_SA(0, 0), a2, voffA);
;             PG8_WAIT_V(8); PG8_WAIT_L(0); PG8_BAR; PG8_MMA(1, 0, At, B0); PG8_MMA(1, 1, At, B1); PG8_BAR; PG8_SCHED;
.LBB0_66:
	ds_read_b128 v[152:155], v149
	ds_read_b128 v[156:159], v149 offset:1024
	ds_read_b128 v[160:163], v149 offset:2048
	ds_read_b128 v[164:167], v149 offset:3072
	ds_read_b128 v[168:171], v150
	ds_read_b128 v[172:175], v150 offset:1024
	ds_read_b128 v[176:179], v150 offset:2048
	ds_read_b128 v[180:183], v150 offset:3072
	s_add_u32 s42, s40, 0xfff80080
	s_addc_u32 s43, s41, -1
	s_cmp_eq_u32 s68, 28
	s_cselect_b32 s45, s35, s43
	s_cselect_b32 s44, s63, s42
	s_cselect_b32 s43, s31, s67
	s_cselect_b32 s42, s64, s65
	s_nop 0
	s_add_i32 m0, s29, 0xc000
	ds_read_b128 v[184:187], v151
	ds_read_b128 v[188:191], v151 offset:1024
	ds_read_b128 v[192:195], v151 offset:2048
	ds_read_b128 v[196:199], v151 offset:3072
	ds_read_b128 v[200:203], v151 offset:4096
	ds_read_b128 v[204:207], v151 offset:5120
	ds_read_b128 v[208:211], v151 offset:6144
	ds_read_b128 v[212:215], v151 offset:7168
	global_load_lds_dwordx4 v136, s[40:41]
	s_nop 0
	s_add_i32 m0, s29, 0xe000
	s_nop 0
	global_load_lds_dwordx4 v138, s[40:41]
	s_waitcnt vmcnt(8)
	s_waitcnt lgkmcnt(0)
	s_barrier
	s_setprio 1
	s_waitcnt lgkmcnt(0)
	v_mfma_f32_16x16x32_bf16 v[124:127], v[152:155], v[184:187], v[124:127]
	v_mfma_f32_16x16x32_bf16 v[120:123], v[160:163], v[184:187], v[120:123]
	v_mfma_f32_16x16x32_bf16 v[116:119], v[152:155], v[192:195], v[116:119]
	v_mfma_f32_16x16x32_bf16 v[112:115], v[160:163], v[192:195], v[112:115]
	v_mfma_f32_16x16x32_bf16 v[100:103], v[152:155], v[200:203], v[100:103]
	v_mfma_f32_16x16x32_bf16 v[96:99], v[160:163], v[200:203], v[96:99]
	v_mfma_f32_16x16x32_bf16 v[84:87], v[152:155], v[208:211], v[84:87]
	v_mfma_f32_16x16x32_bf16 v[80:83], v[160:163], v[208:211], v[80:83]
	v_mfma_f32_16x16x32_bf16 v[124:127], v[156:159], v[188:191], v[124:127]
	v_mfma_f32_16x16x32_bf16 v[120:123], v[164:167], v[188:191], v[120:123]
	v_mfma_f32_16x16x32_bf16 v[116:119], v[156:159], v[196:199], v[116:119]
	v_mfma_f32_16x16x32_bf16 v[112:115], v[164:167], v[196:199], v[112:115]
	v_mfma_f32_16x16x32_bf16 v[100:103], v[156:159], v[204:207], v[100:103]
	v_mfma_f32_16x16x32_bf16 v[96:99], v[164:167], v[204:207], v[96:99]
	v_mfma_f32_16x16x32_bf16 v[84:87], v[156:159], v[212:215], v[84:87]
	v_mfma_f32_16x16x32_bf16 v[80:83], v[164:167], v[212:215], v[80:83]
	s_setprio 0
	s_setprio 1
	v_mfma_f32_16x16x32_bf16 v[108:111], v[168:171], v[184:187], v[108:111]
	v_mfma_f32_16x16x32_bf16 v[104:107], v[176:179], v[184:187], v[104:107]
	v_mfma_f32_16x16x32_bf16 v[92:95], v[168:171], v[192:195], v[92:95]
	v_mfma_f32_16x16x32_bf16 v[88:91], v[176:179], v[192:195], v[88:91]
	v_mfma_f32_16x16x32_bf16 v[76:79], v[168:171], v[200:203], v[76:79]
	v_mfma_f32_16x16x32_bf16 v[72:75], v[176:179], v[200:203], v[72:75]
	v_mfma_f32_16x16x32_bf16 v[68:71], v[168:171], v[208:211], v[68:71]
	v_mfma_f32_16x16x32_bf16 v[64:67], v[176:179], v[208:211], v[64:67]
	v_mfma_f32_16x16x32_bf16 v[108:111], v[172:175], v[188:191], v[108:111]
	v_mfma_f32_16x16x32_bf16 v[104:107], v[180:183], v[188:191], v[104:107]
	v_mfma_f32_16x16x32_bf16 v[92:95], v[172:175], v[196:199], v[92:95]
	v_mfma_f32_16x16x32_bf16 v[88:91], v[180:183], v[196:199], v[88:91]
	v_mfma_f32_16x16x32_bf16 v[76:79], v[172:175], v[204:207], v[76:79]
	v_mfma_f32_16x16x32_bf16 v[72:75], v[180:183], v[204:207], v[72:75]
	v_mfma_f32_16x16x32_bf16 v[68:71], v[172:175], v[212:215], v[68:71]
	v_mfma_f32_16x16x32_bf16 v[64:67], v[180:183], v[212:215], v[64:67]
	s_setprio 0
	s_barrier
	s_add_i32 s69, s59, s48
	v_lshl_add_u64 v[216:217], s[42:43], 0, v[132:133]
	s_mov_b32 m0, s69
	ds_read_b128 v[184:187], v151 offset:16384
	ds_read_b128 v[188:191], v151 offset:17408
	ds_read_b128 v[192:195], v151 offset:18432
	ds_read_b128 v[196:199], v151 offset:19456
	ds_read_b128 v[200:203], v151 offset:20480
	ds_read_b128 v[204:207], v151 offset:21504
	ds_read_b128 v[208:211], v151 offset:22528
	ds_read_b128 v[212:215], v151 offset:23552
	global_load_lds_dwordx4 v[216:217], off
	s_add_i32 m0, s69, 0x2000
	s_add_u32 s70, s42, 0x80000
	v_lshl_add_u64 v[218:219], s[42:43], 0, v[128:129]
	s_addc_u32 s71, s43, 0
	s_add_i32 s69, s60, s48
	global_load_lds_dwordx4 v[218:219], off
	s_nop 0
	s_mov_b32 m0, s69
	v_lshl_add_u64 v[222:223], s[44:45], 0, v[130:131]
	global_load_lds_dwordx4 v132, s[70:71]
	s_nop 0
	s_add_i32 m0, s69, 0x2000
	s_nop 0
	global_load_lds_dwordx4 v128, s[70:71]
	v_lshl_add_u64 v[220:221], s[44:45], 0, v[134:135]
	s_mov_b32 m0, s29
	s_nop 0
	global_load_lds_dwordx4 v[220:221], off
	s_mov_b32 m0, s51
	s_nop 0
	global_load_lds_dwordx4 v[222:223], off
	s_waitcnt vmcnt(8)
	s_waitcnt lgkmcnt(0)
	s_barrier
; #define PG8_STAGE(bufoff, gbase, voff) do { _Pragma("unroll") for (int _i = 0; _i < 2; ++_i) \
;         __builtin_amdgcn_global_load_lds((const unsigned*)((const char*)(gbase) + (voff)[_i]), (PG8_LAS unsigned*)(lds + (bufoff) + ldsw + _i * 8192), 16, 0, 0); } while (0)
; #define PG8_LDA(dst, b, h) do { _Pragma("unroll") for (int m = 0; m < 4; ++m) _Pragma("unroll") for (int k = 0; k < 2; ++k) dst[m][k] = *(const PG8_LAS bf16x8*)(lds + PG8_SA(b, h) + aoff + m * 2048 + k * 1024); } while (0)
; #define PG8_LDB(dst, b, h) do { _Pragma("unroll") for (int n = 0; n < 2; ++n) _Pragma("unroll") for (int k = 0; k < 2; ++k) dst[n][k] = *(const PG8_LAS bf16x8*)(lds + PG8_SB(b, h) + boff + n * 2048 + k * 1024); } while (0)
; #define PG8_MMA(ai, bj, At, Bt) do { __builtin_amdgcn_s_setprio(1); _Pragma("unroll") for (int m = 0; m < 4; ++m) _Pragma("unroll") for (int n = 0; n < 2; ++n) _Pragma("unroll") for (int k = 0; k < 2; ++k) \
;         acc[ai][bj][m][n] = __builtin_amdgcn_mfma_f32_16x16x32_bf16(Bt[n][k], At[m][k], acc[ai][bj][m][n], 0, 0, 0); __builtin_amdgcn_s_setprio(0); } while (0)
; #define PG8_WAIT_V(n) asm volatile("s_waitcnt vmcnt(" #n ")" ::: "memory")
; #define PG8_WAIT_L(n) asm volatile("s_waitcnt lgkmcnt(" #n ")" ::: "memory")
; #define PG8_BAR __builtin_amdgcn_s_barrier()
; #define PG8_SCHED __builtin_amdgcn_sched_barrier(0)
; template <class Epi, class Sched, bool ALIGN_EPI = false, bool SP2 = false>
; __device__ __forceinline__ void gemm_phase(PG8_LAS unsigned char* lds, const Gemm g, const Sched& S, const Epi& E) {
;     ...
;             PG8_WAIT_V(8); PG8_WAIT_L(0); PG8_BAR; PG8_MMA(1, 0, At, B0); PG8_MMA(1, 1, At, B1); PG8_BAR; PG8_SCHED;
;             PG8_LDB(B0, 1, 0); PG8_LDB(B1, 1, 1); PG8_SCHED; PG8_LDA(At, 1, 0); PG8_STAGE(PG8_SA(0, 1), a2 + hstep, voffA);
;             PG8_WAIT_V(8); PG8_WAIT_L(0); PG8_BAR; PG8_MMA(0, 0, At, B0); PG8_MMA(0, 1, At, B1); PG8_BAR; PG8_SCHED;
	s_setprio 1
	s_waitcnt lgkmcnt(0)
	v_mfma_f32_16x16x32_bf16 v[60:63], v[152:155], v[184:187], v[60:63]
	v_mfma_f32_16x16x32_bf16 v[56:59], v[160:163], v[184:187], v[56:59]
	v_mfma_f32_16x16x32_bf16 v[52:55], v[152:155], v[192:195], v[52:55]
	v_mfma_f32_16x16x32_bf16 v[48:51], v[160:163], v[192:195], v[48:51]
	v_mfma_f32_16x16x32_bf16 v[36:39], v[152:155], v[200:203], v[36:39]
	v_mfma_f32_16x16x32_bf16 v[32:35], v[160:163], v[200:203], v[32:35]
	v_mfma_f32_16x16x32_bf16 v[20:23], v[152:155], v[208:211], v[20:23]
	v_mfma_f32_16x16x32_bf16 v[16:19], v[160:163], v[208:211], v[16:19]
	v_mfma_f32_16x16x32_bf16 v[60:63], v[156:159], v[188:191], v[60:63]
	v_mfma_f32_16x16x32_bf16 v[56:59], v[164:167], v[188:191], v[56:59]
	v_mfma_f32_16x16x32_bf16 v[52:55], v[156:159], v[196:199], v[52:55]
	v_mfma_f32_16x16x32_bf16 v[48:51], v[164:167], v[196:199], v[48:51]
	v_mfma_f32_16x16x32_bf16 v[36:39], v[156:159], v[204:207], v[36:39]
	v_mfma_f32_16x16x32_bf16 v[32:35], v[164:167], v[204:207], v[32:35]
	v_mfma_f32_16x16x32_bf16 v[20:23], v[156:159], v[212:215], v[20:23]
	v_mfma_f32_16x16x32_bf16 v[16:19], v[164:167], v[212:215], v[16:19]
	s_setprio 0
	s_setprio 1
	v_mfma_f32_16x16x32_bf16 v[44:47], v[168:171], v[184:187], v[44:47]
	v_mfma_f32_16x16x32_bf16 v[40:43], v[176:179], v[184:187], v[40:43]
	v_mfma_f32_16x16x32_bf16 v[28:31], v[168:171], v[192:195], v[28:31]
	v_mfma_f32_16x16x32_bf16 v[24:27], v[176:179], v[192:195], v[24:27]
	v_mfma_f32_16x16x32_bf16 v[12:15], v[168:171], v[200:203], v[12:15]
	v_mfma_f32_16x16x32_bf16 v[8:11], v[176:179], v[200:203], v[8:11]
	v_mfma_f32_16x16x32_bf16 v[4:7], v[168:171], v[208:211], v[4:7]
	v_mfma_f32_16x16x32_bf16 v[0:3], v[176:179], v[208:211], v[0:3]
	v_mfma_f32_16x16x32_bf16 v[44:47], v[172:175], v[188:191], v[44:47]
	v_mfma_f32_16x16x32_bf16 v[40:43], v[180:183], v[188:191], v[40:43]
	v_mfma_f32_16x16x32_bf16 v[28:31], v[172:175], v[196:199], v[28:31]
	v_mfma_f32_16x16x32_bf16 v[24:27], v[180:183], v[196:199], v[24:27]
	v_mfma_f32_16x16x32_bf16 v[12:15], v[172:175], v[204:207], v[12:15]
	v_mfma_f32_16x16x32_bf16 v[8:11], v[180:183], v[204:207], v[8:11]
	v_mfma_f32_16x16x32_bf16 v[4:7], v[172:175], v[212:215], v[4:7]
	v_mfma_f32_16x16x32_bf16 v[0:3], v[180:183], v[212:215], v[0:3]
	s_setprio 0
	s_barrier
	s_add_i32 s69, 0, 0x18000
	s_add_i32 s70, 0, 0x1c000
	v_add_u32_e32 v164, s69, v147
	v_add_u32_e32 v180, s70, v147
	ds_read_b128 v[152:155], v164
	ds_read_b128 v[156:159], v164 offset:1024
	ds_read_b128 v[160:163], v164 offset:2048
	ds_read_b128 v[164:167], v164 offset:3072
	ds_read_b128 v[168:171], v180
	ds_read_b128 v[172:175], v180 offset:1024
	ds_read_b128 v[176:179], v180 offset:2048
	ds_read_b128 v[180:183], v180 offset:3072
	s_add_u32 s44, s44, 0x80000
	s_addc_u32 s45, s45, 0
	s_mov_b32 m0, s52
	s_nop 0
	ds_read_b128 v[184:187], v151 offset:32768
	ds_read_b128 v[188:191], v151 offset:33792
	ds_read_b128 v[192:195], v151 offset:34816
	ds_read_b128 v[196:199], v151 offset:35840
	ds_read_b128 v[200:203], v151 offset:36864
	ds_read_b128 v[204:207], v151 offset:37888
	ds_read_b128 v[208:211], v151 offset:38912
	ds_read_b128 v[212:215], v151 offset:39936
	global_load_lds_dwordx4 v134, s[44:45]
	s_nop 0
	s_mov_b32 m0, s53
	s_nop 0
	global_load_lds_dwordx4 v130, s[44:45]
	s_waitcnt vmcnt(8)
	s_waitcnt lgkmcnt(0)
	s_barrier
	s_setprio 1
	s_waitcnt lgkmcnt(0)
	v_mfma_f32_16x16x32_bf16 v[124:127], v[152:155], v[184:187], v[124:127]
	v_mfma_f32_16x16x32_bf16 v[120:123], v[160:163], v[184:187], v[120:123]
	v_mfma_f32_16x16x32_bf16 v[116:119], v[152:155], v[192:195], v[116:119]
	v_mfma_f32_16x16x32_bf16 v[112:115], v[160:163], v[192:195], v[112:115]
	v_mfma_f32_16x16x32_bf16 v[100:103], v[152:155], v[200:203], v[100:103]
	v_mfma_f32_16x16x32_bf16 v[96:99], v[160:163], v[200:203], v[96:99]
	v_mfma_f32_16x16x32_bf16 v[84:87], v[152:155], v[208:211], v[84:87]
	v_mfma_f32_16x16x32_bf16 v[80:83], v[160:163], v[208:211], v[80:83]
	v_mfma_f32_16x16x32_bf16 v[124:127], v[156:159], v[188:191], v[124:127]
	v_mfma_f32_16x16x32_bf16 v[120:123], v[164:167], v[188:191], v[120:123]
	v_mfma_f32_16x16x32_bf16 v[116:119], v[156:159], v[196:199], v[116:119]
	v_mfma_f32_16x16x32_bf16 v[112:115], v[164:167], v[196:199], v[112:115]
	v_mfma_f32_16x16x32_bf16 v[100:103], v[156:159], v[204:207], v[100:103]
	v_mfma_f32_16x16x32_bf16 v[96:99], v[164:167], v[204:207], v[96:99]
	v_mfma_f32_16x16x32_bf16 v[84:87], v[156:159], v[212:215], v[84:87]
	v_mfma_f32_16x16x32_bf16 v[80:83], v[164:167], v[212:215], v[80:83]
	s_setprio 0
	s_setprio 1
	v_mfma_f32_16x16x32_bf16 v[108:111], v[168:171], v[184:187], v[108:111]
	v_mfma_f32_16x16x32_bf16 v[104:107], v[176:179], v[184:187], v[104:107]
	v_mfma_f32_16x16x32_bf16 v[92:95], v[168:171], v[192:195], v[92:95]
	v_mfma_f32_16x16x32_bf16 v[88:91], v[176:179], v[192:195], v[88:91]
	v_mfma_f32_16x16x32_bf16 v[76:79], v[168:171], v[200:203], v[76:79]
	v_mfma_f32_16x16x32_bf16 v[72:75], v[176:179], v[200:203], v[72:75]
	v_mfma_f32_16x16x32_bf16 v[68:71], v[168:171], v[208:211], v[68:71]
	v_mfma_f32_16x16x32_bf16 v[64:67], v[176:179], v[208:211], v[64:67]
	v_mfma_f32_16x16x32_bf16 v[108:111], v[172:175], v[188:191], v[108:111]
	v_mfma_f32_16x16x32_bf16 v[104:107], v[180:183], v[188:191], v[104:107]
	v_mfma_f32_16x16x32_bf16 v[92:95], v[172:175], v[196:199], v[92:95]
	v_mfma_f32_16x16x32_bf16 v[88:91], v[180:183], v[196:199], v[88:91]
	v_mfma_f32_16x16x32_bf16 v[76:79], v[172:175], v[204:207], v[76:79]
	v_mfma_f32_16x16x32_bf16 v[72:75], v[180:183], v[204:207], v[72:75]
	v_mfma_f32_16x16x32_bf16 v[68:71], v[172:175], v[212:215], v[68:71]
	v_mfma_f32_16x16x32_bf16 v[64:67], v[180:183], v[212:215], v[64:67]
	s_setprio 0
	s_barrier
; #define PG8_STAGE(bufoff, gbase, voff) do { _Pragma("unroll") for (int _i = 0; _i < 2; ++_i) \
;         __builtin_amdgcn_global_load_lds((const unsigned*)((const char*)(gbase) + (voff)[_i]), (PG8_LAS unsigned*)(lds + (bufoff) + ldsw + _i * 8192), 16, 0, 0); } while (0)
; #define PG8_LDA(dst, b, h) do { _Pragma("unroll") for (int m = 0; m < 4; ++m) _Pragma("unroll") for (int k = 0; k < 2; ++k) dst[m][k] = *(const PG8_LAS bf16x8*)(lds + PG8_SA(b, h) + aoff + m * 2048 + k * 1024); } while (0)
; #define PG8_MMA(ai, bj, At, Bt) do { __builtin_amdgcn_s_setprio(1); _Pragma("unroll") for (int m = 0; m < 4; ++m) _Pragma("unroll") for (int n = 0; n < 2; ++n) _Pragma("unroll") for (int k = 0; k < 2; ++k) \
;         acc[ai][bj][m][n] = __builtin_amdgcn_mfma_f32_16x16x32_bf16(Bt[n][k], At[m][k], acc[ai][bj][m][n], 0, 0, 0); __builtin_amdgcn_s_setprio(0); } while (0)
; #define PG8_WAIT_V(n) asm volatile("s_waitcnt vmcnt(" #n ")" ::: "memory")
; #define PG8_WAIT_L(n) asm volatile("s_waitcnt lgkmcnt(" #n ")" ::: "memory")
; #define PG8_BAR __builtin_amdgcn_s_barrier()
; #define PG8_SCHED __builtin_amdgcn_sched_barrier(0)
; template <class Epi, class Sched, bool ALIGN_EPI = false, bool SP2 = false>
; __device__ __forceinline__ void gemm_phase(PG8_LAS unsigned char* lds, const Gemm g, const Sched& S, const Epi& E) {
;     ...
;         for (int t = 0; t < nt; t += 2) {
;             const bool last = (t == nt - 2);
;             const char* a1 = cA + (size_t)(t + 1) * kstep;
;             const char* a2 = last ? nA : cA + (size_t)(t + 2) * kstep; const char* b2 = last ? nB : cB + (size_t)(t + 2) * kstep;
;             const char* a3 = a2 + kstep; const char* b3 = b2 + kstep;
;     ...
;             PG8_LDA(At, 1, 1); PG8_STAGE(PG8_SB(1, 0), b3, voffB); PG8_STAGE(PG8_SB(1, 1), b3 + hstep, voffB); PG8_STAGE(PG8_SA(1, 0), a3, voffA);
;             PG8_WAIT_V(8); PG8_WAIT_L(0); PG8_BAR; PG8_MMA(1, 0, At, B0); PG8_MMA(1, 1, At, B1); PG8_BAR; PG8_SCHED;
	s_add_i32 s44, s69, s48
	v_lshl_add_u64 v[216:217], v[216:217], 0, s[12:13]
	s_mov_b32 m0, s44
	ds_read_b128 v[184:187], v151 offset:49152
	ds_read_b128 v[188:191], v151 offset:50176
	ds_read_b128 v[192:195], v151 offset:51200
	ds_read_b128 v[196:199], v151 offset:52224
	ds_read_b128 v[200:203], v151 offset:53248
	ds_read_b128 v[204:207], v151 offset:54272
	ds_read_b128 v[208:211], v151 offset:55296
	ds_read_b128 v[212:215], v151 offset:56320
	global_load_lds_dwordx4 v[216:217], off
	s_add_i32 m0, s44, 0x2000
	s_add_u32 s42, s42, 0x80080
	v_lshl_add_u64 v[216:217], v[218:219], 0, s[12:13]
	s_addc_u32 s43, s43, 0
	s_add_i32 s44, s70, s48
	global_load_lds_dwordx4 v[216:217], off
	s_nop 0
	s_mov_b32 m0, s44
	s_nop 0
	global_load_lds_dwordx4 v132, s[42:43]
	s_nop 0
	s_add_i32 m0, s44, 0x2000
	s_nop 0
	global_load_lds_dwordx4 v128, s[42:43]
	v_lshl_add_u64 v[216:217], v[220:221], 0, s[12:13]
	s_mov_b32 m0, s55
	s_nop 0
	global_load_lds_dwordx4 v[216:217], off
	v_lshl_add_u64 v[216:217], v[222:223], 0, s[12:13]
	s_mov_b32 m0, s56
	s_nop 0
	global_load_lds_dwordx4 v[216:217], off
	s_waitcnt vmcnt(8)
	s_waitcnt lgkmcnt(0)
	s_barrier
	s_setprio 1
	s_waitcnt lgkmcnt(0)
	v_mfma_f32_16x16x32_bf16 v[60:63], v[152:155], v[184:187], v[60:63]
	v_mfma_f32_16x16x32_bf16 v[56:59], v[160:163], v[184:187], v[56:59]
	v_mfma_f32_16x16x32_bf16 v[52:55], v[152:155], v[192:195], v[52:55]
	v_mfma_f32_16x16x32_bf16 v[48:51], v[160:163], v[192:195], v[48:51]
	v_mfma_f32_16x16x32_bf16 v[36:39], v[152:155], v[200:203], v[36:39]
	v_mfma_f32_16x16x32_bf16 v[32:35], v[160:163], v[200:203], v[32:35]
	v_mfma_f32_16x16x32_bf16 v[20:23], v[152:155], v[208:211], v[20:23]
	v_mfma_f32_16x16x32_bf16 v[16:19], v[160:163], v[208:211], v[16:19]
	v_mfma_f32_16x16x32_bf16 v[60:63], v[156:159], v[188:191], v[60:63]
	v_mfma_f32_16x16x32_bf16 v[56:59], v[164:167], v[188:191], v[56:59]
	v_mfma_f32_16x16x32_bf16 v[52:55], v[156:159], v[196:199], v[52:55]
	v_mfma_f32_16x16x32_bf16 v[48:51], v[164:167], v[196:199], v[48:51]
	v_mfma_f32_16x16x32_bf16 v[36:39], v[156:159], v[204:207], v[36:39]
	v_mfma_f32_16x16x32_bf16 v[32:35], v[164:167], v[204:207], v[32:35]
	v_mfma_f32_16x16x32_bf16 v[20:23], v[156:159], v[212:215], v[20:23]
	v_mfma_f32_16x16x32_bf16 v[16:19], v[164:167], v[212:215], v[16:19]
	s_setprio 0
	s_setprio 1
	v_mfma_f32_16x16x32_bf16 v[44:47], v[168:171], v[184:187], v[44:47]
	v_mfma_f32_16x16x32_bf16 v[40:43], v[176:179], v[184:187], v[40:43]
	v_mfma_f32_16x16x32_bf16 v[28:31], v[168:171], v[192:195], v[28:31]
	v_mfma_f32_16x16x32_bf16 v[24:27], v[176:179], v[192:195], v[24:27]
	v_mfma_f32_16x16x32_bf16 v[12:15], v[168:171], v[200:203], v[12:15]
	v_mfma_f32_16x16x32_bf16 v[8:11], v[176:179], v[200:203], v[8:11]
	v_mfma_f32_16x16x32_bf16 v[4:7], v[168:171], v[208:211], v[4:7]
	v_mfma_f32_16x16x32_bf16 v[0:3], v[176:179], v[208:211], v[0:3]
	v_mfma_f32_16x16x32_bf16 v[44:47], v[172:175], v[188:191], v[44:47]
	v_mfma_f32_16x16x32_bf16 v[40:43], v[180:183], v[188:191], v[40:43]
	v_mfma_f32_16x16x32_bf16 v[28:31], v[172:175], v[196:199], v[28:31]
	v_mfma_f32_16x16x32_bf16 v[24:27], v[180:183], v[196:199], v[24:27]
	v_mfma_f32_16x16x32_bf16 v[12:15], v[172:175], v[204:207], v[12:15]
	v_mfma_f32_16x16x32_bf16 v[8:11], v[180:183], v[204:207], v[8:11]
	v_mfma_f32_16x16x32_bf16 v[4:7], v[172:175], v[212:215], v[4:7]
	v_mfma_f32_16x16x32_bf16 v[0:3], v[180:183], v[212:215], v[0:3]
	s_setprio 0
	s_barrier
	s_add_i32 s68, s68, 2
	s_add_u32 s40, s40, 0x100
	s_addc_u32 s41, s41, 0
	s_add_u32 s65, s65, 0x100
	s_addc_u32 s67, s67, 0
	s_cmp_gt_u32 s68, 29
	s_cbranch_scc0 .LBB0_66
	s_and_b64 vcc, exec, s[26:27]
	s_cbranch_vccz .LBB0_69
	s_barrier

; #define PG8_STAGE(bufoff, gbase, voff) do { _Pragma("unroll") for (int _i = 0; _i < 2; ++_i) \
;         __builtin_amdgcn_global_load_lds((const unsigned*)((const char*)(gbase) + (voff)[_i]), (PG8_LAS unsigned*)(lds + (bufoff) + ldsw + _i * 8192), 16, 0, 0); } while (0)
; #define PG8_LDA(dst, b, h) do { _Pragma("unroll") for (int m = 0; m < 4; ++m) _Pragma("unroll") for (int k = 0; k < 2; ++k) dst[m][k] = *(const PG8_LAS bf16x8*)(lds + PG8_SA(b, h) + aoff + m * 2048 + k * 1024); } while (0)
; #define PG8_LDB(dst, b, h) do { _Pragma("unroll") for (int n = 0; n < 2; ++n) _Pragma("unroll") for (int k = 0; k < 2; ++k) dst[n][k] = *(const PG8_LAS bf16x8*)(lds + PG8_SB(b, h) + boff + n * 2048 + k * 1024); } while (0)
; #define PG8_MMA(ai, bj, At, Bt) do { __builtin_amdgcn_s_setprio(1); _Pragma("unroll") for (int m = 0; m < 4; ++m) _Pragma("unroll") for (int n = 0; n < 2; ++n) _Pragma("unroll") for (int k = 0; k < 2; ++k) \
;         acc[ai][bj][m][n] = __builtin_amdgcn_mfma_f32_16x16x32_bf16(Bt[n][k], At[m][k], acc[ai][bj][m][n], 0, 0, 0); __builtin_amdgcn_s_setprio(0); } while (0)
; #define PG8_WAIT_V(n) asm volatile("s_waitcnt vmcnt(" #n ")" ::: "memory")
; #define PG8_WAIT_L(n) asm volatile("s_waitcnt lgkmcnt(" #n ")" ::: "memory")
; #define PG8_BAR __builtin_amdgcn_s_barrier()
; #define PG8_SCHED __builtin_amdgcn_sched_barrier(0)
; template <class Epi, class Sched, bool ALIGN_EPI = false, bool SP2 = false>
; __device__ __forceinline__ void gemm_phase(PG8_LAS unsigned char* lds, const Gemm g, const Sched& S, const Epi& E) {
;     ...
;             PG8_LDB(B0, 0, 0); PG8_LDB(B1, 0, 1); PG8_SCHED; PG8_LDA(At, 0, 0); PG8_STAGE(PG8_SA(1, 1), a1 + hstep, voffA);
;             PG8_WAIT_V(8); PG8_WAIT_L(0); PG8_BAR; PG8_MMA(0, 0, At, B0); PG8_MMA(0, 1, At, B1); PG8_BAR; PG8_SCHED;
;             PG8_LDA(At, 0, 1); PG8_STAGE(PG8_SB(0, 0), b2, voffB); PG8_STAGE(PG8_SB(0, 1), b2 + hstep, voffB); PG8_STAGE(PG8_SA(0, 0), a2, voffA);
;             PG8_WAIT_V(8); PG8_WAIT_L(0); PG8_BAR; PG8_MMA(1, 0, At, B0); PG8_MMA(1, 1, At, B1); PG8_BAR; PG8_SCHED;
.LBB0_333:
	ds_read_b128 v[64:67], v211
	ds_read_b128 v[68:71], v211 offset:1024
	ds_read_b128 v[72:75], v211 offset:2048
	ds_read_b128 v[76:79], v211 offset:3072
	ds_read_b128 v[144:147], v212
	ds_read_b128 v[148:151], v212 offset:1024
	ds_read_b128 v[152:155], v212 offset:2048
	ds_read_b128 v[156:159], v212 offset:3072
	s_add_u32 s60, s58, 0xfff80080
	s_addc_u32 s61, s59, -1
	s_cmp_eq_u32 s81, 28
	s_cselect_b32 s63, s11, s61
	s_cselect_b32 s62, s51, s60
	s_cselect_b32 s61, s49, s80
	s_cselect_b32 s60, s78, s79
	s_nop 0
	s_add_i32 m0, s57, 0xc000
	ds_read_b128 v[176:179], v213
	ds_read_b128 v[180:183], v213 offset:1024
	ds_read_b128 v[184:187], v213 offset:2048
	ds_read_b128 v[188:191], v213 offset:3072
	ds_read_b128 v[192:195], v213 offset:4096
	ds_read_b128 v[196:199], v213 offset:5120
	ds_read_b128 v[200:203], v213 offset:6144
	ds_read_b128 v[204:207], v213 offset:7168
	global_load_lds_dwordx4 v168, s[58:59]
	s_nop 0
	s_add_i32 m0, s57, 0xe000
	s_nop 0
	global_load_lds_dwordx4 v170, s[58:59]
	s_waitcnt vmcnt(8)
	s_waitcnt lgkmcnt(0)
	s_barrier
	s_setprio 1
	s_waitcnt lgkmcnt(0)
	v_mfma_f32_16x16x32_bf16 v[140:143], v[64:67], v[176:179], v[140:143]
	v_mfma_f32_16x16x32_bf16 v[136:139], v[72:75], v[176:179], v[136:139]
	v_mfma_f32_16x16x32_bf16 v[124:127], v[64:67], v[184:187], v[124:127]
	v_mfma_f32_16x16x32_bf16 v[120:123], v[72:75], v[184:187], v[120:123]
	v_mfma_f32_16x16x32_bf16 v[108:111], v[64:67], v[192:195], v[108:111]
	v_mfma_f32_16x16x32_bf16 v[104:107], v[72:75], v[192:195], v[104:107]
	v_mfma_f32_16x16x32_bf16 v[92:95], v[64:67], v[200:203], v[92:95]
	v_mfma_f32_16x16x32_bf16 v[88:91], v[72:75], v[200:203], v[88:91]
	v_mfma_f32_16x16x32_bf16 v[140:143], v[68:71], v[180:183], v[140:143]
	v_mfma_f32_16x16x32_bf16 v[136:139], v[76:79], v[180:183], v[136:139]
	v_mfma_f32_16x16x32_bf16 v[124:127], v[68:71], v[188:191], v[124:127]
	v_mfma_f32_16x16x32_bf16 v[120:123], v[76:79], v[188:191], v[120:123]
	v_mfma_f32_16x16x32_bf16 v[108:111], v[68:71], v[196:199], v[108:111]
	v_mfma_f32_16x16x32_bf16 v[104:107], v[76:79], v[196:199], v[104:107]
	v_mfma_f32_16x16x32_bf16 v[92:95], v[68:71], v[204:207], v[92:95]
	v_mfma_f32_16x16x32_bf16 v[88:91], v[76:79], v[204:207], v[88:91]
	s_setprio 0
	s_setprio 1
	v_mfma_f32_16x16x32_bf16 v[132:135], v[144:147], v[176:179], v[132:135]
	v_mfma_f32_16x16x32_bf16 v[128:131], v[152:155], v[176:179], v[128:131]
	v_mfma_f32_16x16x32_bf16 v[116:119], v[144:147], v[184:187], v[116:119]
	v_mfma_f32_16x16x32_bf16 v[112:115], v[152:155], v[184:187], v[112:115]
	v_mfma_f32_16x16x32_bf16 v[100:103], v[144:147], v[192:195], v[100:103]
	v_mfma_f32_16x16x32_bf16 v[96:99], v[152:155], v[192:195], v[96:99]
	v_mfma_f32_16x16x32_bf16 v[84:87], v[144:147], v[200:203], v[84:87]
	v_mfma_f32_16x16x32_bf16 v[80:83], v[152:155], v[200:203], v[80:83]
	v_mfma_f32_16x16x32_bf16 v[132:135], v[148:151], v[180:183], v[132:135]
	v_mfma_f32_16x16x32_bf16 v[128:131], v[156:159], v[180:183], v[128:131]
	v_mfma_f32_16x16x32_bf16 v[116:119], v[148:151], v[188:191], v[116:119]
	v_mfma_f32_16x16x32_bf16 v[112:115], v[156:159], v[188:191], v[112:115]
	v_mfma_f32_16x16x32_bf16 v[100:103], v[148:151], v[196:199], v[100:103]
	v_mfma_f32_16x16x32_bf16 v[96:99], v[156:159], v[196:199], v[96:99]
	v_mfma_f32_16x16x32_bf16 v[84:87], v[148:151], v[204:207], v[84:87]
	v_mfma_f32_16x16x32_bf16 v[80:83], v[156:159], v[204:207], v[80:83]
	s_setprio 0
	s_barrier
	s_add_i32 s82, s75, s64
	v_lshl_add_u64 v[216:217], s[60:61], 0, v[162:163]
	s_mov_b32 m0, s82
	ds_read_b128 v[176:179], v213 offset:16384
	ds_read_b128 v[180:183], v213 offset:17408
	ds_read_b128 v[184:187], v213 offset:18432
	ds_read_b128 v[188:191], v213 offset:19456
	ds_read_b128 v[192:195], v213 offset:20480
	ds_read_b128 v[196:199], v213 offset:21504
	ds_read_b128 v[200:203], v213 offset:22528
	ds_read_b128 v[204:207], v213 offset:23552
	global_load_lds_dwordx4 v[216:217], off
	s_add_i32 m0, s82, 0x2000
	s_add_u32 s82, s60, 0x80000
	v_lshl_add_u64 v[218:219], s[60:61], 0, v[166:167]
	s_addc_u32 s83, s61, 0
	s_add_i32 s84, s76, s64
	global_load_lds_dwordx4 v[218:219], off
	s_nop 0
	s_mov_b32 m0, s84
	v_lshl_add_u64 v[222:223], s[62:63], 0, v[164:165]
	global_load_lds_dwordx4 v162, s[82:83]
	s_nop 0
	s_add_i32 m0, s84, 0x2000
	s_nop 0
	global_load_lds_dwordx4 v166, s[82:83]
	v_lshl_add_u64 v[220:221], s[62:63], 0, v[160:161]
	s_mov_b32 m0, s57
	s_nop 0
	global_load_lds_dwordx4 v[220:221], off
	s_mov_b32 m0, s65
	s_nop 0
	global_load_lds_dwordx4 v[222:223], off
	s_waitcnt vmcnt(8)
	s_waitcnt lgkmcnt(0)
	s_barrier
; #define PG8_STAGE(bufoff, gbase, voff) do { _Pragma("unroll") for (int _i = 0; _i < 2; ++_i) \
;         __builtin_amdgcn_global_load_lds((const unsigned*)((const char*)(gbase) + (voff)[_i]), (PG8_LAS unsigned*)(lds + (bufoff) + ldsw + _i * 8192), 16, 0, 0); } while (0)
; #define PG8_LDA(dst, b, h) do { _Pragma("unroll") for (int m = 0; m < 4; ++m) _Pragma("unroll") for (int k = 0; k < 2; ++k) dst[m][k] = *(const PG8_LAS bf16x8*)(lds + PG8_SA(b, h) + aoff + m * 2048 + k * 1024); } while (0)
; #define PG8_LDB(dst, b, h) do { _Pragma("unroll") for (int n = 0; n < 2; ++n) _Pragma("unroll") for (int k = 0; k < 2; ++k) dst[n][k] = *(const PG8_LAS bf16x8*)(lds + PG8_SB(b, h) + boff + n * 2048 + k * 1024); } while (0)
; #define PG8_MMA(ai, bj, At, Bt) do { __builtin_amdgcn_s_setprio(1); _Pragma("unroll") for (int m = 0; m < 4; ++m) _Pragma("unroll") for (int n = 0; n < 2; ++n) _Pragma("unroll") for (int k = 0; k < 2; ++k) \
;         acc[ai][bj][m][n] = __builtin_amdgcn_mfma_f32_16x16x32_bf16(Bt[n][k], At[m][k], acc[ai][bj][m][n], 0, 0, 0); __builtin_amdgcn_s_setprio(0); } while (0)
; #define PG8_WAIT_V(n) asm volatile("s_waitcnt vmcnt(" #n ")" ::: "memory")
; #define PG8_WAIT_L(n) asm volatile("s_waitcnt lgkmcnt(" #n ")" ::: "memory")
; #define PG8_BAR __builtin_amdgcn_s_barrier()
; #define PG8_SCHED __builtin_amdgcn_sched_barrier(0)
; template <class Epi, class Sched, bool ALIGN_EPI = false, bool SP2 = false>
; __device__ __forceinline__ void gemm_phase(PG8_LAS unsigned char* lds, const Gemm g, const Sched& S, const Epi& E) {
;     ...
;             PG8_WAIT_V(8); PG8_WAIT_L(0); PG8_BAR; PG8_MMA(1, 0, At, B0); PG8_MMA(1, 1, At, B1); PG8_BAR; PG8_SCHED;
;             PG8_LDB(B0, 1, 0); PG8_LDB(B1, 1, 1); PG8_SCHED; PG8_LDA(At, 1, 0); PG8_STAGE(PG8_SA(0, 1), a2 + hstep, voffA);
;             PG8_WAIT_V(8); PG8_WAIT_L(0); PG8_BAR; PG8_MMA(0, 0, At, B0); PG8_MMA(0, 1, At, B1); PG8_BAR; PG8_SCHED;
	s_setprio 1
	s_waitcnt lgkmcnt(0)
	v_mfma_f32_16x16x32_bf16 v[60:63], v[64:67], v[176:179], v[60:63]
	v_mfma_f32_16x16x32_bf16 v[56:59], v[72:75], v[176:179], v[56:59]
	v_mfma_f32_16x16x32_bf16 v[44:47], v[64:67], v[184:187], v[44:47]
	v_mfma_f32_16x16x32_bf16 v[40:43], v[72:75], v[184:187], v[40:43]
	v_mfma_f32_16x16x32_bf16 v[28:31], v[64:67], v[192:195], v[28:31]
	v_mfma_f32_16x16x32_bf16 v[24:27], v[72:75], v[192:195], v[24:27]
	v_mfma_f32_16x16x32_bf16 v[12:15], v[64:67], v[200:203], v[12:15]
	v_mfma_f32_16x16x32_bf16 v[8:11], v[72:75], v[200:203], v[8:11]
	v_mfma_f32_16x16x32_bf16 v[60:63], v[68:71], v[180:183], v[60:63]
	v_mfma_f32_16x16x32_bf16 v[56:59], v[76:79], v[180:183], v[56:59]
	v_mfma_f32_16x16x32_bf16 v[44:47], v[68:71], v[188:191], v[44:47]
	v_mfma_f32_16x16x32_bf16 v[40:43], v[76:79], v[188:191], v[40:43]
	v_mfma_f32_16x16x32_bf16 v[28:31], v[68:71], v[196:199], v[28:31]
	v_mfma_f32_16x16x32_bf16 v[24:27], v[76:79], v[196:199], v[24:27]
	v_mfma_f32_16x16x32_bf16 v[12:15], v[68:71], v[204:207], v[12:15]
	v_mfma_f32_16x16x32_bf16 v[8:11], v[76:79], v[204:207], v[8:11]
	s_setprio 0
	s_setprio 1
	v_mfma_f32_16x16x32_bf16 v[52:55], v[144:147], v[176:179], v[52:55]
	v_mfma_f32_16x16x32_bf16 v[48:51], v[152:155], v[176:179], v[48:51]
	v_mfma_f32_16x16x32_bf16 v[36:39], v[144:147], v[184:187], v[36:39]
	v_mfma_f32_16x16x32_bf16 v[32:35], v[152:155], v[184:187], v[32:35]
	v_mfma_f32_16x16x32_bf16 v[20:23], v[144:147], v[192:195], v[20:23]
	v_mfma_f32_16x16x32_bf16 v[16:19], v[152:155], v[192:195], v[16:19]
	v_mfma_f32_16x16x32_bf16 v[4:7], v[144:147], v[200:203], v[4:7]
	v_mfma_f32_16x16x32_bf16 v[0:3], v[152:155], v[200:203], v[0:3]
	v_mfma_f32_16x16x32_bf16 v[52:55], v[148:151], v[180:183], v[52:55]
	v_mfma_f32_16x16x32_bf16 v[48:51], v[156:159], v[180:183], v[48:51]
	v_mfma_f32_16x16x32_bf16 v[36:39], v[148:151], v[188:191], v[36:39]
	v_mfma_f32_16x16x32_bf16 v[32:35], v[156:159], v[188:191], v[32:35]
	v_mfma_f32_16x16x32_bf16 v[20:23], v[148:151], v[196:199], v[20:23]
	v_mfma_f32_16x16x32_bf16 v[16:19], v[156:159], v[196:199], v[16:19]
	v_mfma_f32_16x16x32_bf16 v[4:7], v[148:151], v[204:207], v[4:7]
	v_mfma_f32_16x16x32_bf16 v[0:3], v[156:159], v[204:207], v[0:3]
	s_setprio 0
	s_barrier
	s_add_i32 s82, 0, 0x18000
	s_add_i32 s83, 0, 0x1c000
	v_add_u32_e32 v76, s82, v209
	v_add_u32_e32 v156, s83, v209
	ds_read_b128 v[64:67], v76
	ds_read_b128 v[68:71], v76 offset:1024
	ds_read_b128 v[72:75], v76 offset:2048
	ds_read_b128 v[76:79], v76 offset:3072
	ds_read_b128 v[144:147], v156
	ds_read_b128 v[148:151], v156 offset:1024
	ds_read_b128 v[152:155], v156 offset:2048
	ds_read_b128 v[156:159], v156 offset:3072
	s_add_u32 s62, s62, 0x80000
	s_addc_u32 s63, s63, 0
	s_mov_b32 m0, s67
	s_nop 0
	ds_read_b128 v[176:179], v213 offset:32768
	ds_read_b128 v[180:183], v213 offset:33792
	ds_read_b128 v[184:187], v213 offset:34816
	ds_read_b128 v[188:191], v213 offset:35840
	ds_read_b128 v[192:195], v213 offset:36864
	ds_read_b128 v[196:199], v213 offset:37888
	ds_read_b128 v[200:203], v213 offset:38912
	ds_read_b128 v[204:207], v213 offset:39936
	global_load_lds_dwordx4 v160, s[62:63]
	s_nop 0
	s_mov_b32 m0, s68
	s_nop 0
	global_load_lds_dwordx4 v164, s[62:63]
	s_waitcnt vmcnt(8)
	s_waitcnt lgkmcnt(0)
	s_barrier
	s_setprio 1
	s_waitcnt lgkmcnt(0)
	v_mfma_f32_16x16x32_bf16 v[140:143], v[64:67], v[176:179], v[140:143]
	v_mfma_f32_16x16x32_bf16 v[136:139], v[72:75], v[176:179], v[136:139]
	v_mfma_f32_16x16x32_bf16 v[124:127], v[64:67], v[184:187], v[124:127]
	v_mfma_f32_16x16x32_bf16 v[120:123], v[72:75], v[184:187], v[120:123]
	v_mfma_f32_16x16x32_bf16 v[108:111], v[64:67], v[192:195], v[108:111]
	v_mfma_f32_16x16x32_bf16 v[104:107], v[72:75], v[192:195], v[104:107]
	v_mfma_f32_16x16x32_bf16 v[92:95], v[64:67], v[200:203], v[92:95]
	v_mfma_f32_16x16x32_bf16 v[88:91], v[72:75], v[200:203], v[88:91]
	v_mfma_f32_16x16x32_bf16 v[140:143], v[68:71], v[180:183], v[140:143]
	v_mfma_f32_16x16x32_bf16 v[136:139], v[76:79], v[180:183], v[136:139]
	v_mfma_f32_16x16x32_bf16 v[124:127], v[68:71], v[188:191], v[124:127]
	v_mfma_f32_16x16x32_bf16 v[120:123], v[76:79], v[188:191], v[120:123]
	v_mfma_f32_16x16x32_bf16 v[108:111], v[68:71], v[196:199], v[108:111]
	v_mfma_f32_16x16x32_bf16 v[104:107], v[76:79], v[196:199], v[104:107]
	v_mfma_f32_16x16x32_bf16 v[92:95], v[68:71], v[204:207], v[92:95]
	v_mfma_f32_16x16x32_bf16 v[88:91], v[76:79], v[204:207], v[88:91]
	s_setprio 0
	s_setprio 1
	v_mfma_f32_16x16x32_bf16 v[132:135], v[144:147], v[176:179], v[132:135]
	v_mfma_f32_16x16x32_bf16 v[128:131], v[152:155], v[176:179], v[128:131]
	v_mfma_f32_16x16x32_bf16 v[116:119], v[144:147], v[184:187], v[116:119]
	v_mfma_f32_16x16x32_bf16 v[112:115], v[152:155], v[184:187], v[112:115]
	v_mfma_f32_16x16x32_bf16 v[100:103], v[144:147], v[192:195], v[100:103]
	v_mfma_f32_16x16x32_bf16 v[96:99], v[152:155], v[192:195], v[96:99]
	v_mfma_f32_16x16x32_bf16 v[84:87], v[144:147], v[200:203], v[84:87]
	v_mfma_f32_16x16x32_bf16 v[80:83], v[152:155], v[200:203], v[80:83]
	v_mfma_f32_16x16x32_bf16 v[132:135], v[148:151], v[180:183], v[132:135]
	v_mfma_f32_16x16x32_bf16 v[128:131], v[156:159], v[180:183], v[128:131]
	v_mfma_f32_16x16x32_bf16 v[116:119], v[148:151], v[188:191], v[116:119]
	v_mfma_f32_16x16x32_bf16 v[112:115], v[156:159], v[188:191], v[112:115]
	v_mfma_f32_16x16x32_bf16 v[100:103], v[148:151], v[196:199], v[100:103]
	v_mfma_f32_16x16x32_bf16 v[96:99], v[156:159], v[196:199], v[96:99]
	v_mfma_f32_16x16x32_bf16 v[84:87], v[148:151], v[204:207], v[84:87]
	v_mfma_f32_16x16x32_bf16 v[80:83], v[156:159], v[204:207], v[80:83]
	s_setprio 0
	s_barrier
; #define PG8_STAGE(bufoff, gbase, voff) do { _Pragma("unroll") for (int _i = 0; _i < 2; ++_i) \
;         __builtin_amdgcn_global_load_lds((const unsigned*)((const char*)(gbase) + (voff)[_i]), (PG8_LAS unsigned*)(lds + (bufoff) + ldsw + _i * 8192), 16, 0, 0); } while (0)
; #define PG8_LDA(dst, b, h) do { _Pragma("unroll") for (int m = 0; m < 4; ++m) _Pragma("unroll") for (int k = 0; k < 2; ++k) dst[m][k] = *(const PG8_LAS bf16x8*)(lds + PG8_SA(b, h) + aoff + m * 2048 + k * 1024); } while (0)
; #define PG8_MMA(ai, bj, At, Bt) do { __builtin_amdgcn_s_setprio(1); _Pragma("unroll") for (int m = 0; m < 4; ++m) _Pragma("unroll") for (int n = 0; n < 2; ++n) _Pragma("unroll") for (int k = 0; k < 2; ++k) \
;         acc[ai][bj][m][n] = __builtin_amdgcn_mfma_f32_16x16x32_bf16(Bt[n][k], At[m][k], acc[ai][bj][m][n], 0, 0, 0); __builtin_amdgcn_s_setprio(0); } while (0)
; #define PG8_WAIT_V(n) asm volatile("s_waitcnt vmcnt(" #n ")" ::: "memory")
; #define PG8_WAIT_L(n) asm volatile("s_waitcnt lgkmcnt(" #n ")" ::: "memory")
; #define PG8_BAR __builtin_amdgcn_s_barrier()
; #define PG8_SCHED __builtin_amdgcn_sched_barrier(0)
; template <class Epi, class Sched, bool ALIGN_EPI = false, bool SP2 = false>
; __device__ __forceinline__ void gemm_phase(PG8_LAS unsigned char* lds, const Gemm g, const Sched& S, const Epi& E) {
;     ...
;         for (int t = 0; t < nt; t += 2) {
;             const bool last = (t == nt - 2);
;             const char* a1 = cA + (size_t)(t + 1) * kstep;
;             const char* a2 = last ? nA : cA + (size_t)(t + 2) * kstep; const char* b2 = last ? nB : cB + (size_t)(t + 2) * kstep;
;             const char* a3 = a2 + kstep; const char* b3 = b2 + kstep;
;     ...
;             PG8_LDA(At, 1, 1); PG8_STAGE(PG8_SB(1, 0), b3, voffB); PG8_STAGE(PG8_SB(1, 1), b3 + hstep, voffB); PG8_STAGE(PG8_SA(1, 0), a3, voffA);
;             PG8_WAIT_V(8); PG8_WAIT_L(0); PG8_BAR; PG8_MMA(1, 0, At, B0); PG8_MMA(1, 1, At, B1); PG8_BAR; PG8_SCHED;
	s_add_i32 s62, s82, s64
	v_lshl_add_u64 v[216:217], v[216:217], 0, s[40:41]
	s_mov_b32 m0, s62
	ds_read_b128 v[176:179], v213 offset:49152
	ds_read_b128 v[180:183], v213 offset:50176
	ds_read_b128 v[184:187], v213 offset:51200
	ds_read_b128 v[188:191], v213 offset:52224
	ds_read_b128 v[192:195], v213 offset:53248
	ds_read_b128 v[196:199], v213 offset:54272
	ds_read_b128 v[200:203], v213 offset:55296
	ds_read_b128 v[204:207], v213 offset:56320
	global_load_lds_dwordx4 v[216:217], off
	s_add_i32 m0, s62, 0x2000
	s_add_u32 s60, s60, 0x80080
	v_lshl_add_u64 v[216:217], v[218:219], 0, s[40:41]
	s_addc_u32 s61, s61, 0
	s_add_i32 s62, s83, s64
	global_load_lds_dwordx4 v[216:217], off
	s_nop 0
	s_mov_b32 m0, s62
	s_nop 0
	global_load_lds_dwordx4 v162, s[60:61]
	s_nop 0
	s_add_i32 m0, s62, 0x2000
	s_nop 0
	global_load_lds_dwordx4 v166, s[60:61]
	v_lshl_add_u64 v[216:217], v[220:221], 0, s[40:41]
	s_mov_b32 m0, s70
	s_nop 0
	global_load_lds_dwordx4 v[216:217], off
	v_lshl_add_u64 v[216:217], v[222:223], 0, s[40:41]
	s_mov_b32 m0, s71
	s_nop 0
	global_load_lds_dwordx4 v[216:217], off
	s_waitcnt vmcnt(8)
	s_waitcnt lgkmcnt(0)
	s_barrier
	s_setprio 1
	s_waitcnt lgkmcnt(0)
	v_mfma_f32_16x16x32_bf16 v[60:63], v[64:67], v[176:179], v[60:63]
	v_mfma_f32_16x16x32_bf16 v[56:59], v[72:75], v[176:179], v[56:59]
	v_mfma_f32_16x16x32_bf16 v[44:47], v[64:67], v[184:187], v[44:47]
	v_mfma_f32_16x16x32_bf16 v[40:43], v[72:75], v[184:187], v[40:43]
	v_mfma_f32_16x16x32_bf16 v[28:31], v[64:67], v[192:195], v[28:31]
	v_mfma_f32_16x16x32_bf16 v[24:27], v[72:75], v[192:195], v[24:27]
	v_mfma_f32_16x16x32_bf16 v[12:15], v[64:67], v[200:203], v[12:15]
	v_mfma_f32_16x16x32_bf16 v[8:11], v[72:75], v[200:203], v[8:11]
	v_mfma_f32_16x16x32_bf16 v[60:63], v[68:71], v[180:183], v[60:63]
	v_mfma_f32_16x16x32_bf16 v[56:59], v[76:79], v[180:183], v[56:59]
	v_mfma_f32_16x16x32_bf16 v[44:47], v[68:71], v[188:191], v[44:47]
	v_mfma_f32_16x16x32_bf16 v[40:43], v[76:79], v[188:191], v[40:43]
	v_mfma_f32_16x16x32_bf16 v[28:31], v[68:71], v[196:199], v[28:31]
	v_mfma_f32_16x16x32_bf16 v[24:27], v[76:79], v[196:199], v[24:27]
	v_mfma_f32_16x16x32_bf16 v[12:15], v[68:71], v[204:207], v[12:15]
	v_mfma_f32_16x16x32_bf16 v[8:11], v[76:79], v[204:207], v[8:11]
	s_setprio 0
	s_setprio 1
	v_mfma_f32_16x16x32_bf16 v[52:55], v[144:147], v[176:179], v[52:55]
	v_mfma_f32_16x16x32_bf16 v[48:51], v[152:155], v[176:179], v[48:51]
	v_mfma_f32_16x16x32_bf16 v[36:39], v[144:147], v[184:187], v[36:39]
	v_mfma_f32_16x16x32_bf16 v[32:35], v[152:155], v[184:187], v[32:35]
	v_mfma_f32_16x16x32_bf16 v[20:23], v[144:147], v[192:195], v[20:23]
	v_mfma_f32_16x16x32_bf16 v[16:19], v[152:155], v[192:195], v[16:19]
	v_mfma_f32_16x16x32_bf16 v[4:7], v[144:147], v[200:203], v[4:7]
	v_mfma_f32_16x16x32_bf16 v[0:3], v[152:155], v[200:203], v[0:3]
	v_mfma_f32_16x16x32_bf16 v[52:55], v[148:151], v[180:183], v[52:55]
	v_mfma_f32_16x16x32_bf16 v[48:51], v[156:159], v[180:183], v[48:51]
	v_mfma_f32_16x16x32_bf16 v[36:39], v[148:151], v[188:191], v[36:39]
	v_mfma_f32_16x16x32_bf16 v[32:35], v[156:159], v[188:191], v[32:35]
	v_mfma_f32_16x16x32_bf16 v[20:23], v[148:151], v[196:199], v[20:23]
	v_mfma_f32_16x16x32_bf16 v[16:19], v[156:159], v[196:199], v[16:19]
	v_mfma_f32_16x16x32_bf16 v[4:7], v[148:151], v[204:207], v[4:7]
	v_mfma_f32_16x16x32_bf16 v[0:3], v[156:159], v[204:207], v[0:3]
	s_setprio 0
	s_barrier
	s_add_i32 s81, s81, 2
	s_add_u32 s58, s58, 0x100
	s_addc_u32 s59, s59, 0
	s_add_u32 s79, s79, 0x100
	s_addc_u32 s80, s80, 0
	s_cmp_gt_u32 s81, 29
	s_cbranch_scc0 .LBB0_333
	s_and_b64 vcc, exec, s[42:43]
	s_cbranch_vccz .LBB0_336
	s_barrier

; #define PG8_STAGE(bufoff, gbase, voff) do { _Pragma("unroll") for (int _i = 0; _i < 2; ++_i) \
;         __builtin_amdgcn_global_load_lds((const unsigned*)((const char*)(gbase) + (voff)[_i]), (PG8_LAS unsigned*)(lds + (bufoff) + ldsw + _i * 8192), 16, 0, 0); } while (0)
; #define PG8_LDA(dst, b, h) do { _Pragma("unroll") for (int m = 0; m < 4; ++m) _Pragma("unroll") for (int k = 0; k < 2; ++k) dst[m][k] = *(const PG8_LAS bf16x8*)(lds + PG8_SA(b, h) + aoff + m * 2048 + k * 1024); } while (0)
; #define PG8_LDB(dst, b, h) do { _Pragma("unroll") for (int n = 0; n < 2; ++n) _Pragma("unroll") for (int k = 0; k < 2; ++k) dst[n][k] = *(const PG8_LAS bf16x8*)(lds + PG8_SB(b, h) + boff + n * 2048 + k * 1024); } while (0)
; #define PG8_MMA(ai, bj, At, Bt) do { __builtin_amdgcn_s_setprio(1); _Pragma("unroll") for (int m = 0; m < 4; ++m) _Pragma("unroll") for (int n = 0; n < 2; ++n) _Pragma("unroll") for (int k = 0; k < 2; ++k) \
;         acc[ai][bj][m][n] = __builtin_amdgcn_mfma_f32_16x16x32_bf16(Bt[n][k], At[m][k], acc[ai][bj][m][n], 0, 0, 0); __builtin_amdgcn_s_setprio(0); } while (0)
; #define PG8_WAIT_V(n) asm volatile("s_waitcnt vmcnt(" #n ")" ::: "memory")
; #define PG8_WAIT_L(n) asm volatile("s_waitcnt lgkmcnt(" #n ")" ::: "memory")
; #define PG8_BAR __builtin_amdgcn_s_barrier()
; #define PG8_SCHED __builtin_amdgcn_sched_barrier(0)
; template <class Epi, class Sched, bool ALIGN_EPI = false, bool SP2 = false>
; __device__ __forceinline__ void gemm_phase(PG8_LAS unsigned char* lds, const Gemm g, const Sched& S, const Epi& E) {
;     ...
;             PG8_LDB(B0, 0, 0); PG8_LDB(B1, 0, 1); PG8_SCHED; PG8_LDA(At, 0, 0); PG8_STAGE(PG8_SA(1, 1), a1 + hstep, voffA);
;             PG8_WAIT_V(8); PG8_WAIT_L(0); PG8_BAR; PG8_MMA(0, 0, At, B0); PG8_MMA(0, 1, At, B1); PG8_BAR; PG8_SCHED;
;             PG8_LDA(At, 0, 1); PG8_STAGE(PG8_SB(0, 0), b2, voffB); PG8_STAGE(PG8_SB(0, 1), b2 + hstep, voffB); PG8_STAGE(PG8_SA(0, 0), a2, voffA);
;             PG8_WAIT_V(8); PG8_WAIT_L(0); PG8_BAR; PG8_MMA(1, 0, At, B0); PG8_MMA(1, 1, At, B1); PG8_BAR; PG8_SCHED;
.LBB0_428:
	ds_read_b128 v[128:131], v201
	ds_read_b128 v[132:135], v201 offset:1024
	ds_read_b128 v[136:139], v201 offset:2048
	ds_read_b128 v[140:143], v201 offset:3072
	ds_read_b128 v[144:147], v205
	ds_read_b128 v[148:151], v205 offset:1024
	ds_read_b128 v[152:155], v205 offset:2048
	ds_read_b128 v[156:159], v205 offset:3072
	s_add_u32 s12, s10, 0xfff80080
	s_addc_u32 s13, s11, -1
	s_cmp_eq_u32 s85, 28
	s_cselect_b32 s61, s55, s13
	s_cselect_b32 s60, s81, s12
	s_cselect_b32 s13, s53, s84
	s_cselect_b32 s12, s82, s83
	s_nop 0
	s_add_i32 m0, s65, 0xc000
	ds_read_b128 v[176:179], v207
	ds_read_b128 v[184:187], v207 offset:1024
	ds_read_b128 v[190:193], v207 offset:2048
	ds_read_b128 v[210:213], v207 offset:3072
	ds_read_b128 v[214:217], v207 offset:4096
	ds_read_b128 v[218:221], v207 offset:5120
	ds_read_b128 v[222:225], v207 offset:6144
	ds_read_b128 v[226:229], v207 offset:7168
	global_load_lds_dwordx4 v168, s[10:11]
	s_nop 0
	s_add_i32 m0, s65, 0xe000
	s_nop 0
	global_load_lds_dwordx4 v170, s[10:11]
	s_waitcnt vmcnt(8)
	s_waitcnt lgkmcnt(0)
	s_barrier
	s_setprio 1
	s_waitcnt lgkmcnt(0)
	v_mfma_f32_16x16x32_bf16 v[124:127], v[128:131], v[176:179], v[124:127]
	v_mfma_f32_16x16x32_bf16 v[120:123], v[136:139], v[176:179], v[120:123]
	v_mfma_f32_16x16x32_bf16 v[108:111], v[128:131], v[190:193], v[108:111]
	v_mfma_f32_16x16x32_bf16 v[104:107], v[136:139], v[190:193], v[104:107]
	v_mfma_f32_16x16x32_bf16 v[92:95], v[128:131], v[214:217], v[92:95]
	v_mfma_f32_16x16x32_bf16 v[88:91], v[136:139], v[214:217], v[88:91]
	v_mfma_f32_16x16x32_bf16 v[76:79], v[128:131], v[222:225], v[76:79]
	v_mfma_f32_16x16x32_bf16 v[72:75], v[136:139], v[222:225], v[72:75]
	v_mfma_f32_16x16x32_bf16 v[124:127], v[132:135], v[184:187], v[124:127]
	v_mfma_f32_16x16x32_bf16 v[120:123], v[140:143], v[184:187], v[120:123]
	v_mfma_f32_16x16x32_bf16 v[108:111], v[132:135], v[210:213], v[108:111]
	v_mfma_f32_16x16x32_bf16 v[104:107], v[140:143], v[210:213], v[104:107]
	v_mfma_f32_16x16x32_bf16 v[92:95], v[132:135], v[218:221], v[92:95]
	v_mfma_f32_16x16x32_bf16 v[88:91], v[140:143], v[218:221], v[88:91]
	v_mfma_f32_16x16x32_bf16 v[76:79], v[132:135], v[226:229], v[76:79]
	v_mfma_f32_16x16x32_bf16 v[72:75], v[140:143], v[226:229], v[72:75]
	s_setprio 0
	s_setprio 1
	v_mfma_f32_16x16x32_bf16 v[116:119], v[144:147], v[176:179], v[116:119]
	v_mfma_f32_16x16x32_bf16 v[112:115], v[152:155], v[176:179], v[112:115]
	v_mfma_f32_16x16x32_bf16 v[100:103], v[144:147], v[190:193], v[100:103]
	v_mfma_f32_16x16x32_bf16 v[96:99], v[152:155], v[190:193], v[96:99]
	v_mfma_f32_16x16x32_bf16 v[84:87], v[144:147], v[214:217], v[84:87]
	v_mfma_f32_16x16x32_bf16 v[80:83], v[152:155], v[214:217], v[80:83]
	v_mfma_f32_16x16x32_bf16 v[68:71], v[144:147], v[222:225], v[68:71]
	v_mfma_f32_16x16x32_bf16 v[64:67], v[152:155], v[222:225], v[64:67]
	v_mfma_f32_16x16x32_bf16 v[116:119], v[148:151], v[184:187], v[116:119]
	v_mfma_f32_16x16x32_bf16 v[112:115], v[156:159], v[184:187], v[112:115]
	v_mfma_f32_16x16x32_bf16 v[100:103], v[148:151], v[210:213], v[100:103]
	v_mfma_f32_16x16x32_bf16 v[96:99], v[156:159], v[210:213], v[96:99]
	v_mfma_f32_16x16x32_bf16 v[84:87], v[148:151], v[218:221], v[84:87]
	v_mfma_f32_16x16x32_bf16 v[80:83], v[156:159], v[218:221], v[80:83]
	v_mfma_f32_16x16x32_bf16 v[68:71], v[148:151], v[226:229], v[68:71]
	v_mfma_f32_16x16x32_bf16 v[64:67], v[156:159], v[226:229], v[64:67]
	s_setprio 0
	s_barrier
	s_add_i32 s86, s75, s64
	v_lshl_add_u64 v[180:181], s[12:13], 0, v[162:163]
	s_mov_b32 m0, s86
	ds_read_b128 v[176:179], v207 offset:16384
	ds_read_b128 v[184:187], v207 offset:17408
	ds_read_b128 v[190:193], v207 offset:18432
	ds_read_b128 v[210:213], v207 offset:19456
	ds_read_b128 v[214:217], v207 offset:20480
	ds_read_b128 v[218:221], v207 offset:21504
	ds_read_b128 v[222:225], v207 offset:22528
	ds_read_b128 v[226:229], v207 offset:23552
	global_load_lds_dwordx4 v[180:181], off
	s_add_i32 m0, s86, 0x2000
	s_add_u32 s86, s12, 0x80000
	v_lshl_add_u64 v[194:195], s[12:13], 0, v[166:167]
	s_addc_u32 s87, s13, 0
	s_add_i32 s88, s76, s64
	global_load_lds_dwordx4 v[194:195], off
	s_nop 0
	s_mov_b32 m0, s88
	v_lshl_add_u64 v[202:203], s[60:61], 0, v[164:165]
	global_load_lds_dwordx4 v162, s[86:87]
	s_nop 0
	s_add_i32 m0, s88, 0x2000
	s_nop 0
	global_load_lds_dwordx4 v166, s[86:87]
	v_lshl_add_u64 v[198:199], s[60:61], 0, v[160:161]
	s_mov_b32 m0, s65
	s_nop 0
	global_load_lds_dwordx4 v[198:199], off
	s_mov_b32 m0, s67
	s_nop 0
	global_load_lds_dwordx4 v[202:203], off
	s_waitcnt vmcnt(8)
	s_waitcnt lgkmcnt(0)
	s_barrier
; #define PG8_STAGE(bufoff, gbase, voff) do { _Pragma("unroll") for (int _i = 0; _i < 2; ++_i) \
;         __builtin_amdgcn_global_load_lds((const unsigned*)((const char*)(gbase) + (voff)[_i]), (PG8_LAS unsigned*)(lds + (bufoff) + ldsw + _i * 8192), 16, 0, 0); } while (0)
; #define PG8_LDA(dst, b, h) do { _Pragma("unroll") for (int m = 0; m < 4; ++m) _Pragma("unroll") for (int k = 0; k < 2; ++k) dst[m][k] = *(const PG8_LAS bf16x8*)(lds + PG8_SA(b, h) + aoff + m * 2048 + k * 1024); } while (0)
; #define PG8_LDB(dst, b, h) do { _Pragma("unroll") for (int n = 0; n < 2; ++n) _Pragma("unroll") for (int k = 0; k < 2; ++k) dst[n][k] = *(const PG8_LAS bf16x8*)(lds + PG8_SB(b, h) + boff + n * 2048 + k * 1024); } while (0)
; #define PG8_MMA(ai, bj, At, Bt) do { __builtin_amdgcn_s_setprio(1); _Pragma("unroll") for (int m = 0; m < 4; ++m) _Pragma("unroll") for (int n = 0; n < 2; ++n) _Pragma("unroll") for (int k = 0; k < 2; ++k) \
;         acc[ai][bj][m][n] = __builtin_amdgcn_mfma_f32_16x16x32_bf16(Bt[n][k], At[m][k], acc[ai][bj][m][n], 0, 0, 0); __builtin_amdgcn_s_setprio(0); } while (0)
; #define PG8_WAIT_V(n) asm volatile("s_waitcnt vmcnt(" #n ")" ::: "memory")
; #define PG8_WAIT_L(n) asm volatile("s_waitcnt lgkmcnt(" #n ")" ::: "memory")
; #define PG8_BAR __builtin_amdgcn_s_barrier()
; #define PG8_SCHED __builtin_amdgcn_sched_barrier(0)
; template <class Epi, class Sched, bool ALIGN_EPI = false, bool SP2 = false>
; __device__ __forceinline__ void gemm_phase(PG8_LAS unsigned char* lds, const Gemm g, const Sched& S, const Epi& E) {
;     ...
;             PG8_WAIT_V(8); PG8_WAIT_L(0); PG8_BAR; PG8_MMA(1, 0, At, B0); PG8_MMA(1, 1, At, B1); PG8_BAR; PG8_SCHED;
;             PG8_LDB(B0, 1, 0); PG8_LDB(B1, 1, 1); PG8_SCHED; PG8_LDA(At, 1, 0); PG8_STAGE(PG8_SA(0, 1), a2 + hstep, voffA);
;             PG8_WAIT_V(8); PG8_WAIT_L(0); PG8_BAR; PG8_MMA(0, 0, At, B0); PG8_MMA(0, 1, At, B1); PG8_BAR; PG8_SCHED;
	s_setprio 1
	s_waitcnt lgkmcnt(0)
	v_mfma_f32_16x16x32_bf16 v[60:63], v[128:131], v[176:179], v[60:63]
	v_mfma_f32_16x16x32_bf16 v[56:59], v[136:139], v[176:179], v[56:59]
	v_mfma_f32_16x16x32_bf16 v[44:47], v[128:131], v[190:193], v[44:47]
	v_mfma_f32_16x16x32_bf16 v[40:43], v[136:139], v[190:193], v[40:43]
	v_mfma_f32_16x16x32_bf16 v[28:31], v[128:131], v[214:217], v[28:31]
	v_mfma_f32_16x16x32_bf16 v[24:27], v[136:139], v[214:217], v[24:27]
	v_mfma_f32_16x16x32_bf16 v[12:15], v[128:131], v[222:225], v[12:15]
	v_mfma_f32_16x16x32_bf16 v[8:11], v[136:139], v[222:225], v[8:11]
	v_mfma_f32_16x16x32_bf16 v[60:63], v[132:135], v[184:187], v[60:63]
	v_mfma_f32_16x16x32_bf16 v[56:59], v[140:143], v[184:187], v[56:59]
	v_mfma_f32_16x16x32_bf16 v[44:47], v[132:135], v[210:213], v[44:47]
	v_mfma_f32_16x16x32_bf16 v[40:43], v[140:143], v[210:213], v[40:43]
	v_mfma_f32_16x16x32_bf16 v[28:31], v[132:135], v[218:221], v[28:31]
	v_mfma_f32_16x16x32_bf16 v[24:27], v[140:143], v[218:221], v[24:27]
	v_mfma_f32_16x16x32_bf16 v[12:15], v[132:135], v[226:229], v[12:15]
	v_mfma_f32_16x16x32_bf16 v[8:11], v[140:143], v[226:229], v[8:11]
	s_setprio 0
	s_setprio 1
	v_mfma_f32_16x16x32_bf16 v[52:55], v[144:147], v[176:179], v[52:55]
	v_mfma_f32_16x16x32_bf16 v[48:51], v[152:155], v[176:179], v[48:51]
	v_mfma_f32_16x16x32_bf16 v[36:39], v[144:147], v[190:193], v[36:39]
	v_mfma_f32_16x16x32_bf16 v[32:35], v[152:155], v[190:193], v[32:35]
	v_mfma_f32_16x16x32_bf16 v[20:23], v[144:147], v[214:217], v[20:23]
	v_mfma_f32_16x16x32_bf16 v[16:19], v[152:155], v[214:217], v[16:19]
	v_mfma_f32_16x16x32_bf16 v[4:7], v[144:147], v[222:225], v[4:7]
	v_mfma_f32_16x16x32_bf16 v[0:3], v[152:155], v[222:225], v[0:3]
	v_mfma_f32_16x16x32_bf16 v[52:55], v[148:151], v[184:187], v[52:55]
	v_mfma_f32_16x16x32_bf16 v[48:51], v[156:159], v[184:187], v[48:51]
	v_mfma_f32_16x16x32_bf16 v[36:39], v[148:151], v[210:213], v[36:39]
	v_mfma_f32_16x16x32_bf16 v[32:35], v[156:159], v[210:213], v[32:35]
	v_mfma_f32_16x16x32_bf16 v[20:23], v[148:151], v[218:221], v[20:23]
	v_mfma_f32_16x16x32_bf16 v[16:19], v[156:159], v[218:221], v[16:19]
	v_mfma_f32_16x16x32_bf16 v[4:7], v[148:151], v[226:229], v[4:7]
	v_mfma_f32_16x16x32_bf16 v[0:3], v[156:159], v[226:229], v[0:3]
	s_setprio 0
	s_barrier
	s_add_i32 s86, 0, 0x18000
	s_add_i32 s87, 0, 0x1c000
	v_add_u32_e32 v140, s86, v189
	v_add_u32_e32 v156, s87, v189
	ds_read_b128 v[128:131], v140
	ds_read_b128 v[132:135], v140 offset:1024
	ds_read_b128 v[136:139], v140 offset:2048
	ds_read_b128 v[140:143], v140 offset:3072
	ds_read_b128 v[144:147], v156
	ds_read_b128 v[148:151], v156 offset:1024
	ds_read_b128 v[152:155], v156 offset:2048
	ds_read_b128 v[156:159], v156 offset:3072
	s_add_u32 s60, s60, 0x80000
	s_addc_u32 s61, s61, 0
	s_mov_b32 m0, s68
	s_nop 0
	ds_read_b128 v[176:179], v207 offset:32768
	ds_read_b128 v[184:187], v207 offset:33792
	ds_read_b128 v[190:193], v207 offset:34816
	ds_read_b128 v[210:213], v207 offset:35840
	ds_read_b128 v[214:217], v207 offset:36864
	ds_read_b128 v[218:221], v207 offset:37888
	ds_read_b128 v[222:225], v207 offset:38912
	ds_read_b128 v[226:229], v207 offset:39936
	global_load_lds_dwordx4 v160, s[60:61]
	s_nop 0
	s_mov_b32 m0, s69
	s_nop 0
	global_load_lds_dwordx4 v164, s[60:61]
	s_waitcnt vmcnt(8)
	s_waitcnt lgkmcnt(0)
	s_barrier
	s_setprio 1
	s_waitcnt lgkmcnt(0)
	v_mfma_f32_16x16x32_bf16 v[124:127], v[128:131], v[176:179], v[124:127]
	v_mfma_f32_16x16x32_bf16 v[120:123], v[136:139], v[176:179], v[120:123]
	v_mfma_f32_16x16x32_bf16 v[108:111], v[128:131], v[190:193], v[108:111]
	v_mfma_f32_16x16x32_bf16 v[104:107], v[136:139], v[190:193], v[104:107]
	v_mfma_f32_16x16x32_bf16 v[92:95], v[128:131], v[214:217], v[92:95]
	v_mfma_f32_16x16x32_bf16 v[88:91], v[136:139], v[214:217], v[88:91]
	v_mfma_f32_16x16x32_bf16 v[76:79], v[128:131], v[222:225], v[76:79]
	v_mfma_f32_16x16x32_bf16 v[72:75], v[136:139], v[222:225], v[72:75]
	v_mfma_f32_16x16x32_bf16 v[124:127], v[132:135], v[184:187], v[124:127]
	v_mfma_f32_16x16x32_bf16 v[120:123], v[140:143], v[184:187], v[120:123]
	v_mfma_f32_16x16x32_bf16 v[108:111], v[132:135], v[210:213], v[108:111]
	v_mfma_f32_16x16x32_bf16 v[104:107], v[140:143], v[210:213], v[104:107]
	v_mfma_f32_16x16x32_bf16 v[92:95], v[132:135], v[218:221], v[92:95]
	v_mfma_f32_16x16x32_bf16 v[88:91], v[140:143], v[218:221], v[88:91]
	v_mfma_f32_16x16x32_bf16 v[76:79], v[132:135], v[226:229], v[76:79]
	v_mfma_f32_16x16x32_bf16 v[72:75], v[140:143], v[226:229], v[72:75]
	s_setprio 0
	s_setprio 1
	v_mfma_f32_16x16x32_bf16 v[116:119], v[144:147], v[176:179], v[116:119]
	v_mfma_f32_16x16x32_bf16 v[112:115], v[152:155], v[176:179], v[112:115]
	v_mfma_f32_16x16x32_bf16 v[100:103], v[144:147], v[190:193], v[100:103]
	v_mfma_f32_16x16x32_bf16 v[96:99], v[152:155], v[190:193], v[96:99]
	v_mfma_f32_16x16x32_bf16 v[84:87], v[144:147], v[214:217], v[84:87]
	v_mfma_f32_16x16x32_bf16 v[80:83], v[152:155], v[214:217], v[80:83]
	v_mfma_f32_16x16x32_bf16 v[68:71], v[144:147], v[222:225], v[68:71]
	v_mfma_f32_16x16x32_bf16 v[64:67], v[152:155], v[222:225], v[64:67]
	v_mfma_f32_16x16x32_bf16 v[116:119], v[148:151], v[184:187], v[116:119]
	v_mfma_f32_16x16x32_bf16 v[112:115], v[156:159], v[184:187], v[112:115]
	v_mfma_f32_16x16x32_bf16 v[100:103], v[148:151], v[210:213], v[100:103]
	v_mfma_f32_16x16x32_bf16 v[96:99], v[156:159], v[210:213], v[96:99]
	v_mfma_f32_16x16x32_bf16 v[84:87], v[148:151], v[218:221], v[84:87]
	v_mfma_f32_16x16x32_bf16 v[80:83], v[156:159], v[218:221], v[80:83]
	v_mfma_f32_16x16x32_bf16 v[68:71], v[148:151], v[226:229], v[68:71]
	v_mfma_f32_16x16x32_bf16 v[64:67], v[156:159], v[226:229], v[64:67]
	s_setprio 0
	s_barrier
; #define PG8_STAGE(bufoff, gbase, voff) do { _Pragma("unroll") for (int _i = 0; _i < 2; ++_i) \
;         __builtin_amdgcn_global_load_lds((const unsigned*)((const char*)(gbase) + (voff)[_i]), (PG8_LAS unsigned*)(lds + (bufoff) + ldsw + _i * 8192), 16, 0, 0); } while (0)
; #define PG8_LDA(dst, b, h) do { _Pragma("unroll") for (int m = 0; m < 4; ++m) _Pragma("unroll") for (int k = 0; k < 2; ++k) dst[m][k] = *(const PG8_LAS bf16x8*)(lds + PG8_SA(b, h) + aoff + m * 2048 + k * 1024); } while (0)
; #define PG8_MMA(ai, bj, At, Bt) do { __builtin_amdgcn_s_setprio(1); _Pragma("unroll") for (int m = 0; m < 4; ++m) _Pragma("unroll") for (int n = 0; n < 2; ++n) _Pragma("unroll") for (int k = 0; k < 2; ++k) \
;         acc[ai][bj][m][n] = __builtin_amdgcn_mfma_f32_16x16x32_bf16(Bt[n][k], At[m][k], acc[ai][bj][m][n], 0, 0, 0); __builtin_amdgcn_s_setprio(0); } while (0)
; #define PG8_WAIT_V(n) asm volatile("s_waitcnt vmcnt(" #n ")" ::: "memory")
; #define PG8_WAIT_L(n) asm volatile("s_waitcnt lgkmcnt(" #n ")" ::: "memory")
; #define PG8_BAR __builtin_amdgcn_s_barrier()
; #define PG8_SCHED __builtin_amdgcn_sched_barrier(0)
; template <class Epi, class Sched, bool ALIGN_EPI = false, bool SP2 = false>
; __device__ __forceinline__ void gemm_phase(PG8_LAS unsigned char* lds, const Gemm g, const Sched& S, const Epi& E) {
;     ...
;         for (int t = 0; t < nt; t += 2) {
;             const bool last = (t == nt - 2);
;             const char* a1 = cA + (size_t)(t + 1) * kstep;
;             const char* a2 = last ? nA : cA + (size_t)(t + 2) * kstep; const char* b2 = last ? nB : cB + (size_t)(t + 2) * kstep;
;             const char* a3 = a2 + kstep; const char* b3 = b2 + kstep;
;     ...
;             PG8_LDA(At, 1, 1); PG8_STAGE(PG8_SB(1, 0), b3, voffB); PG8_STAGE(PG8_SB(1, 1), b3 + hstep, voffB); PG8_STAGE(PG8_SA(1, 0), a3, voffA);
;             PG8_WAIT_V(8); PG8_WAIT_L(0); PG8_BAR; PG8_MMA(1, 0, At, B0); PG8_MMA(1, 1, At, B1); PG8_BAR; PG8_SCHED;
	s_add_i32 s60, s86, s64
	v_lshl_add_u64 v[180:181], v[180:181], 0, s[40:41]
	s_mov_b32 m0, s60
	ds_read_b128 v[176:179], v207 offset:49152
	ds_read_b128 v[184:187], v207 offset:50176
	ds_read_b128 v[190:193], v207 offset:51200
	ds_read_b128 v[210:213], v207 offset:52224
	ds_read_b128 v[214:217], v207 offset:53248
	ds_read_b128 v[218:221], v207 offset:54272
	ds_read_b128 v[222:225], v207 offset:55296
	ds_read_b128 v[226:229], v207 offset:56320
	global_load_lds_dwordx4 v[180:181], off
	s_add_i32 m0, s60, 0x2000
	s_add_u32 s12, s12, 0x80080
	v_lshl_add_u64 v[180:181], v[194:195], 0, s[40:41]
	s_addc_u32 s13, s13, 0
	s_add_i32 s60, s87, s64
	global_load_lds_dwordx4 v[180:181], off
	s_nop 0
	s_mov_b32 m0, s60
	s_nop 0
	global_load_lds_dwordx4 v162, s[12:13]
	s_nop 0
	s_add_i32 m0, s60, 0x2000
	s_nop 0
	global_load_lds_dwordx4 v166, s[12:13]
	v_lshl_add_u64 v[180:181], v[198:199], 0, s[40:41]
	s_mov_b32 m0, s71
	s_nop 0
	global_load_lds_dwordx4 v[180:181], off
	v_lshl_add_u64 v[180:181], v[202:203], 0, s[40:41]
	s_mov_b32 m0, s72
	s_nop 0
	global_load_lds_dwordx4 v[180:181], off
	s_waitcnt vmcnt(8)
	s_waitcnt lgkmcnt(0)
	s_barrier
	s_setprio 1
	s_waitcnt lgkmcnt(0)
	v_mfma_f32_16x16x32_bf16 v[60:63], v[128:131], v[176:179], v[60:63]
	v_mfma_f32_16x16x32_bf16 v[56:59], v[136:139], v[176:179], v[56:59]
	v_mfma_f32_16x16x32_bf16 v[44:47], v[128:131], v[190:193], v[44:47]
	v_mfma_f32_16x16x32_bf16 v[40:43], v[136:139], v[190:193], v[40:43]
	v_mfma_f32_16x16x32_bf16 v[28:31], v[128:131], v[214:217], v[28:31]
	v_mfma_f32_16x16x32_bf16 v[24:27], v[136:139], v[214:217], v[24:27]
	v_mfma_f32_16x16x32_bf16 v[12:15], v[128:131], v[222:225], v[12:15]
	v_mfma_f32_16x16x32_bf16 v[8:11], v[136:139], v[222:225], v[8:11]
	v_mfma_f32_16x16x32_bf16 v[60:63], v[132:135], v[184:187], v[60:63]
	v_mfma_f32_16x16x32_bf16 v[56:59], v[140:143], v[184:187], v[56:59]
	v_mfma_f32_16x16x32_bf16 v[44:47], v[132:135], v[210:213], v[44:47]
	v_mfma_f32_16x16x32_bf16 v[40:43], v[140:143], v[210:213], v[40:43]
	v_mfma_f32_16x16x32_bf16 v[28:31], v[132:135], v[218:221], v[28:31]
	v_mfma_f32_16x16x32_bf16 v[24:27], v[140:143], v[218:221], v[24:27]
	v_mfma_f32_16x16x32_bf16 v[12:15], v[132:135], v[226:229], v[12:15]
	v_mfma_f32_16x16x32_bf16 v[8:11], v[140:143], v[226:229], v[8:11]
	s_setprio 0
	s_setprio 1
	v_mfma_f32_16x16x32_bf16 v[52:55], v[144:147], v[176:179], v[52:55]
	v_mfma_f32_16x16x32_bf16 v[48:51], v[152:155], v[176:179], v[48:51]
	v_mfma_f32_16x16x32_bf16 v[36:39], v[144:147], v[190:193], v[36:39]
	v_mfma_f32_16x16x32_bf16 v[32:35], v[152:155], v[190:193], v[32:35]
	v_mfma_f32_16x16x32_bf16 v[20:23], v[144:147], v[214:217], v[20:23]
	v_mfma_f32_16x16x32_bf16 v[16:19], v[152:155], v[214:217], v[16:19]
	v_mfma_f32_16x16x32_bf16 v[4:7], v[144:147], v[222:225], v[4:7]
	v_mfma_f32_16x16x32_bf16 v[0:3], v[152:155], v[222:225], v[0:3]
	v_mfma_f32_16x16x32_bf16 v[52:55], v[148:151], v[184:187], v[52:55]
	v_mfma_f32_16x16x32_bf16 v[48:51], v[156:159], v[184:187], v[48:51]
	v_mfma_f32_16x16x32_bf16 v[36:39], v[148:151], v[210:213], v[36:39]
	v_mfma_f32_16x16x32_bf16 v[32:35], v[156:159], v[210:213], v[32:35]
	v_mfma_f32_16x16x32_bf16 v[20:23], v[148:151], v[218:221], v[20:23]
	v_mfma_f32_16x16x32_bf16 v[16:19], v[156:159], v[218:221], v[16:19]
	v_mfma_f32_16x16x32_bf16 v[4:7], v[148:151], v[226:229], v[4:7]
	v_mfma_f32_16x16x32_bf16 v[0:3], v[156:159], v[226:229], v[0:3]
	s_setprio 0
	s_barrier
	s_add_i32 s85, s85, 2
	s_add_u32 s10, s10, 0x100
	s_addc_u32 s11, s11, 0
	s_add_u32 s83, s83, 0x100
	s_addc_u32 s84, s84, 0
	s_cmp_gt_u32 s85, 29
	s_cbranch_scc0 .LBB0_428
	s_and_b64 vcc, exec, s[42:43]
	s_cbranch_vccz .LBB0_431
	s_barrier

; #define PG8_STAGE(bufoff, gbase, voff) do { _Pragma("unroll") for (int _i = 0; _i < 2; ++_i) \
;         __builtin_amdgcn_global_load_lds((const unsigned*)((const char*)(gbase) + (voff)[_i]), (PG8_LAS unsigned*)(lds + (bufoff) + ldsw + _i * 8192), 16, 0, 0); } while (0)
; #define PG8_LDA(dst, b, h) do { _Pragma("unroll") for (int m = 0; m < 4; ++m) _Pragma("unroll") for (int k = 0; k < 2; ++k) dst[m][k] = *(const PG8_LAS bf16x8*)(lds + PG8_SA(b, h) + aoff + m * 2048 + k * 1024); } while (0)
; #define PG8_LDB(dst, b, h) do { _Pragma("unroll") for (int n = 0; n < 2; ++n) _Pragma("unroll") for (int k = 0; k < 2; ++k) dst[n][k] = *(const PG8_LAS bf16x8*)(lds + PG8_SB(b, h) + boff + n * 2048 + k * 1024); } while (0)
; #define PG8_MMA(ai, bj, At, Bt) do { __builtin_amdgcn_s_setprio(1); _Pragma("unroll") for (int m = 0; m < 4; ++m) _Pragma("unroll") for (int n = 0; n < 2; ++n) _Pragma("unroll") for (int k = 0; k < 2; ++k) \
;         acc[ai][bj][m][n] = __builtin_amdgcn_mfma_f32_16x16x32_bf16(Bt[n][k], At[m][k], acc[ai][bj][m][n], 0, 0, 0); __builtin_amdgcn_s_setprio(0); } while (0)
; #define PG8_WAIT_V(n) asm volatile("s_waitcnt vmcnt(" #n ")" ::: "memory")
; #define PG8_WAIT_L(n) asm volatile("s_waitcnt lgkmcnt(" #n ")" ::: "memory")
; #define PG8_BAR __builtin_amdgcn_s_barrier()
; #define PG8_SCHED __builtin_amdgcn_sched_barrier(0)
; template <class Epi, class Sched, bool ALIGN_EPI = false, bool SP2 = false>
; __device__ __forceinline__ void gemm_phase(PG8_LAS unsigned char* lds, const Gemm g, const Sched& S, const Epi& E) {
;     ...
;             PG8_LDB(B0, 0, 0); PG8_LDB(B1, 0, 1); PG8_SCHED; PG8_LDA(At, 0, 0); PG8_STAGE(PG8_SA(1, 1), a1 + hstep, voffA);
;             PG8_WAIT_V(8); PG8_WAIT_L(0); PG8_BAR; PG8_MMA(0, 0, At, B0); PG8_MMA(0, 1, At, B1); PG8_BAR; PG8_SCHED;
;             PG8_LDA(At, 0, 1); PG8_STAGE(PG8_SB(0, 0), b2, voffB); PG8_STAGE(PG8_SB(0, 1), b2 + hstep, voffB); PG8_STAGE(PG8_SA(0, 0), a2, voffA);
;             PG8_WAIT_V(8); PG8_WAIT_L(0); PG8_BAR; PG8_MMA(1, 0, At, B0); PG8_MMA(1, 1, At, B1); PG8_BAR; PG8_SCHED;
.LBB0_509:
	ds_read_b128 v[64:67], v213
	ds_read_b128 v[68:71], v213 offset:1024
	ds_read_b128 v[72:75], v213 offset:2048
	ds_read_b128 v[76:79], v213 offset:3072
	ds_read_b128 v[144:147], v214
	ds_read_b128 v[148:151], v214 offset:1024
	ds_read_b128 v[152:155], v214 offset:2048
	ds_read_b128 v[156:159], v214 offset:3072
	s_add_u32 s60, s58, 0xffe00080
	s_addc_u32 s61, s59, -1
	s_cmpk_eq_i32 s81, 0x7c
	s_cselect_b32 s63, s11, s61
	s_cselect_b32 s62, s51, s60
	s_cselect_b32 s61, s49, s80
	s_cselect_b32 s60, s78, s79
	s_nop 0
	s_add_i32 m0, s57, 0xc000
	ds_read_b128 v[176:179], v215
	ds_read_b128 v[180:183], v215 offset:1024
	ds_read_b128 v[184:187], v215 offset:2048
	ds_read_b128 v[188:191], v215 offset:3072
	ds_read_b128 v[192:195], v215 offset:4096
	ds_read_b128 v[196:199], v215 offset:5120
	ds_read_b128 v[200:203], v215 offset:6144
	ds_read_b128 v[204:207], v215 offset:7168
	global_load_lds_dwordx4 v168, s[58:59]
	s_nop 0
	s_add_i32 m0, s57, 0xe000
	s_nop 0
	global_load_lds_dwordx4 v170, s[58:59]
	s_waitcnt vmcnt(8)
	s_waitcnt lgkmcnt(0)
	s_barrier
	s_setprio 1
	s_waitcnt lgkmcnt(0)
	v_mfma_f32_16x16x32_bf16 v[140:143], v[64:67], v[176:179], v[140:143]
	v_mfma_f32_16x16x32_bf16 v[136:139], v[72:75], v[176:179], v[136:139]
	v_mfma_f32_16x16x32_bf16 v[124:127], v[64:67], v[184:187], v[124:127]
	v_mfma_f32_16x16x32_bf16 v[120:123], v[72:75], v[184:187], v[120:123]
	v_mfma_f32_16x16x32_bf16 v[108:111], v[64:67], v[192:195], v[108:111]
	v_mfma_f32_16x16x32_bf16 v[104:107], v[72:75], v[192:195], v[104:107]
	v_mfma_f32_16x16x32_bf16 v[92:95], v[64:67], v[200:203], v[92:95]
	v_mfma_f32_16x16x32_bf16 v[88:91], v[72:75], v[200:203], v[88:91]
	v_mfma_f32_16x16x32_bf16 v[140:143], v[68:71], v[180:183], v[140:143]
	v_mfma_f32_16x16x32_bf16 v[136:139], v[76:79], v[180:183], v[136:139]
	v_mfma_f32_16x16x32_bf16 v[124:127], v[68:71], v[188:191], v[124:127]
	v_mfma_f32_16x16x32_bf16 v[120:123], v[76:79], v[188:191], v[120:123]
	v_mfma_f32_16x16x32_bf16 v[108:111], v[68:71], v[196:199], v[108:111]
	v_mfma_f32_16x16x32_bf16 v[104:107], v[76:79], v[196:199], v[104:107]
	v_mfma_f32_16x16x32_bf16 v[92:95], v[68:71], v[204:207], v[92:95]
	v_mfma_f32_16x16x32_bf16 v[88:91], v[76:79], v[204:207], v[88:91]
	s_setprio 0
	s_setprio 1
	v_mfma_f32_16x16x32_bf16 v[132:135], v[144:147], v[176:179], v[132:135]
	v_mfma_f32_16x16x32_bf16 v[128:131], v[152:155], v[176:179], v[128:131]
	v_mfma_f32_16x16x32_bf16 v[116:119], v[144:147], v[184:187], v[116:119]
	v_mfma_f32_16x16x32_bf16 v[112:115], v[152:155], v[184:187], v[112:115]
	v_mfma_f32_16x16x32_bf16 v[100:103], v[144:147], v[192:195], v[100:103]
	v_mfma_f32_16x16x32_bf16 v[96:99], v[152:155], v[192:195], v[96:99]
	v_mfma_f32_16x16x32_bf16 v[84:87], v[144:147], v[200:203], v[84:87]
	v_mfma_f32_16x16x32_bf16 v[80:83], v[152:155], v[200:203], v[80:83]
	v_mfma_f32_16x16x32_bf16 v[132:135], v[148:151], v[180:183], v[132:135]
	v_mfma_f32_16x16x32_bf16 v[128:131], v[156:159], v[180:183], v[128:131]
	v_mfma_f32_16x16x32_bf16 v[116:119], v[148:151], v[188:191], v[116:119]
	v_mfma_f32_16x16x32_bf16 v[112:115], v[156:159], v[188:191], v[112:115]
	v_mfma_f32_16x16x32_bf16 v[100:103], v[148:151], v[196:199], v[100:103]
	v_mfma_f32_16x16x32_bf16 v[96:99], v[156:159], v[196:199], v[96:99]
	v_mfma_f32_16x16x32_bf16 v[84:87], v[148:151], v[204:207], v[84:87]
	v_mfma_f32_16x16x32_bf16 v[80:83], v[156:159], v[204:207], v[80:83]
	s_setprio 0
	s_barrier
	s_add_i32 s82, s75, s64
	v_lshl_add_u64 v[208:209], s[60:61], 0, v[162:163]
	s_mov_b32 m0, s82
	ds_read_b128 v[176:179], v215 offset:16384
	ds_read_b128 v[180:183], v215 offset:17408
	ds_read_b128 v[184:187], v215 offset:18432
	ds_read_b128 v[188:191], v215 offset:19456
	ds_read_b128 v[192:195], v215 offset:20480
	ds_read_b128 v[196:199], v215 offset:21504
	ds_read_b128 v[200:203], v215 offset:22528
	ds_read_b128 v[204:207], v215 offset:23552
	global_load_lds_dwordx4 v[208:209], off
	s_add_i32 m0, s82, 0x2000
	s_add_u32 s82, s60, 0x200000
	v_lshl_add_u64 v[218:219], s[60:61], 0, v[166:167]
	s_addc_u32 s83, s61, 0
	s_add_i32 s84, s76, s64
	global_load_lds_dwordx4 v[218:219], off
	s_nop 0
	s_mov_b32 m0, s84
	v_lshl_add_u64 v[222:223], s[62:63], 0, v[164:165]
	global_load_lds_dwordx4 v162, s[82:83]
	s_nop 0
	s_add_i32 m0, s84, 0x2000
	s_nop 0
	global_load_lds_dwordx4 v166, s[82:83]
	v_lshl_add_u64 v[220:221], s[62:63], 0, v[160:161]
	s_mov_b32 m0, s57
	s_nop 0
	global_load_lds_dwordx4 v[220:221], off
	s_mov_b32 m0, s65
	s_nop 0
	global_load_lds_dwordx4 v[222:223], off
	s_waitcnt vmcnt(8)
	s_waitcnt lgkmcnt(0)
	s_barrier
; #define PG8_STAGE(bufoff, gbase, voff) do { _Pragma("unroll") for (int _i = 0; _i < 2; ++_i) \
;         __builtin_amdgcn_global_load_lds((const unsigned*)((const char*)(gbase) + (voff)[_i]), (PG8_LAS unsigned*)(lds + (bufoff) + ldsw + _i * 8192), 16, 0, 0); } while (0)
; #define PG8_LDA(dst, b, h) do { _Pragma("unroll") for (int m = 0; m < 4; ++m) _Pragma("unroll") for (int k = 0; k < 2; ++k) dst[m][k] = *(const PG8_LAS bf16x8*)(lds + PG8_SA(b, h) + aoff + m * 2048 + k * 1024); } while (0)
; #define PG8_LDB(dst, b, h) do { _Pragma("unroll") for (int n = 0; n < 2; ++n) _Pragma("unroll") for (int k = 0; k < 2; ++k) dst[n][k] = *(const PG8_LAS bf16x8*)(lds + PG8_SB(b, h) + boff + n * 2048 + k * 1024); } while (0)
; #define PG8_MMA(ai, bj, At, Bt) do { __builtin_amdgcn_s_setprio(1); _Pragma("unroll") for (int m = 0; m < 4; ++m) _Pragma("unroll") for (int n = 0; n < 2; ++n) _Pragma("unroll") for (int k = 0; k < 2; ++k) \
;         acc[ai][bj][m][n] = __builtin_amdgcn_mfma_f32_16x16x32_bf16(Bt[n][k], At[m][k], acc[ai][bj][m][n], 0, 0, 0); __builtin_amdgcn_s_setprio(0); } while (0)
; #define PG8_WAIT_V(n) asm volatile("s_waitcnt vmcnt(" #n ")" ::: "memory")
; #define PG8_WAIT_L(n) asm volatile("s_waitcnt lgkmcnt(" #n ")" ::: "memory")
; #define PG8_BAR __builtin_amdgcn_s_barrier()
; #define PG8_SCHED __builtin_amdgcn_sched_barrier(0)
; template <class Epi, class Sched, bool ALIGN_EPI = false, bool SP2 = false>
; __device__ __forceinline__ void gemm_phase(PG8_LAS unsigned char* lds, const Gemm g, const Sched& S, const Epi& E) {
;     ...
;             PG8_WAIT_V(8); PG8_WAIT_L(0); PG8_BAR; PG8_MMA(1, 0, At, B0); PG8_MMA(1, 1, At, B1); PG8_BAR; PG8_SCHED;
;             PG8_LDB(B0, 1, 0); PG8_LDB(B1, 1, 1); PG8_SCHED; PG8_LDA(At, 1, 0); PG8_STAGE(PG8_SA(0, 1), a2 + hstep, voffA);
;             PG8_WAIT_V(8); PG8_WAIT_L(0); PG8_BAR; PG8_MMA(0, 0, At, B0); PG8_MMA(0, 1, At, B1); PG8_BAR; PG8_SCHED;
	s_setprio 1
	s_waitcnt lgkmcnt(0)
	v_mfma_f32_16x16x32_bf16 v[60:63], v[64:67], v[176:179], v[60:63]
	v_mfma_f32_16x16x32_bf16 v[56:59], v[72:75], v[176:179], v[56:59]
	v_mfma_f32_16x16x32_bf16 v[44:47], v[64:67], v[184:187], v[44:47]
	v_mfma_f32_16x16x32_bf16 v[40:43], v[72:75], v[184:187], v[40:43]
	v_mfma_f32_16x16x32_bf16 v[28:31], v[64:67], v[192:195], v[28:31]
	v_mfma_f32_16x16x32_bf16 v[24:27], v[72:75], v[192:195], v[24:27]
	v_mfma_f32_16x16x32_bf16 v[12:15], v[64:67], v[200:203], v[12:15]
	v_mfma_f32_16x16x32_bf16 v[8:11], v[72:75], v[200:203], v[8:11]
	v_mfma_f32_16x16x32_bf16 v[60:63], v[68:71], v[180:183], v[60:63]
	v_mfma_f32_16x16x32_bf16 v[56:59], v[76:79], v[180:183], v[56:59]
	v_mfma_f32_16x16x32_bf16 v[44:47], v[68:71], v[188:191], v[44:47]
	v_mfma_f32_16x16x32_bf16 v[40:43], v[76:79], v[188:191], v[40:43]
	v_mfma_f32_16x16x32_bf16 v[28:31], v[68:71], v[196:199], v[28:31]
	v_mfma_f32_16x16x32_bf16 v[24:27], v[76:79], v[196:199], v[24:27]
	v_mfma_f32_16x16x32_bf16 v[12:15], v[68:71], v[204:207], v[12:15]
	v_mfma_f32_16x16x32_bf16 v[8:11], v[76:79], v[204:207], v[8:11]
	s_setprio 0
	s_setprio 1
	v_mfma_f32_16x16x32_bf16 v[52:55], v[144:147], v[176:179], v[52:55]
	v_mfma_f32_16x16x32_bf16 v[48:51], v[152:155], v[176:179], v[48:51]
	v_mfma_f32_16x16x32_bf16 v[36:39], v[144:147], v[184:187], v[36:39]
	v_mfma_f32_16x16x32_bf16 v[32:35], v[152:155], v[184:187], v[32:35]
	v_mfma_f32_16x16x32_bf16 v[20:23], v[144:147], v[192:195], v[20:23]
	v_mfma_f32_16x16x32_bf16 v[16:19], v[152:155], v[192:195], v[16:19]
	v_mfma_f32_16x16x32_bf16 v[4:7], v[144:147], v[200:203], v[4:7]
	v_mfma_f32_16x16x32_bf16 v[0:3], v[152:155], v[200:203], v[0:3]
	v_mfma_f32_16x16x32_bf16 v[52:55], v[148:151], v[180:183], v[52:55]
	v_mfma_f32_16x16x32_bf16 v[48:51], v[156:159], v[180:183], v[48:51]
	v_mfma_f32_16x16x32_bf16 v[36:39], v[148:151], v[188:191], v[36:39]
	v_mfma_f32_16x16x32_bf16 v[32:35], v[156:159], v[188:191], v[32:35]
	v_mfma_f32_16x16x32_bf16 v[20:23], v[148:151], v[196:199], v[20:23]
	v_mfma_f32_16x16x32_bf16 v[16:19], v[156:159], v[196:199], v[16:19]
	v_mfma_f32_16x16x32_bf16 v[4:7], v[148:151], v[204:207], v[4:7]
	v_mfma_f32_16x16x32_bf16 v[0:3], v[156:159], v[204:207], v[0:3]
	s_setprio 0
	s_barrier
	s_add_i32 s82, 0, 0x18000
	s_add_i32 s83, 0, 0x1c000
	v_add_u32_e32 v76, s82, v211
	v_add_u32_e32 v156, s83, v211
	ds_read_b128 v[64:67], v76
	ds_read_b128 v[68:71], v76 offset:1024
	ds_read_b128 v[72:75], v76 offset:2048
	ds_read_b128 v[76:79], v76 offset:3072
	ds_read_b128 v[144:147], v156
	ds_read_b128 v[148:151], v156 offset:1024
	ds_read_b128 v[152:155], v156 offset:2048
	ds_read_b128 v[156:159], v156 offset:3072
	s_add_u32 s62, s62, 0x200000
	s_addc_u32 s63, s63, 0
	s_mov_b32 m0, s67
	s_nop 0
	ds_read_b128 v[176:179], v215 offset:32768
	ds_read_b128 v[180:183], v215 offset:33792
	ds_read_b128 v[184:187], v215 offset:34816
	ds_read_b128 v[188:191], v215 offset:35840
	ds_read_b128 v[192:195], v215 offset:36864
	ds_read_b128 v[196:199], v215 offset:37888
	ds_read_b128 v[200:203], v215 offset:38912
	ds_read_b128 v[204:207], v215 offset:39936
	global_load_lds_dwordx4 v160, s[62:63]
	s_nop 0
	s_mov_b32 m0, s68
	s_nop 0
	global_load_lds_dwordx4 v164, s[62:63]
	s_waitcnt vmcnt(8)
	s_waitcnt lgkmcnt(0)
	s_barrier
	s_setprio 1
	s_waitcnt lgkmcnt(0)
	v_mfma_f32_16x16x32_bf16 v[140:143], v[64:67], v[176:179], v[140:143]
	v_mfma_f32_16x16x32_bf16 v[136:139], v[72:75], v[176:179], v[136:139]
	v_mfma_f32_16x16x32_bf16 v[124:127], v[64:67], v[184:187], v[124:127]
	v_mfma_f32_16x16x32_bf16 v[120:123], v[72:75], v[184:187], v[120:123]
	v_mfma_f32_16x16x32_bf16 v[108:111], v[64:67], v[192:195], v[108:111]
	v_mfma_f32_16x16x32_bf16 v[104:107], v[72:75], v[192:195], v[104:107]
	v_mfma_f32_16x16x32_bf16 v[92:95], v[64:67], v[200:203], v[92:95]
	v_mfma_f32_16x16x32_bf16 v[88:91], v[72:75], v[200:203], v[88:91]
	v_mfma_f32_16x16x32_bf16 v[140:143], v[68:71], v[180:183], v[140:143]
	v_mfma_f32_16x16x32_bf16 v[136:139], v[76:79], v[180:183], v[136:139]
	v_mfma_f32_16x16x32_bf16 v[124:127], v[68:71], v[188:191], v[124:127]
	v_mfma_f32_16x16x32_bf16 v[120:123], v[76:79], v[188:191], v[120:123]
	v_mfma_f32_16x16x32_bf16 v[108:111], v[68:71], v[196:199], v[108:111]
	v_mfma_f32_16x16x32_bf16 v[104:107], v[76:79], v[196:199], v[104:107]
	v_mfma_f32_16x16x32_bf16 v[92:95], v[68:71], v[204:207], v[92:95]
	v_mfma_f32_16x16x32_bf16 v[88:91], v[76:79], v[204:207], v[88:91]
	s_setprio 0
	s_setprio 1
	v_mfma_f32_16x16x32_bf16 v[132:135], v[144:147], v[176:179], v[132:135]
	v_mfma_f32_16x16x32_bf16 v[128:131], v[152:155], v[176:179], v[128:131]
	v_mfma_f32_16x16x32_bf16 v[116:119], v[144:147], v[184:187], v[116:119]
	v_mfma_f32_16x16x32_bf16 v[112:115], v[152:155], v[184:187], v[112:115]
	v_mfma_f32_16x16x32_bf16 v[100:103], v[144:147], v[192:195], v[100:103]
	v_mfma_f32_16x16x32_bf16 v[96:99], v[152:155], v[192:195], v[96:99]
	v_mfma_f32_16x16x32_bf16 v[84:87], v[144:147], v[200:203], v[84:87]
	v_mfma_f32_16x16x32_bf16 v[80:83], v[152:155], v[200:203], v[80:83]
	v_mfma_f32_16x16x32_bf16 v[132:135], v[148:151], v[180:183], v[132:135]
	v_mfma_f32_16x16x32_bf16 v[128:131], v[156:159], v[180:183], v[128:131]
	v_mfma_f32_16x16x32_bf16 v[116:119], v[148:151], v[188:191], v[116:119]
	v_mfma_f32_16x16x32_bf16 v[112:115], v[156:159], v[188:191], v[112:115]
	v_mfma_f32_16x16x32_bf16 v[100:103], v[148:151], v[196:199], v[100:103]
	v_mfma_f32_16x16x32_bf16 v[96:99], v[156:159], v[196:199], v[96:99]
	v_mfma_f32_16x16x32_bf16 v[84:87], v[148:151], v[204:207], v[84:87]
	v_mfma_f32_16x16x32_bf16 v[80:83], v[156:159], v[204:207], v[80:83]
	s_setprio 0
	s_barrier
; #define PG8_STAGE(bufoff, gbase, voff) do { _Pragma("unroll") for (int _i = 0; _i < 2; ++_i) \
;         __builtin_amdgcn_global_load_lds((const unsigned*)((const char*)(gbase) + (voff)[_i]), (PG8_LAS unsigned*)(lds + (bufoff) + ldsw + _i * 8192), 16, 0, 0); } while (0)
; #define PG8_LDA(dst, b, h) do { _Pragma("unroll") for (int m = 0; m < 4; ++m) _Pragma("unroll") for (int k = 0; k < 2; ++k) dst[m][k] = *(const PG8_LAS bf16x8*)(lds + PG8_SA(b, h) + aoff + m * 2048 + k * 1024); } while (0)
; #define PG8_MMA(ai, bj, At, Bt) do { __builtin_amdgcn_s_setprio(1); _Pragma("unroll") for (int m = 0; m < 4; ++m) _Pragma("unroll") for (int n = 0; n < 2; ++n) _Pragma("unroll") for (int k = 0; k < 2; ++k) \
;         acc[ai][bj][m][n] = __builtin_amdgcn_mfma_f32_16x16x32_bf16(Bt[n][k], At[m][k], acc[ai][bj][m][n], 0, 0, 0); __builtin_amdgcn_s_setprio(0); } while (0)
; #define PG8_WAIT_V(n) asm volatile("s_waitcnt vmcnt(" #n ")" ::: "memory")
; #define PG8_WAIT_L(n) asm volatile("s_waitcnt lgkmcnt(" #n ")" ::: "memory")
; #define PG8_BAR __builtin_amdgcn_s_barrier()
; #define PG8_SCHED __builtin_amdgcn_sched_barrier(0)
; template <class Epi, class Sched, bool ALIGN_EPI = false, bool SP2 = false>
; __device__ __forceinline__ void gemm_phase(PG8_LAS unsigned char* lds, const Gemm g, const Sched& S, const Epi& E) {
;     ...
;         for (int t = 0; t < nt; t += 2) {
;             const bool last = (t == nt - 2);
;             const char* a1 = cA + (size_t)(t + 1) * kstep;
;             const char* a2 = last ? nA : cA + (size_t)(t + 2) * kstep; const char* b2 = last ? nB : cB + (size_t)(t + 2) * kstep;
;             const char* a3 = a2 + kstep; const char* b3 = b2 + kstep;
;     ...
;             PG8_LDA(At, 1, 1); PG8_STAGE(PG8_SB(1, 0), b3, voffB); PG8_STAGE(PG8_SB(1, 1), b3 + hstep, voffB); PG8_STAGE(PG8_SA(1, 0), a3, voffA);
;             PG8_WAIT_V(8); PG8_WAIT_L(0); PG8_BAR; PG8_MMA(1, 0, At, B0); PG8_MMA(1, 1, At, B1); PG8_BAR; PG8_SCHED;
	s_add_i32 s62, s82, s64
	v_lshl_add_u64 v[208:209], v[208:209], 0, s[40:41]
	s_mov_b32 m0, s62
	ds_read_b128 v[176:179], v215 offset:49152
	ds_read_b128 v[180:183], v215 offset:50176
	ds_read_b128 v[184:187], v215 offset:51200
	ds_read_b128 v[188:191], v215 offset:52224
	ds_read_b128 v[192:195], v215 offset:53248
	ds_read_b128 v[196:199], v215 offset:54272
	ds_read_b128 v[200:203], v215 offset:55296
	ds_read_b128 v[204:207], v215 offset:56320
	global_load_lds_dwordx4 v[208:209], off
	s_add_i32 m0, s62, 0x2000
	s_add_u32 s60, s60, 0x200080
	v_lshl_add_u64 v[208:209], v[218:219], 0, s[40:41]
	s_addc_u32 s61, s61, 0
	s_add_i32 s62, s83, s64
	global_load_lds_dwordx4 v[208:209], off
	s_nop 0
	s_mov_b32 m0, s62
	s_nop 0
	global_load_lds_dwordx4 v162, s[60:61]
	s_nop 0
	s_add_i32 m0, s62, 0x2000
	s_nop 0
	global_load_lds_dwordx4 v166, s[60:61]
	v_lshl_add_u64 v[208:209], v[220:221], 0, s[40:41]
	s_mov_b32 m0, s70
	s_nop 0
	global_load_lds_dwordx4 v[208:209], off
	v_lshl_add_u64 v[208:209], v[222:223], 0, s[40:41]
	s_mov_b32 m0, s71
	s_nop 0
	global_load_lds_dwordx4 v[208:209], off
	s_waitcnt vmcnt(8)
	s_waitcnt lgkmcnt(0)
	s_barrier
	s_setprio 1
	s_waitcnt lgkmcnt(0)
	v_mfma_f32_16x16x32_bf16 v[60:63], v[64:67], v[176:179], v[60:63]
	v_mfma_f32_16x16x32_bf16 v[56:59], v[72:75], v[176:179], v[56:59]
	v_mfma_f32_16x16x32_bf16 v[44:47], v[64:67], v[184:187], v[44:47]
	v_mfma_f32_16x16x32_bf16 v[40:43], v[72:75], v[184:187], v[40:43]
	v_mfma_f32_16x16x32_bf16 v[28:31], v[64:67], v[192:195], v[28:31]
	v_mfma_f32_16x16x32_bf16 v[24:27], v[72:75], v[192:195], v[24:27]
	v_mfma_f32_16x16x32_bf16 v[12:15], v[64:67], v[200:203], v[12:15]
	v_mfma_f32_16x16x32_bf16 v[8:11], v[72:75], v[200:203], v[8:11]
	v_mfma_f32_16x16x32_bf16 v[60:63], v[68:71], v[180:183], v[60:63]
	v_mfma_f32_16x16x32_bf16 v[56:59], v[76:79], v[180:183], v[56:59]
	v_mfma_f32_16x16x32_bf16 v[44:47], v[68:71], v[188:191], v[44:47]
	v_mfma_f32_16x16x32_bf16 v[40:43], v[76:79], v[188:191], v[40:43]
	v_mfma_f32_16x16x32_bf16 v[28:31], v[68:71], v[196:199], v[28:31]
	v_mfma_f32_16x16x32_bf16 v[24:27], v[76:79], v[196:199], v[24:27]
	v_mfma_f32_16x16x32_bf16 v[12:15], v[68:71], v[204:207], v[12:15]
	v_mfma_f32_16x16x32_bf16 v[8:11], v[76:79], v[204:207], v[8:11]
	s_setprio 0
	s_setprio 1
	v_mfma_f32_16x16x32_bf16 v[52:55], v[144:147], v[176:179], v[52:55]
	v_mfma_f32_16x16x32_bf16 v[48:51], v[152:155], v[176:179], v[48:51]
	v_mfma_f32_16x16x32_bf16 v[36:39], v[144:147], v[184:187], v[36:39]
	v_mfma_f32_16x16x32_bf16 v[32:35], v[152:155], v[184:187], v[32:35]
	v_mfma_f32_16x16x32_bf16 v[20:23], v[144:147], v[192:195], v[20:23]
	v_mfma_f32_16x16x32_bf16 v[16:19], v[152:155], v[192:195], v[16:19]
	v_mfma_f32_16x16x32_bf16 v[4:7], v[144:147], v[200:203], v[4:7]
	v_mfma_f32_16x16x32_bf16 v[0:3], v[152:155], v[200:203], v[0:3]
	v_mfma_f32_16x16x32_bf16 v[52:55], v[148:151], v[180:183], v[52:55]
	v_mfma_f32_16x16x32_bf16 v[48:51], v[156:159], v[180:183], v[48:51]
	v_mfma_f32_16x16x32_bf16 v[36:39], v[148:151], v[188:191], v[36:39]
	v_mfma_f32_16x16x32_bf16 v[32:35], v[156:159], v[188:191], v[32:35]
	v_mfma_f32_16x16x32_bf16 v[20:23], v[148:151], v[196:199], v[20:23]
	v_mfma_f32_16x16x32_bf16 v[16:19], v[156:159], v[196:199], v[16:19]
	v_mfma_f32_16x16x32_bf16 v[4:7], v[148:151], v[204:207], v[4:7]
	v_mfma_f32_16x16x32_bf16 v[0:3], v[156:159], v[204:207], v[0:3]
	s_setprio 0
	s_barrier
	s_add_i32 s81, s81, 2
	s_add_u32 s58, s58, 0x100
	s_addc_u32 s59, s59, 0
	s_add_u32 s79, s79, 0x100
	s_addc_u32 s80, s80, 0
	s_cmpk_gt_u32 s81, 0x7d
	s_cbranch_scc0 .LBB0_509
	s_and_b64 vcc, exec, s[42:43]
	s_cbranch_vccz .LBB0_512
	s_barrier

; #define PG8_STAGE(bufoff, gbase, voff) do { _Pragma("unroll") for (int _i = 0; _i < 2; ++_i) \
;         __builtin_amdgcn_global_load_lds((const unsigned*)((const char*)(gbase) + (voff)[_i]), (PG8_LAS unsigned*)(lds + (bufoff) + ldsw + _i * 8192), 16, 0, 0); } while (0)
; #define PG8_LDA(dst, b, h) do { _Pragma("unroll") for (int m = 0; m < 4; ++m) _Pragma("unroll") for (int k = 0; k < 2; ++k) dst[m][k] = *(const PG8_LAS bf16x8*)(lds + PG8_SA(b, h) + aoff + m * 2048 + k * 1024); } while (0)
; #define PG8_LDB(dst, b, h) do { _Pragma("unroll") for (int n = 0; n < 2; ++n) _Pragma("unroll") for (int k = 0; k < 2; ++k) dst[n][k] = *(const PG8_LAS bf16x8*)(lds + PG8_SB(b, h) + boff + n * 2048 + k * 1024); } while (0)
; #define PG8_MMA(ai, bj, At, Bt) do { __builtin_amdgcn_s_setprio(1); _Pragma("unroll") for (int m = 0; m < 4; ++m) _Pragma("unroll") for (int n = 0; n < 2; ++n) _Pragma("unroll") for (int k = 0; k < 2; ++k) \
;         acc[ai][bj][m][n] = __builtin_amdgcn_mfma_f32_16x16x32_bf16(Bt[n][k], At[m][k], acc[ai][bj][m][n], 0, 0, 0); __builtin_amdgcn_s_setprio(0); } while (0)
; #define PG8_WAIT_V(n) asm volatile("s_waitcnt vmcnt(" #n ")" ::: "memory")
; #define PG8_WAIT_L(n) asm volatile("s_waitcnt lgkmcnt(" #n ")" ::: "memory")
; #define PG8_BAR __builtin_amdgcn_s_barrier()
; #define PG8_SCHED __builtin_amdgcn_sched_barrier(0)
; template <class Epi, class Sched, bool ALIGN_EPI = false, bool SP2 = false>
; __device__ __forceinline__ void gemm_phase(PG8_LAS unsigned char* lds, const Gemm g, const Sched& S, const Epi& E) {
;     ...
;             PG8_LDB(B0, 0, 0); PG8_LDB(B1, 0, 1); PG8_SCHED; PG8_LDA(At, 0, 0); PG8_STAGE(PG8_SA(1, 1), a1 + hstep, voffA);
;             PG8_WAIT_V(8); PG8_WAIT_L(0); PG8_BAR; PG8_MMA(0, 0, At, B0); PG8_MMA(0, 1, At, B1); PG8_BAR; PG8_SCHED;
;             PG8_LDA(At, 0, 1); PG8_STAGE(PG8_SB(0, 0), b2, voffB); PG8_STAGE(PG8_SB(0, 1), b2 + hstep, voffB); PG8_STAGE(PG8_SA(0, 0), a2, voffA);
;             PG8_WAIT_V(8); PG8_WAIT_L(0); PG8_BAR; PG8_MMA(1, 0, At, B0); PG8_MMA(1, 1, At, B1); PG8_BAR; PG8_SCHED;
.LBB0_679:
	ds_read_b128 v[128:131], v203
	ds_read_b128 v[132:135], v203 offset:1024
	ds_read_b128 v[136:139], v203 offset:2048
	ds_read_b128 v[140:143], v203 offset:3072
	ds_read_b128 v[144:147], v205
	ds_read_b128 v[148:151], v205 offset:1024
	ds_read_b128 v[152:155], v205 offset:2048
	ds_read_b128 v[156:159], v205 offset:3072
	s_add_u32 s12, s10, 0xfff80080
	s_addc_u32 s13, s11, -1
	s_cmp_eq_u32 s78, 28
	s_cselect_b32 s55, s49, s13
	s_cselect_b32 s54, s74, s12
	s_cselect_b32 s13, s47, s77
	s_cselect_b32 s12, s75, s76
	s_nop 0
	s_add_i32 m0, s60, 0xc000
	ds_read_b128 v[176:179], v207
	ds_read_b128 v[180:183], v207 offset:1024
	ds_read_b128 v[184:187], v207 offset:2048
	ds_read_b128 v[192:195], v207 offset:3072
	ds_read_b128 v[210:213], v207 offset:4096
	ds_read_b128 v[214:217], v207 offset:5120
	ds_read_b128 v[218:221], v207 offset:6144
	ds_read_b128 v[222:225], v207 offset:7168
	global_load_lds_dwordx4 v168, s[10:11]
	s_nop 0
	s_add_i32 m0, s60, 0xe000
	s_nop 0
	global_load_lds_dwordx4 v170, s[10:11]
	s_waitcnt vmcnt(8)
	s_waitcnt lgkmcnt(0)
	s_barrier
	s_setprio 1
	s_waitcnt lgkmcnt(0)
	v_mfma_f32_16x16x32_bf16 v[124:127], v[128:131], v[176:179], v[124:127]
	v_mfma_f32_16x16x32_bf16 v[120:123], v[136:139], v[176:179], v[120:123]
	v_mfma_f32_16x16x32_bf16 v[112:115], v[128:131], v[184:187], v[112:115]
	v_mfma_f32_16x16x32_bf16 v[104:107], v[136:139], v[184:187], v[104:107]
	v_mfma_f32_16x16x32_bf16 v[100:103], v[128:131], v[210:213], v[100:103]
	v_mfma_f32_16x16x32_bf16 v[88:91], v[136:139], v[210:213], v[88:91]
	v_mfma_f32_16x16x32_bf16 v[84:87], v[128:131], v[218:221], v[84:87]
	v_mfma_f32_16x16x32_bf16 v[72:75], v[136:139], v[218:221], v[72:75]
	v_mfma_f32_16x16x32_bf16 v[124:127], v[132:135], v[180:183], v[124:127]
	v_mfma_f32_16x16x32_bf16 v[120:123], v[140:143], v[180:183], v[120:123]
	v_mfma_f32_16x16x32_bf16 v[112:115], v[132:135], v[192:195], v[112:115]
	v_mfma_f32_16x16x32_bf16 v[104:107], v[140:143], v[192:195], v[104:107]
	v_mfma_f32_16x16x32_bf16 v[100:103], v[132:135], v[214:217], v[100:103]
	v_mfma_f32_16x16x32_bf16 v[88:91], v[140:143], v[214:217], v[88:91]
	v_mfma_f32_16x16x32_bf16 v[84:87], v[132:135], v[222:225], v[84:87]
	v_mfma_f32_16x16x32_bf16 v[72:75], v[140:143], v[222:225], v[72:75]
	s_setprio 0
	s_setprio 1
	v_mfma_f32_16x16x32_bf16 v[116:119], v[144:147], v[176:179], v[116:119]
	v_mfma_f32_16x16x32_bf16 v[108:111], v[152:155], v[176:179], v[108:111]
	v_mfma_f32_16x16x32_bf16 v[96:99], v[144:147], v[184:187], v[96:99]
	v_mfma_f32_16x16x32_bf16 v[92:95], v[152:155], v[184:187], v[92:95]
	v_mfma_f32_16x16x32_bf16 v[80:83], v[144:147], v[210:213], v[80:83]
	v_mfma_f32_16x16x32_bf16 v[76:79], v[152:155], v[210:213], v[76:79]
	v_mfma_f32_16x16x32_bf16 v[68:71], v[144:147], v[218:221], v[68:71]
	v_mfma_f32_16x16x32_bf16 v[64:67], v[152:155], v[218:221], v[64:67]
	v_mfma_f32_16x16x32_bf16 v[116:119], v[148:151], v[180:183], v[116:119]
	v_mfma_f32_16x16x32_bf16 v[108:111], v[156:159], v[180:183], v[108:111]
	v_mfma_f32_16x16x32_bf16 v[96:99], v[148:151], v[192:195], v[96:99]
	v_mfma_f32_16x16x32_bf16 v[92:95], v[156:159], v[192:195], v[92:95]
	v_mfma_f32_16x16x32_bf16 v[80:83], v[148:151], v[214:217], v[80:83]
	v_mfma_f32_16x16x32_bf16 v[76:79], v[156:159], v[214:217], v[76:79]
	v_mfma_f32_16x16x32_bf16 v[68:71], v[148:151], v[222:225], v[68:71]
	v_mfma_f32_16x16x32_bf16 v[64:67], v[156:159], v[222:225], v[64:67]
	s_setprio 0
	s_barrier
	s_add_i32 s79, s70, s57
	v_lshl_add_u64 v[188:189], s[12:13], 0, v[164:165]
	s_mov_b32 m0, s79
	ds_read_b128 v[176:179], v207 offset:16384
	ds_read_b128 v[180:183], v207 offset:17408
	ds_read_b128 v[184:187], v207 offset:18432
	ds_read_b128 v[192:195], v207 offset:19456
	ds_read_b128 v[210:213], v207 offset:20480
	ds_read_b128 v[214:217], v207 offset:21504
	ds_read_b128 v[218:221], v207 offset:22528
	ds_read_b128 v[222:225], v207 offset:23552
	global_load_lds_dwordx4 v[188:189], off
	s_add_i32 m0, s79, 0x2000
	s_add_u32 s80, s12, 0x80000
	v_lshl_add_u64 v[198:199], s[12:13], 0, v[160:161]
	s_addc_u32 s81, s13, 0
	s_add_i32 s79, s71, s57
	global_load_lds_dwordx4 v[198:199], off
	s_nop 0
	s_mov_b32 m0, s79
	v_lshl_add_u64 v[228:229], s[54:55], 0, v[162:163]
	global_load_lds_dwordx4 v164, s[80:81]
	s_nop 0
	s_add_i32 m0, s79, 0x2000
	s_nop 0
	global_load_lds_dwordx4 v160, s[80:81]
	v_lshl_add_u64 v[226:227], s[54:55], 0, v[166:167]
	s_mov_b32 m0, s60
	s_nop 0
	global_load_lds_dwordx4 v[226:227], off
	s_mov_b32 m0, s61
	s_nop 0
	global_load_lds_dwordx4 v[228:229], off
	s_waitcnt vmcnt(8)
	s_waitcnt lgkmcnt(0)
	s_barrier
; #define PG8_STAGE(bufoff, gbase, voff) do { _Pragma("unroll") for (int _i = 0; _i < 2; ++_i) \
;         __builtin_amdgcn_global_load_lds((const unsigned*)((const char*)(gbase) + (voff)[_i]), (PG8_LAS unsigned*)(lds + (bufoff) + ldsw + _i * 8192), 16, 0, 0); } while (0)
; #define PG8_LDA(dst, b, h) do { _Pragma("unroll") for (int m = 0; m < 4; ++m) _Pragma("unroll") for (int k = 0; k < 2; ++k) dst[m][k] = *(const PG8_LAS bf16x8*)(lds + PG8_SA(b, h) + aoff + m * 2048 + k * 1024); } while (0)
; #define PG8_LDB(dst, b, h) do { _Pragma("unroll") for (int n = 0; n < 2; ++n) _Pragma("unroll") for (int k = 0; k < 2; ++k) dst[n][k] = *(const PG8_LAS bf16x8*)(lds + PG8_SB(b, h) + boff + n * 2048 + k * 1024); } while (0)
; #define PG8_MMA(ai, bj, At, Bt) do { __builtin_amdgcn_s_setprio(1); _Pragma("unroll") for (int m = 0; m < 4; ++m) _Pragma("unroll") for (int n = 0; n < 2; ++n) _Pragma("unroll") for (int k = 0; k < 2; ++k) \
;         acc[ai][bj][m][n] = __builtin_amdgcn_mfma_f32_16x16x32_bf16(Bt[n][k], At[m][k], acc[ai][bj][m][n], 0, 0, 0); __builtin_amdgcn_s_setprio(0); } while (0)
; #define PG8_WAIT_V(n) asm volatile("s_waitcnt vmcnt(" #n ")" ::: "memory")
; #define PG8_WAIT_L(n) asm volatile("s_waitcnt lgkmcnt(" #n ")" ::: "memory")
; #define PG8_BAR __builtin_amdgcn_s_barrier()
; #define PG8_SCHED __builtin_amdgcn_sched_barrier(0)
; template <class Epi, class Sched, bool ALIGN_EPI = false, bool SP2 = false>
; __device__ __forceinline__ void gemm_phase(PG8_LAS unsigned char* lds, const Gemm g, const Sched& S, const Epi& E) {
;     ...
;             PG8_WAIT_V(8); PG8_WAIT_L(0); PG8_BAR; PG8_MMA(1, 0, At, B0); PG8_MMA(1, 1, At, B1); PG8_BAR; PG8_SCHED;
;             PG8_LDB(B0, 1, 0); PG8_LDB(B1, 1, 1); PG8_SCHED; PG8_LDA(At, 1, 0); PG8_STAGE(PG8_SA(0, 1), a2 + hstep, voffA);
;             PG8_WAIT_V(8); PG8_WAIT_L(0); PG8_BAR; PG8_MMA(0, 0, At, B0); PG8_MMA(0, 1, At, B1); PG8_BAR; PG8_SCHED;
	s_setprio 1
	s_waitcnt lgkmcnt(0)
	v_mfma_f32_16x16x32_bf16 v[60:63], v[128:131], v[176:179], v[60:63]
	v_mfma_f32_16x16x32_bf16 v[56:59], v[136:139], v[176:179], v[56:59]
	v_mfma_f32_16x16x32_bf16 v[52:55], v[128:131], v[184:187], v[52:55]
	v_mfma_f32_16x16x32_bf16 v[40:43], v[136:139], v[184:187], v[40:43]
	v_mfma_f32_16x16x32_bf16 v[36:39], v[128:131], v[210:213], v[36:39]
	v_mfma_f32_16x16x32_bf16 v[24:27], v[136:139], v[210:213], v[24:27]
	v_mfma_f32_16x16x32_bf16 v[20:23], v[128:131], v[218:221], v[20:23]
	v_mfma_f32_16x16x32_bf16 v[8:11], v[136:139], v[218:221], v[8:11]
	v_mfma_f32_16x16x32_bf16 v[60:63], v[132:135], v[180:183], v[60:63]
	v_mfma_f32_16x16x32_bf16 v[56:59], v[140:143], v[180:183], v[56:59]
	v_mfma_f32_16x16x32_bf16 v[52:55], v[132:135], v[192:195], v[52:55]
	v_mfma_f32_16x16x32_bf16 v[40:43], v[140:143], v[192:195], v[40:43]
	v_mfma_f32_16x16x32_bf16 v[36:39], v[132:135], v[214:217], v[36:39]
	v_mfma_f32_16x16x32_bf16 v[24:27], v[140:143], v[214:217], v[24:27]
	v_mfma_f32_16x16x32_bf16 v[20:23], v[132:135], v[222:225], v[20:23]
	v_mfma_f32_16x16x32_bf16 v[8:11], v[140:143], v[222:225], v[8:11]
	s_setprio 0
	s_setprio 1
	v_mfma_f32_16x16x32_bf16 v[48:51], v[144:147], v[176:179], v[48:51]
	v_mfma_f32_16x16x32_bf16 v[44:47], v[152:155], v[176:179], v[44:47]
	v_mfma_f32_16x16x32_bf16 v[32:35], v[144:147], v[184:187], v[32:35]
	v_mfma_f32_16x16x32_bf16 v[28:31], v[152:155], v[184:187], v[28:31]
	v_mfma_f32_16x16x32_bf16 v[16:19], v[144:147], v[210:213], v[16:19]
	v_mfma_f32_16x16x32_bf16 v[12:15], v[152:155], v[210:213], v[12:15]
	v_mfma_f32_16x16x32_bf16 v[4:7], v[144:147], v[218:221], v[4:7]
	v_mfma_f32_16x16x32_bf16 v[0:3], v[152:155], v[218:221], v[0:3]
	v_mfma_f32_16x16x32_bf16 v[48:51], v[148:151], v[180:183], v[48:51]
	v_mfma_f32_16x16x32_bf16 v[44:47], v[156:159], v[180:183], v[44:47]
	v_mfma_f32_16x16x32_bf16 v[32:35], v[148:151], v[192:195], v[32:35]
	v_mfma_f32_16x16x32_bf16 v[28:31], v[156:159], v[192:195], v[28:31]
	v_mfma_f32_16x16x32_bf16 v[16:19], v[148:151], v[214:217], v[16:19]
	v_mfma_f32_16x16x32_bf16 v[12:15], v[156:159], v[214:217], v[12:15]
	v_mfma_f32_16x16x32_bf16 v[4:7], v[148:151], v[222:225], v[4:7]
	v_mfma_f32_16x16x32_bf16 v[0:3], v[156:159], v[222:225], v[0:3]
	s_setprio 0
	s_barrier
	s_add_i32 s79, 0, 0x18000
	s_add_i32 s80, 0, 0x1c000
	v_add_u32_e32 v140, s79, v197
	v_add_u32_e32 v156, s80, v197
	ds_read_b128 v[128:131], v140
	ds_read_b128 v[132:135], v140 offset:1024
	ds_read_b128 v[136:139], v140 offset:2048
	ds_read_b128 v[140:143], v140 offset:3072
	ds_read_b128 v[144:147], v156
	ds_read_b128 v[148:151], v156 offset:1024
	ds_read_b128 v[152:155], v156 offset:2048
	ds_read_b128 v[156:159], v156 offset:3072
	s_add_u32 s54, s54, 0x80000
	s_addc_u32 s55, s55, 0
	s_mov_b32 m0, s62
	s_nop 0
	ds_read_b128 v[176:179], v207 offset:32768
	ds_read_b128 v[180:183], v207 offset:33792
	ds_read_b128 v[184:187], v207 offset:34816
	ds_read_b128 v[192:195], v207 offset:35840
	ds_read_b128 v[210:213], v207 offset:36864
	ds_read_b128 v[214:217], v207 offset:37888
	ds_read_b128 v[218:221], v207 offset:38912
	ds_read_b128 v[222:225], v207 offset:39936
	global_load_lds_dwordx4 v166, s[54:55]
	s_nop 0
	s_mov_b32 m0, s63
	s_nop 0
	global_load_lds_dwordx4 v162, s[54:55]
	s_waitcnt vmcnt(8)
	s_waitcnt lgkmcnt(0)
	s_barrier
	s_setprio 1
	s_waitcnt lgkmcnt(0)
	v_mfma_f32_16x16x32_bf16 v[124:127], v[128:131], v[176:179], v[124:127]
	v_mfma_f32_16x16x32_bf16 v[120:123], v[136:139], v[176:179], v[120:123]
	v_mfma_f32_16x16x32_bf16 v[112:115], v[128:131], v[184:187], v[112:115]
	v_mfma_f32_16x16x32_bf16 v[104:107], v[136:139], v[184:187], v[104:107]
	v_mfma_f32_16x16x32_bf16 v[100:103], v[128:131], v[210:213], v[100:103]
	v_mfma_f32_16x16x32_bf16 v[88:91], v[136:139], v[210:213], v[88:91]
	v_mfma_f32_16x16x32_bf16 v[84:87], v[128:131], v[218:221], v[84:87]
	v_mfma_f32_16x16x32_bf16 v[72:75], v[136:139], v[218:221], v[72:75]
	v_mfma_f32_16x16x32_bf16 v[124:127], v[132:135], v[180:183], v[124:127]
	v_mfma_f32_16x16x32_bf16 v[120:123], v[140:143], v[180:183], v[120:123]
	v_mfma_f32_16x16x32_bf16 v[112:115], v[132:135], v[192:195], v[112:115]
	v_mfma_f32_16x16x32_bf16 v[104:107], v[140:143], v[192:195], v[104:107]
	v_mfma_f32_16x16x32_bf16 v[100:103], v[132:135], v[214:217], v[100:103]
	v_mfma_f32_16x16x32_bf16 v[88:91], v[140:143], v[214:217], v[88:91]
	v_mfma_f32_16x16x32_bf16 v[84:87], v[132:135], v[222:225], v[84:87]
	v_mfma_f32_16x16x32_bf16 v[72:75], v[140:143], v[222:225], v[72:75]
	s_setprio 0
	s_setprio 1
	v_mfma_f32_16x16x32_bf16 v[116:119], v[144:147], v[176:179], v[116:119]
	v_mfma_f32_16x16x32_bf16 v[108:111], v[152:155], v[176:179], v[108:111]
	v_mfma_f32_16x16x32_bf16 v[96:99], v[144:147], v[184:187], v[96:99]
	v_mfma_f32_16x16x32_bf16 v[92:95], v[152:155], v[184:187], v[92:95]
	v_mfma_f32_16x16x32_bf16 v[80:83], v[144:147], v[210:213], v[80:83]
	v_mfma_f32_16x16x32_bf16 v[76:79], v[152:155], v[210:213], v[76:79]
	v_mfma_f32_16x16x32_bf16 v[68:71], v[144:147], v[218:221], v[68:71]
	v_mfma_f32_16x16x32_bf16 v[64:67], v[152:155], v[218:221], v[64:67]
	v_mfma_f32_16x16x32_bf16 v[116:119], v[148:151], v[180:183], v[116:119]
	v_mfma_f32_16x16x32_bf16 v[108:111], v[156:159], v[180:183], v[108:111]
	v_mfma_f32_16x16x32_bf16 v[96:99], v[148:151], v[192:195], v[96:99]
	v_mfma_f32_16x16x32_bf16 v[92:95], v[156:159], v[192:195], v[92:95]
	v_mfma_f32_16x16x32_bf16 v[80:83], v[148:151], v[214:217], v[80:83]
	v_mfma_f32_16x16x32_bf16 v[76:79], v[156:159], v[214:217], v[76:79]
	v_mfma_f32_16x16x32_bf16 v[68:71], v[148:151], v[222:225], v[68:71]
	v_mfma_f32_16x16x32_bf16 v[64:67], v[156:159], v[222:225], v[64:67]
	s_setprio 0
	s_barrier
; #define PG8_STAGE(bufoff, gbase, voff) do { _Pragma("unroll") for (int _i = 0; _i < 2; ++_i) \
;         __builtin_amdgcn_global_load_lds((const unsigned*)((const char*)(gbase) + (voff)[_i]), (PG8_LAS unsigned*)(lds + (bufoff) + ldsw + _i * 8192), 16, 0, 0); } while (0)
; #define PG8_LDA(dst, b, h) do { _Pragma("unroll") for (int m = 0; m < 4; ++m) _Pragma("unroll") for (int k = 0; k < 2; ++k) dst[m][k] = *(const PG8_LAS bf16x8*)(lds + PG8_SA(b, h) + aoff + m * 2048 + k * 1024); } while (0)
; #define PG8_MMA(ai, bj, At, Bt) do { __builtin_amdgcn_s_setprio(1); _Pragma("unroll") for (int m = 0; m < 4; ++m) _Pragma("unroll") for (int n = 0; n < 2; ++n) _Pragma("unroll") for (int k = 0; k < 2; ++k) \
;         acc[ai][bj][m][n] = __builtin_amdgcn_mfma_f32_16x16x32_bf16(Bt[n][k], At[m][k], acc[ai][bj][m][n], 0, 0, 0); __builtin_amdgcn_s_setprio(0); } while (0)
; #define PG8_WAIT_V(n) asm volatile("s_waitcnt vmcnt(" #n ")" ::: "memory")
; #define PG8_WAIT_L(n) asm volatile("s_waitcnt lgkmcnt(" #n ")" ::: "memory")
; #define PG8_BAR __builtin_amdgcn_s_barrier()
; #define PG8_SCHED __builtin_amdgcn_sched_barrier(0)
; template <class Epi, class Sched, bool ALIGN_EPI = false, bool SP2 = false>
; __device__ __forceinline__ void gemm_phase(PG8_LAS unsigned char* lds, const Gemm g, const Sched& S, const Epi& E) {
;     ...
;             PG8_LDA(At, 1, 1); PG8_STAGE(PG8_SB(1, 0), b3, voffB); PG8_STAGE(PG8_SB(1, 1), b3 + hstep, voffB); PG8_STAGE(PG8_SA(1, 0), a3, voffA);
;             PG8_WAIT_V(8); PG8_WAIT_L(0); PG8_BAR; PG8_MMA(1, 0, At, B0); PG8_MMA(1, 1, At, B1); PG8_BAR; PG8_SCHED;
;     ...
;         if constexpr (ALIGN_EPI) { if (wr == 0) PG8_BAR; }
	s_add_i32 s54, s79, s57
	v_lshl_add_u64 v[188:189], v[188:189], 0, s[40:41]
	s_mov_b32 m0, s54
	ds_read_b128 v[176:179], v207 offset:49152
	ds_read_b128 v[180:183], v207 offset:50176
	ds_read_b128 v[184:187], v207 offset:51200
	ds_read_b128 v[192:195], v207 offset:52224
	ds_read_b128 v[210:213], v207 offset:53248
	ds_read_b128 v[214:217], v207 offset:54272
	ds_read_b128 v[218:221], v207 offset:55296
	ds_read_b128 v[222:225], v207 offset:56320
	global_load_lds_dwordx4 v[188:189], off
	s_add_i32 m0, s54, 0x2000
	s_add_u32 s12, s12, 0x80080
	v_lshl_add_u64 v[188:189], v[198:199], 0, s[40:41]
	s_addc_u32 s13, s13, 0
	s_add_i32 s54, s80, s57
	global_load_lds_dwordx4 v[188:189], off
	s_nop 0
	s_mov_b32 m0, s54
	s_nop 0
	global_load_lds_dwordx4 v164, s[12:13]
	s_nop 0
	s_add_i32 m0, s54, 0x2000
	s_nop 0
	global_load_lds_dwordx4 v160, s[12:13]
	v_lshl_add_u64 v[188:189], v[226:227], 0, s[40:41]
	s_mov_b32 m0, s65
	s_nop 0
	global_load_lds_dwordx4 v[188:189], off
	v_lshl_add_u64 v[188:189], v[228:229], 0, s[40:41]
	s_mov_b32 m0, s67
	s_nop 0
	global_load_lds_dwordx4 v[188:189], off
	s_waitcnt vmcnt(8)
	s_waitcnt lgkmcnt(0)
	s_barrier
	s_setprio 1
	s_waitcnt lgkmcnt(0)
	v_mfma_f32_16x16x32_bf16 v[60:63], v[128:131], v[176:179], v[60:63]
	v_mfma_f32_16x16x32_bf16 v[56:59], v[136:139], v[176:179], v[56:59]
	v_mfma_f32_16x16x32_bf16 v[52:55], v[128:131], v[184:187], v[52:55]
	v_mfma_f32_16x16x32_bf16 v[40:43], v[136:139], v[184:187], v[40:43]
	v_mfma_f32_16x16x32_bf16 v[36:39], v[128:131], v[210:213], v[36:39]
	v_mfma_f32_16x16x32_bf16 v[24:27], v[136:139], v[210:213], v[24:27]
	v_mfma_f32_16x16x32_bf16 v[20:23], v[128:131], v[218:221], v[20:23]
	v_mfma_f32_16x16x32_bf16 v[8:11], v[136:139], v[218:221], v[8:11]
	v_mfma_f32_16x16x32_bf16 v[60:63], v[132:135], v[180:183], v[60:63]
	v_mfma_f32_16x16x32_bf16 v[56:59], v[140:143], v[180:183], v[56:59]
	v_mfma_f32_16x16x32_bf16 v[52:55], v[132:135], v[192:195], v[52:55]
	v_mfma_f32_16x16x32_bf16 v[40:43], v[140:143], v[192:195], v[40:43]
	v_mfma_f32_16x16x32_bf16 v[36:39], v[132:135], v[214:217], v[36:39]
	v_mfma_f32_16x16x32_bf16 v[24:27], v[140:143], v[214:217], v[24:27]
	v_mfma_f32_16x16x32_bf16 v[20:23], v[132:135], v[222:225], v[20:23]
	v_mfma_f32_16x16x32_bf16 v[8:11], v[140:143], v[222:225], v[8:11]
	s_setprio 0
	s_setprio 1
	v_mfma_f32_16x16x32_bf16 v[48:51], v[144:147], v[176:179], v[48:51]
	v_mfma_f32_16x16x32_bf16 v[44:47], v[152:155], v[176:179], v[44:47]
	v_mfma_f32_16x16x32_bf16 v[32:35], v[144:147], v[184:187], v[32:35]
	v_mfma_f32_16x16x32_bf16 v[28:31], v[152:155], v[184:187], v[28:31]
	v_mfma_f32_16x16x32_bf16 v[16:19], v[144:147], v[210:213], v[16:19]
	v_mfma_f32_16x16x32_bf16 v[12:15], v[152:155], v[210:213], v[12:15]
	v_mfma_f32_16x16x32_bf16 v[4:7], v[144:147], v[218:221], v[4:7]
	v_mfma_f32_16x16x32_bf16 v[0:3], v[152:155], v[218:221], v[0:3]
	v_mfma_f32_16x16x32_bf16 v[48:51], v[148:151], v[180:183], v[48:51]
	v_mfma_f32_16x16x32_bf16 v[44:47], v[156:159], v[180:183], v[44:47]
	v_mfma_f32_16x16x32_bf16 v[32:35], v[148:151], v[192:195], v[32:35]
	v_mfma_f32_16x16x32_bf16 v[28:31], v[156:159], v[192:195], v[28:31]
	v_mfma_f32_16x16x32_bf16 v[16:19], v[148:151], v[214:217], v[16:19]
	v_mfma_f32_16x16x32_bf16 v[12:15], v[156:159], v[214:217], v[12:15]
	v_mfma_f32_16x16x32_bf16 v[4:7], v[148:151], v[222:225], v[4:7]
	v_mfma_f32_16x16x32_bf16 v[0:3], v[156:159], v[222:225], v[0:3]
	s_setprio 0
	s_barrier
	s_add_i32 s78, s78, 2
	s_add_u32 s10, s10, 0x100
	s_addc_u32 s11, s11, 0
	s_add_u32 s76, s76, 0x100
	s_addc_u32 s77, s77, 0
	s_cmp_gt_u32 s78, 29
	s_cbranch_scc0 .LBB0_679
	s_and_b64 vcc, exec, s[42:43]
	s_cbranch_vccz .LBB0_682
	s_barrier

; #define PG8_STAGE(bufoff, gbase, voff) do { _Pragma("unroll") for (int _i = 0; _i < 2; ++_i) \
;         __builtin_amdgcn_global_load_lds((const unsigned*)((const char*)(gbase) + (voff)[_i]), (PG8_LAS unsigned*)(lds + (bufoff) + ldsw + _i * 8192), 16, 0, 0); } while (0)
; #define PG8_LDA(dst, b, h) do { _Pragma("unroll") for (int m = 0; m < 4; ++m) _Pragma("unroll") for (int k = 0; k < 2; ++k) dst[m][k] = *(const PG8_LAS bf16x8*)(lds + PG8_SA(b, h) + aoff + m * 2048 + k * 1024); } while (0)
; #define PG8_LDB(dst, b, h) do { _Pragma("unroll") for (int n = 0; n < 2; ++n) _Pragma("unroll") for (int k = 0; k < 2; ++k) dst[n][k] = *(const PG8_LAS bf16x8*)(lds + PG8_SB(b, h) + boff + n * 2048 + k * 1024); } while (0)
; #define PG8_MMA(ai, bj, At, Bt) do { __builtin_amdgcn_s_setprio(1); _Pragma("unroll") for (int m = 0; m < 4; ++m) _Pragma("unroll") for (int n = 0; n < 2; ++n) _Pragma("unroll") for (int k = 0; k < 2; ++k) \
;         acc[ai][bj][m][n] = __builtin_amdgcn_mfma_f32_16x16x32_bf16(Bt[n][k], At[m][k], acc[ai][bj][m][n], 0, 0, 0); __builtin_amdgcn_s_setprio(0); } while (0)
; #define PG8_WAIT_V(n) asm volatile("s_waitcnt vmcnt(" #n ")" ::: "memory")
; #define PG8_BAR __builtin_amdgcn_s_barrier()
; template <class Epi, class Sched, bool ALIGN_EPI = false, bool SP2 = false>
; __device__ __forceinline__ void gemm_phase(PG8_LAS unsigned char* lds, const Gemm g, const Sched& S, const Epi& E) {
;     ...
;         for (int t = 0; t < nt; t += 2) {
;             const bool last = (t == nt - 2);
;             const char* a1 = cA + (size_t)(t + 1) * kstep;
;             const char* a2 = last ? nA : cA + (size_t)(t + 2) * kstep; const char* b2 = last ? nB : cB + (size_t)(t + 2) * kstep;
;             const char* a3 = a2 + kstep; const char* b3 = b2 + kstep;
;             if (last && has_next) S.a_ready(nxt);
;             if constexpr (SP2) {
;             PG8_LDB(B0, 0, 0); PG8_LDB(B1, 0, 1); PG8_SCHED; PG8_LDA(At, 0, 0); PG8_STAGE(PG8_SA(1, 1), a1 + hstep, voffA);
;             PG8_WAIT_V(8); PG8_WAIT_L(0); PG8_BAR; PG8_MMA(0, 0, At, B0); PG8_MMA(0, 1, At, B1); PG8_BAR; PG8_SCHED;
;             PG8_LDA(At, 0, 1); PG8_STAGE(PG8_SB(0, 0), b2, voffB); PG8_STAGE(PG8_SB(0, 1), b2 + hstep, voffB); PG8_STAGE(PG8_SA(0, 0), a2, voffA);
;             PG8_WAIT_V(8); PG8_WAIT_L(0); PG8_BAR; PG8_MMA(1, 0, At, B0); PG8_MMA(1, 1, At, B1); PG8_BAR; PG8_SCHED;
.LBB0_939:
	ds_read_b128 v[64:67], v213
	ds_read_b128 v[68:71], v213 offset:1024
	ds_read_b128 v[72:75], v213 offset:2048
	ds_read_b128 v[76:79], v213 offset:3072
	ds_read_b128 v[144:147], v214
	ds_read_b128 v[148:151], v214 offset:1024
	ds_read_b128 v[152:155], v214 offset:2048
	ds_read_b128 v[156:159], v214 offset:3072
	s_add_u32 s60, s58, 0xfff80080
	s_addc_u32 s61, s59, -1
	s_cmp_eq_u32 s81, 28
	s_cselect_b32 s63, s11, s61
	s_cselect_b32 s62, s51, s60
	s_cselect_b32 s61, s49, s80
	s_cselect_b32 s60, s78, s79
	s_nop 0
	s_add_i32 m0, s57, 0xc000
	ds_read_b128 v[176:179], v215
	ds_read_b128 v[180:183], v215 offset:1024
	ds_read_b128 v[184:187], v215 offset:2048
	ds_read_b128 v[188:191], v215 offset:3072
	ds_read_b128 v[192:195], v215 offset:4096
	ds_read_b128 v[196:199], v215 offset:5120
	ds_read_b128 v[200:203], v215 offset:6144
	ds_read_b128 v[204:207], v215 offset:7168
	global_load_lds_dwordx4 v168, s[58:59]
	s_nop 0
	s_add_i32 m0, s57, 0xe000
	s_nop 0
	global_load_lds_dwordx4 v170, s[58:59]
	s_waitcnt vmcnt(8)
	s_waitcnt lgkmcnt(0)
	s_barrier
	s_setprio 1
	s_waitcnt lgkmcnt(0)
	v_mfma_f32_16x16x32_bf16 v[140:143], v[64:67], v[176:179], v[140:143]
	v_mfma_f32_16x16x32_bf16 v[136:139], v[72:75], v[176:179], v[136:139]
	v_mfma_f32_16x16x32_bf16 v[124:127], v[64:67], v[184:187], v[124:127]
	v_mfma_f32_16x16x32_bf16 v[120:123], v[72:75], v[184:187], v[120:123]
	v_mfma_f32_16x16x32_bf16 v[108:111], v[64:67], v[192:195], v[108:111]
	v_mfma_f32_16x16x32_bf16 v[104:107], v[72:75], v[192:195], v[104:107]
	v_mfma_f32_16x16x32_bf16 v[92:95], v[64:67], v[200:203], v[92:95]
	v_mfma_f32_16x16x32_bf16 v[88:91], v[72:75], v[200:203], v[88:91]
	v_mfma_f32_16x16x32_bf16 v[140:143], v[68:71], v[180:183], v[140:143]
	v_mfma_f32_16x16x32_bf16 v[136:139], v[76:79], v[180:183], v[136:139]
	v_mfma_f32_16x16x32_bf16 v[124:127], v[68:71], v[188:191], v[124:127]
	v_mfma_f32_16x16x32_bf16 v[120:123], v[76:79], v[188:191], v[120:123]
	v_mfma_f32_16x16x32_bf16 v[108:111], v[68:71], v[196:199], v[108:111]
	v_mfma_f32_16x16x32_bf16 v[104:107], v[76:79], v[196:199], v[104:107]
	v_mfma_f32_16x16x32_bf16 v[92:95], v[68:71], v[204:207], v[92:95]
	v_mfma_f32_16x16x32_bf16 v[88:91], v[76:79], v[204:207], v[88:91]
	s_setprio 0
	s_setprio 1
	v_mfma_f32_16x16x32_bf16 v[132:135], v[144:147], v[176:179], v[132:135]
	v_mfma_f32_16x16x32_bf16 v[128:131], v[152:155], v[176:179], v[128:131]
	v_mfma_f32_16x16x32_bf16 v[116:119], v[144:147], v[184:187], v[116:119]
	v_mfma_f32_16x16x32_bf16 v[112:115], v[152:155], v[184:187], v[112:115]
	v_mfma_f32_16x16x32_bf16 v[100:103], v[144:147], v[192:195], v[100:103]
	v_mfma_f32_16x16x32_bf16 v[96:99], v[152:155], v[192:195], v[96:99]
	v_mfma_f32_16x16x32_bf16 v[84:87], v[144:147], v[200:203], v[84:87]
	v_mfma_f32_16x16x32_bf16 v[80:83], v[152:155], v[200:203], v[80:83]
	v_mfma_f32_16x16x32_bf16 v[132:135], v[148:151], v[180:183], v[132:135]
	v_mfma_f32_16x16x32_bf16 v[128:131], v[156:159], v[180:183], v[128:131]
	v_mfma_f32_16x16x32_bf16 v[116:119], v[148:151], v[188:191], v[116:119]
	v_mfma_f32_16x16x32_bf16 v[112:115], v[156:159], v[188:191], v[112:115]
	v_mfma_f32_16x16x32_bf16 v[100:103], v[148:151], v[196:199], v[100:103]
	v_mfma_f32_16x16x32_bf16 v[96:99], v[156:159], v[196:199], v[96:99]
	v_mfma_f32_16x16x32_bf16 v[84:87], v[148:151], v[204:207], v[84:87]
	v_mfma_f32_16x16x32_bf16 v[80:83], v[156:159], v[204:207], v[80:83]
	s_setprio 0
	s_barrier
	s_add_i32 s82, s75, s64
	v_lshl_add_u64 v[208:209], s[60:61], 0, v[162:163]
	s_mov_b32 m0, s82
	ds_read_b128 v[176:179], v215 offset:16384
	ds_read_b128 v[180:183], v215 offset:17408
	ds_read_b128 v[184:187], v215 offset:18432
	ds_read_b128 v[188:191], v215 offset:19456
	ds_read_b128 v[192:195], v215 offset:20480
	ds_read_b128 v[196:199], v215 offset:21504
	ds_read_b128 v[200:203], v215 offset:22528
	ds_read_b128 v[204:207], v215 offset:23552
	global_load_lds_dwordx4 v[208:209], off
	s_add_i32 m0, s82, 0x2000
	s_add_u32 s82, s60, 0x80000
	v_lshl_add_u64 v[218:219], s[60:61], 0, v[166:167]
	s_addc_u32 s83, s61, 0
	s_add_i32 s84, s76, s64
	global_load_lds_dwordx4 v[218:219], off
	s_nop 0
	s_mov_b32 m0, s84
	v_lshl_add_u64 v[222:223], s[62:63], 0, v[164:165]
	global_load_lds_dwordx4 v162, s[82:83]
	s_nop 0
	s_add_i32 m0, s84, 0x2000
	s_nop 0
	global_load_lds_dwordx4 v166, s[82:83]
	v_lshl_add_u64 v[220:221], s[62:63], 0, v[160:161]
	s_mov_b32 m0, s57
	s_nop 0
	global_load_lds_dwordx4 v[220:221], off
	s_mov_b32 m0, s65
	s_nop 0
	global_load_lds_dwordx4 v[222:223], off
	s_waitcnt vmcnt(8)
	s_waitcnt lgkmcnt(0)
	s_barrier
; #define PG8_STAGE(bufoff, gbase, voff) do { _Pragma("unroll") for (int _i = 0; _i < 2; ++_i) \
;         __builtin_amdgcn_global_load_lds((const unsigned*)((const char*)(gbase) + (voff)[_i]), (PG8_LAS unsigned*)(lds + (bufoff) + ldsw + _i * 8192), 16, 0, 0); } while (0)
; #define PG8_LDA(dst, b, h) do { _Pragma("unroll") for (int m = 0; m < 4; ++m) _Pragma("unroll") for (int k = 0; k < 2; ++k) dst[m][k] = *(const PG8_LAS bf16x8*)(lds + PG8_SA(b, h) + aoff + m * 2048 + k * 1024); } while (0)
; #define PG8_LDB(dst, b, h) do { _Pragma("unroll") for (int n = 0; n < 2; ++n) _Pragma("unroll") for (int k = 0; k < 2; ++k) dst[n][k] = *(const PG8_LAS bf16x8*)(lds + PG8_SB(b, h) + boff + n * 2048 + k * 1024); } while (0)
; #define PG8_MMA(ai, bj, At, Bt) do { __builtin_amdgcn_s_setprio(1); _Pragma("unroll") for (int m = 0; m < 4; ++m) _Pragma("unroll") for (int n = 0; n < 2; ++n) _Pragma("unroll") for (int k = 0; k < 2; ++k) \
;         acc[ai][bj][m][n] = __builtin_amdgcn_mfma_f32_16x16x32_bf16(Bt[n][k], At[m][k], acc[ai][bj][m][n], 0, 0, 0); __builtin_amdgcn_s_setprio(0); } while (0)
; #define PG8_WAIT_V(n) asm volatile("s_waitcnt vmcnt(" #n ")" ::: "memory")
; #define PG8_WAIT_L(n) asm volatile("s_waitcnt lgkmcnt(" #n ")" ::: "memory")
; #define PG8_BAR __builtin_amdgcn_s_barrier()
; #define PG8_SCHED __builtin_amdgcn_sched_barrier(0)
; template <class Epi, class Sched, bool ALIGN_EPI = false, bool SP2 = false>
; __device__ __forceinline__ void gemm_phase(PG8_LAS unsigned char* lds, const Gemm g, const Sched& S, const Epi& E) {
;     ...
;             PG8_WAIT_V(8); PG8_WAIT_L(0); PG8_BAR; PG8_MMA(1, 0, At, B0); PG8_MMA(1, 1, At, B1); PG8_BAR; PG8_SCHED;
;             PG8_LDB(B0, 1, 0); PG8_LDB(B1, 1, 1); PG8_SCHED; PG8_LDA(At, 1, 0); PG8_STAGE(PG8_SA(0, 1), a2 + hstep, voffA);
;             PG8_WAIT_V(8); PG8_WAIT_L(0); PG8_BAR; PG8_MMA(0, 0, At, B0); PG8_MMA(0, 1, At, B1); PG8_BAR; PG8_SCHED;
	s_setprio 1
	s_waitcnt lgkmcnt(0)
	v_mfma_f32_16x16x32_bf16 v[60:63], v[64:67], v[176:179], v[60:63]
	v_mfma_f32_16x16x32_bf16 v[56:59], v[72:75], v[176:179], v[56:59]
	v_mfma_f32_16x16x32_bf16 v[44:47], v[64:67], v[184:187], v[44:47]
	v_mfma_f32_16x16x32_bf16 v[40:43], v[72:75], v[184:187], v[40:43]
	v_mfma_f32_16x16x32_bf16 v[28:31], v[64:67], v[192:195], v[28:31]
	v_mfma_f32_16x16x32_bf16 v[24:27], v[72:75], v[192:195], v[24:27]
	v_mfma_f32_16x16x32_bf16 v[12:15], v[64:67], v[200:203], v[12:15]
	v_mfma_f32_16x16x32_bf16 v[8:11], v[72:75], v[200:203], v[8:11]
	v_mfma_f32_16x16x32_bf16 v[60:63], v[68:71], v[180:183], v[60:63]
	v_mfma_f32_16x16x32_bf16 v[56:59], v[76:79], v[180:183], v[56:59]
	v_mfma_f32_16x16x32_bf16 v[44:47], v[68:71], v[188:191], v[44:47]
	v_mfma_f32_16x16x32_bf16 v[40:43], v[76:79], v[188:191], v[40:43]
	v_mfma_f32_16x16x32_bf16 v[28:31], v[68:71], v[196:199], v[28:31]
	v_mfma_f32_16x16x32_bf16 v[24:27], v[76:79], v[196:199], v[24:27]
	v_mfma_f32_16x16x32_bf16 v[12:15], v[68:71], v[204:207], v[12:15]
	v_mfma_f32_16x16x32_bf16 v[8:11], v[76:79], v[204:207], v[8:11]
	s_setprio 0
	s_setprio 1
	v_mfma_f32_16x16x32_bf16 v[52:55], v[144:147], v[176:179], v[52:55]
	v_mfma_f32_16x16x32_bf16 v[48:51], v[152:155], v[176:179], v[48:51]
	v_mfma_f32_16x16x32_bf16 v[36:39], v[144:147], v[184:187], v[36:39]
	v_mfma_f32_16x16x32_bf16 v[32:35], v[152:155], v[184:187], v[32:35]
	v_mfma_f32_16x16x32_bf16 v[20:23], v[144:147], v[192:195], v[20:23]
	v_mfma_f32_16x16x32_bf16 v[16:19], v[152:155], v[192:195], v[16:19]
	v_mfma_f32_16x16x32_bf16 v[4:7], v[144:147], v[200:203], v[4:7]
	v_mfma_f32_16x16x32_bf16 v[0:3], v[152:155], v[200:203], v[0:3]
	v_mfma_f32_16x16x32_bf16 v[52:55], v[148:151], v[180:183], v[52:55]
	v_mfma_f32_16x16x32_bf16 v[48:51], v[156:159], v[180:183], v[48:51]
	v_mfma_f32_16x16x32_bf16 v[36:39], v[148:151], v[188:191], v[36:39]
	v_mfma_f32_16x16x32_bf16 v[32:35], v[156:159], v[188:191], v[32:35]
	v_mfma_f32_16x16x32_bf16 v[20:23], v[148:151], v[196:199], v[20:23]
	v_mfma_f32_16x16x32_bf16 v[16:19], v[156:159], v[196:199], v[16:19]
	v_mfma_f32_16x16x32_bf16 v[4:7], v[148:151], v[204:207], v[4:7]
	v_mfma_f32_16x16x32_bf16 v[0:3], v[156:159], v[204:207], v[0:3]
	s_setprio 0
	s_barrier
	s_add_i32 s82, 0, 0x18000
	s_add_i32 s83, 0, 0x1c000
	v_add_u32_e32 v76, s82, v211
	v_add_u32_e32 v156, s83, v211
	ds_read_b128 v[64:67], v76
	ds_read_b128 v[68:71], v76 offset:1024
	ds_read_b128 v[72:75], v76 offset:2048
	ds_read_b128 v[76:79], v76 offset:3072
	ds_read_b128 v[144:147], v156
	ds_read_b128 v[148:151], v156 offset:1024
	ds_read_b128 v[152:155], v156 offset:2048
	ds_read_b128 v[156:159], v156 offset:3072
	s_add_u32 s62, s62, 0x80000
	s_addc_u32 s63, s63, 0
	s_mov_b32 m0, s67
	s_nop 0
	ds_read_b128 v[176:179], v215 offset:32768
	ds_read_b128 v[180:183], v215 offset:33792
	ds_read_b128 v[184:187], v215 offset:34816
	ds_read_b128 v[188:191], v215 offset:35840
	ds_read_b128 v[192:195], v215 offset:36864
	ds_read_b128 v[196:199], v215 offset:37888
	ds_read_b128 v[200:203], v215 offset:38912
	ds_read_b128 v[204:207], v215 offset:39936
	global_load_lds_dwordx4 v160, s[62:63]
	s_nop 0
	s_mov_b32 m0, s68
	s_nop 0
	global_load_lds_dwordx4 v164, s[62:63]
	s_waitcnt vmcnt(8)
	s_waitcnt lgkmcnt(0)
	s_barrier
	s_setprio 1
	s_waitcnt lgkmcnt(0)
	v_mfma_f32_16x16x32_bf16 v[140:143], v[64:67], v[176:179], v[140:143]
	v_mfma_f32_16x16x32_bf16 v[136:139], v[72:75], v[176:179], v[136:139]
	v_mfma_f32_16x16x32_bf16 v[124:127], v[64:67], v[184:187], v[124:127]
	v_mfma_f32_16x16x32_bf16 v[120:123], v[72:75], v[184:187], v[120:123]
	v_mfma_f32_16x16x32_bf16 v[108:111], v[64:67], v[192:195], v[108:111]
	v_mfma_f32_16x16x32_bf16 v[104:107], v[72:75], v[192:195], v[104:107]
	v_mfma_f32_16x16x32_bf16 v[92:95], v[64:67], v[200:203], v[92:95]
	v_mfma_f32_16x16x32_bf16 v[88:91], v[72:75], v[200:203], v[88:91]
	v_mfma_f32_16x16x32_bf16 v[140:143], v[68:71], v[180:183], v[140:143]
	v_mfma_f32_16x16x32_bf16 v[136:139], v[76:79], v[180:183], v[136:139]
	v_mfma_f32_16x16x32_bf16 v[124:127], v[68:71], v[188:191], v[124:127]
	v_mfma_f32_16x16x32_bf16 v[120:123], v[76:79], v[188:191], v[120:123]
	v_mfma_f32_16x16x32_bf16 v[108:111], v[68:71], v[196:199], v[108:111]
	v_mfma_f32_16x16x32_bf16 v[104:107], v[76:79], v[196:199], v[104:107]
	v_mfma_f32_16x16x32_bf16 v[92:95], v[68:71], v[204:207], v[92:95]
	v_mfma_f32_16x16x32_bf16 v[88:91], v[76:79], v[204:207], v[88:91]
	s_setprio 0
	s_setprio 1
	v_mfma_f32_16x16x32_bf16 v[132:135], v[144:147], v[176:179], v[132:135]
	v_mfma_f32_16x16x32_bf16 v[128:131], v[152:155], v[176:179], v[128:131]
	v_mfma_f32_16x16x32_bf16 v[116:119], v[144:147], v[184:187], v[116:119]
	v_mfma_f32_16x16x32_bf16 v[112:115], v[152:155], v[184:187], v[112:115]
	v_mfma_f32_16x16x32_bf16 v[100:103], v[144:147], v[192:195], v[100:103]
	v_mfma_f32_16x16x32_bf16 v[96:99], v[152:155], v[192:195], v[96:99]
	v_mfma_f32_16x16x32_bf16 v[84:87], v[144:147], v[200:203], v[84:87]
	v_mfma_f32_16x16x32_bf16 v[80:83], v[152:155], v[200:203], v[80:83]
	v_mfma_f32_16x16x32_bf16 v[132:135], v[148:151], v[180:183], v[132:135]
	v_mfma_f32_16x16x32_bf16 v[128:131], v[156:159], v[180:183], v[128:131]
	v_mfma_f32_16x16x32_bf16 v[116:119], v[148:151], v[188:191], v[116:119]
	v_mfma_f32_16x16x32_bf16 v[112:115], v[156:159], v[188:191], v[112:115]
	v_mfma_f32_16x16x32_bf16 v[100:103], v[148:151], v[196:199], v[100:103]
	v_mfma_f32_16x16x32_bf16 v[96:99], v[156:159], v[196:199], v[96:99]
	v_mfma_f32_16x16x32_bf16 v[84:87], v[148:151], v[204:207], v[84:87]
	v_mfma_f32_16x16x32_bf16 v[80:83], v[156:159], v[204:207], v[80:83]
	s_setprio 0
	s_barrier
; #define PG8_STAGE(bufoff, gbase, voff) do { _Pragma("unroll") for (int _i = 0; _i < 2; ++_i) \
;         __builtin_amdgcn_global_load_lds((const unsigned*)((const char*)(gbase) + (voff)[_i]), (PG8_LAS unsigned*)(lds + (bufoff) + ldsw + _i * 8192), 16, 0, 0); } while (0)
; #define PG8_LDA(dst, b, h) do { _Pragma("unroll") for (int m = 0; m < 4; ++m) _Pragma("unroll") for (int k = 0; k < 2; ++k) dst[m][k] = *(const PG8_LAS bf16x8*)(lds + PG8_SA(b, h) + aoff + m * 2048 + k * 1024); } while (0)
; #define PG8_MMA(ai, bj, At, Bt) do { __builtin_amdgcn_s_setprio(1); _Pragma("unroll") for (int m = 0; m < 4; ++m) _Pragma("unroll") for (int n = 0; n < 2; ++n) _Pragma("unroll") for (int k = 0; k < 2; ++k) \
;         acc[ai][bj][m][n] = __builtin_amdgcn_mfma_f32_16x16x32_bf16(Bt[n][k], At[m][k], acc[ai][bj][m][n], 0, 0, 0); __builtin_amdgcn_s_setprio(0); } while (0)
; #define PG8_WAIT_V(n) asm volatile("s_waitcnt vmcnt(" #n ")" ::: "memory")
; #define PG8_WAIT_L(n) asm volatile("s_waitcnt lgkmcnt(" #n ")" ::: "memory")
; #define PG8_BAR __builtin_amdgcn_s_barrier()
; #define PG8_SCHED __builtin_amdgcn_sched_barrier(0)
; template <class Epi, class Sched, bool ALIGN_EPI = false, bool SP2 = false>
; __device__ __forceinline__ void gemm_phase(PG8_LAS unsigned char* lds, const Gemm g, const Sched& S, const Epi& E) {
;     ...
;             PG8_LDA(At, 1, 1); PG8_STAGE(PG8_SB(1, 0), b3, voffB); PG8_STAGE(PG8_SB(1, 1), b3 + hstep, voffB); PG8_STAGE(PG8_SA(1, 0), a3, voffA);
;             PG8_WAIT_V(8); PG8_WAIT_L(0); PG8_BAR; PG8_MMA(1, 0, At, B0); PG8_MMA(1, 1, At, B1); PG8_BAR; PG8_SCHED;
;     ...
;         if constexpr (ALIGN_EPI) { if (wr == 0) PG8_BAR; }
	s_add_i32 s62, s82, s64
	v_lshl_add_u64 v[208:209], v[208:209], 0, s[40:41]
	s_mov_b32 m0, s62
	ds_read_b128 v[176:179], v215 offset:49152
	ds_read_b128 v[180:183], v215 offset:50176
	ds_read_b128 v[184:187], v215 offset:51200
	ds_read_b128 v[188:191], v215 offset:52224
	ds_read_b128 v[192:195], v215 offset:53248
	ds_read_b128 v[196:199], v215 offset:54272
	ds_read_b128 v[200:203], v215 offset:55296
	ds_read_b128 v[204:207], v215 offset:56320
	global_load_lds_dwordx4 v[208:209], off
	s_add_i32 m0, s62, 0x2000
	s_add_u32 s60, s60, 0x80080
	v_lshl_add_u64 v[208:209], v[218:219], 0, s[40:41]
	s_addc_u32 s61, s61, 0
	s_add_i32 s62, s83, s64
	global_load_lds_dwordx4 v[208:209], off
	s_nop 0
	s_mov_b32 m0, s62
	s_nop 0
	global_load_lds_dwordx4 v162, s[60:61]
	s_nop 0
	s_add_i32 m0, s62, 0x2000
	s_nop 0
	global_load_lds_dwordx4 v166, s[60:61]
	v_lshl_add_u64 v[208:209], v[220:221], 0, s[40:41]
	s_mov_b32 m0, s70
	s_nop 0
	global_load_lds_dwordx4 v[208:209], off
	v_lshl_add_u64 v[208:209], v[222:223], 0, s[40:41]
	s_mov_b32 m0, s71
	s_nop 0
	global_load_lds_dwordx4 v[208:209], off
	s_waitcnt vmcnt(8)
	s_waitcnt lgkmcnt(0)
	s_barrier
	s_setprio 1
	s_waitcnt lgkmcnt(0)
	v_mfma_f32_16x16x32_bf16 v[60:63], v[64:67], v[176:179], v[60:63]
	v_mfma_f32_16x16x32_bf16 v[56:59], v[72:75], v[176:179], v[56:59]
	v_mfma_f32_16x16x32_bf16 v[44:47], v[64:67], v[184:187], v[44:47]
	v_mfma_f32_16x16x32_bf16 v[40:43], v[72:75], v[184:187], v[40:43]
	v_mfma_f32_16x16x32_bf16 v[28:31], v[64:67], v[192:195], v[28:31]
	v_mfma_f32_16x16x32_bf16 v[24:27], v[72:75], v[192:195], v[24:27]
	v_mfma_f32_16x16x32_bf16 v[12:15], v[64:67], v[200:203], v[12:15]
	v_mfma_f32_16x16x32_bf16 v[8:11], v[72:75], v[200:203], v[8:11]
	v_mfma_f32_16x16x32_bf16 v[60:63], v[68:71], v[180:183], v[60:63]
	v_mfma_f32_16x16x32_bf16 v[56:59], v[76:79], v[180:183], v[56:59]
	v_mfma_f32_16x16x32_bf16 v[44:47], v[68:71], v[188:191], v[44:47]
	v_mfma_f32_16x16x32_bf16 v[40:43], v[76:79], v[188:191], v[40:43]
	v_mfma_f32_16x16x32_bf16 v[28:31], v[68:71], v[196:199], v[28:31]
	v_mfma_f32_16x16x32_bf16 v[24:27], v[76:79], v[196:199], v[24:27]
	v_mfma_f32_16x16x32_bf16 v[12:15], v[68:71], v[204:207], v[12:15]
	v_mfma_f32_16x16x32_bf16 v[8:11], v[76:79], v[204:207], v[8:11]
	s_setprio 0
	s_setprio 1
	v_mfma_f32_16x16x32_bf16 v[52:55], v[144:147], v[176:179], v[52:55]
	v_mfma_f32_16x16x32_bf16 v[48:51], v[152:155], v[176:179], v[48:51]
	v_mfma_f32_16x16x32_bf16 v[36:39], v[144:147], v[184:187], v[36:39]
	v_mfma_f32_16x16x32_bf16 v[32:35], v[152:155], v[184:187], v[32:35]
	v_mfma_f32_16x16x32_bf16 v[20:23], v[144:147], v[192:195], v[20:23]
	v_mfma_f32_16x16x32_bf16 v[16:19], v[152:155], v[192:195], v[16:19]
	v_mfma_f32_16x16x32_bf16 v[4:7], v[144:147], v[200:203], v[4:7]
	v_mfma_f32_16x16x32_bf16 v[0:3], v[152:155], v[200:203], v[0:3]
	v_mfma_f32_16x16x32_bf16 v[52:55], v[148:151], v[180:183], v[52:55]
	v_mfma_f32_16x16x32_bf16 v[48:51], v[156:159], v[180:183], v[48:51]
	v_mfma_f32_16x16x32_bf16 v[36:39], v[148:151], v[188:191], v[36:39]
	v_mfma_f32_16x16x32_bf16 v[32:35], v[156:159], v[188:191], v[32:35]
	v_mfma_f32_16x16x32_bf16 v[20:23], v[148:151], v[196:199], v[20:23]
	v_mfma_f32_16x16x32_bf16 v[16:19], v[156:159], v[196:199], v[16:19]
	v_mfma_f32_16x16x32_bf16 v[4:7], v[148:151], v[204:207], v[4:7]
	v_mfma_f32_16x16x32_bf16 v[0:3], v[156:159], v[204:207], v[0:3]
	s_setprio 0
	s_barrier
	s_add_i32 s81, s81, 2
	s_add_u32 s58, s58, 0x100
	s_addc_u32 s59, s59, 0
	s_add_u32 s79, s79, 0x100
	s_addc_u32 s80, s80, 0
	s_cmp_gt_u32 s81, 29
	s_cbranch_scc0 .LBB0_939
	s_and_b64 vcc, exec, s[42:43]
	s_cbranch_vccz .LBB0_942
	s_barrier

; #define PG8_STAGE(bufoff, gbase, voff) do { _Pragma("unroll") for (int _i = 0; _i < 2; ++_i) \
;         __builtin_amdgcn_global_load_lds((const unsigned*)((const char*)(gbase) + (voff)[_i]), (PG8_LAS unsigned*)(lds + (bufoff) + ldsw + _i * 8192), 16, 0, 0); } while (0)
; #define PG8_LDA(dst, b, h) do { _Pragma("unroll") for (int m = 0; m < 4; ++m) _Pragma("unroll") for (int k = 0; k < 2; ++k) dst[m][k] = *(const PG8_LAS bf16x8*)(lds + PG8_SA(b, h) + aoff + m * 2048 + k * 1024); } while (0)
; #define PG8_LDB(dst, b, h) do { _Pragma("unroll") for (int n = 0; n < 2; ++n) _Pragma("unroll") for (int k = 0; k < 2; ++k) dst[n][k] = *(const PG8_LAS bf16x8*)(lds + PG8_SB(b, h) + boff + n * 2048 + k * 1024); } while (0)
; #define PG8_MMA(ai, bj, At, Bt) do { __builtin_amdgcn_s_setprio(1); _Pragma("unroll") for (int m = 0; m < 4; ++m) _Pragma("unroll") for (int n = 0; n < 2; ++n) _Pragma("unroll") for (int k = 0; k < 2; ++k) \
;         acc[ai][bj][m][n] = __builtin_amdgcn_mfma_f32_16x16x32_bf16(Bt[n][k], At[m][k], acc[ai][bj][m][n], 0, 0, 0); __builtin_amdgcn_s_setprio(0); } while (0)
; #define PG8_WAIT_V(n) asm volatile("s_waitcnt vmcnt(" #n ")" ::: "memory")
; #define PG8_BAR __builtin_amdgcn_s_barrier()
; template <class Epi, class Sched, bool ALIGN_EPI = false, bool SP2 = false>
; __device__ __forceinline__ void gemm_phase(PG8_LAS unsigned char* lds, const Gemm g, const Sched& S, const Epi& E) {
;     ...
;         for (int t = 0; t < nt; t += 2) {
;             const bool last = (t == nt - 2);
;             const char* a1 = cA + (size_t)(t + 1) * kstep;
;             const char* a2 = last ? nA : cA + (size_t)(t + 2) * kstep; const char* b2 = last ? nB : cB + (size_t)(t + 2) * kstep;
;             const char* a3 = a2 + kstep; const char* b3 = b2 + kstep;
;             if (last && has_next) S.a_ready(nxt);
;             if constexpr (SP2) {
;             PG8_LDB(B0, 0, 0); PG8_LDB(B1, 0, 1); PG8_SCHED; PG8_LDA(At, 0, 0); PG8_STAGE(PG8_SA(1, 1), a1 + hstep, voffA);
;             PG8_WAIT_V(8); PG8_WAIT_L(0); PG8_BAR; PG8_MMA(0, 0, At, B0); PG8_MMA(0, 1, At, B1); PG8_BAR; PG8_SCHED;
;             PG8_LDA(At, 0, 1); PG8_STAGE(PG8_SB(0, 0), b2, voffB); PG8_STAGE(PG8_SB(0, 1), b2 + hstep, voffB); PG8_STAGE(PG8_SA(0, 0), a2, voffA);
;             PG8_WAIT_V(8); PG8_WAIT_L(0); PG8_BAR; PG8_MMA(1, 0, At, B0); PG8_MMA(1, 1, At, B1); PG8_BAR; PG8_SCHED;
.LBB0_1034:
	ds_read_b128 v[128:131], v201
	ds_read_b128 v[132:135], v201 offset:1024
	ds_read_b128 v[136:139], v201 offset:2048
	ds_read_b128 v[140:143], v201 offset:3072
	ds_read_b128 v[144:147], v205
	ds_read_b128 v[148:151], v205 offset:1024
	ds_read_b128 v[152:155], v205 offset:2048
	ds_read_b128 v[156:159], v205 offset:3072
	s_add_u32 s12, s10, 0xfff80080
	s_addc_u32 s13, s11, -1
	s_cmp_eq_u32 s83, 28
	s_cselect_b32 s59, s53, s13
	s_cselect_b32 s58, s79, s12
	s_cselect_b32 s13, s51, s82
	s_cselect_b32 s12, s80, s81
	s_nop 0
	s_add_i32 m0, s63, 0xc000
	ds_read_b128 v[176:179], v207
	ds_read_b128 v[184:187], v207 offset:1024
	ds_read_b128 v[190:193], v207 offset:2048
	ds_read_b128 v[210:213], v207 offset:3072
	ds_read_b128 v[214:217], v207 offset:4096
	ds_read_b128 v[218:221], v207 offset:5120
	ds_read_b128 v[222:225], v207 offset:6144
	ds_read_b128 v[226:229], v207 offset:7168
	global_load_lds_dwordx4 v168, s[10:11]
	s_nop 0
	s_add_i32 m0, s63, 0xe000
	s_nop 0
	global_load_lds_dwordx4 v170, s[10:11]
	s_waitcnt vmcnt(8)
	s_waitcnt lgkmcnt(0)
	s_barrier
	s_setprio 1
	s_waitcnt lgkmcnt(0)
	v_mfma_f32_16x16x32_bf16 v[124:127], v[128:131], v[176:179], v[124:127]
	v_mfma_f32_16x16x32_bf16 v[120:123], v[136:139], v[176:179], v[120:123]
	v_mfma_f32_16x16x32_bf16 v[108:111], v[128:131], v[190:193], v[108:111]
	v_mfma_f32_16x16x32_bf16 v[104:107], v[136:139], v[190:193], v[104:107]
	v_mfma_f32_16x16x32_bf16 v[92:95], v[128:131], v[214:217], v[92:95]
	v_mfma_f32_16x16x32_bf16 v[88:91], v[136:139], v[214:217], v[88:91]
	v_mfma_f32_16x16x32_bf16 v[76:79], v[128:131], v[222:225], v[76:79]
	v_mfma_f32_16x16x32_bf16 v[72:75], v[136:139], v[222:225], v[72:75]
	v_mfma_f32_16x16x32_bf16 v[124:127], v[132:135], v[184:187], v[124:127]
	v_mfma_f32_16x16x32_bf16 v[120:123], v[140:143], v[184:187], v[120:123]
	v_mfma_f32_16x16x32_bf16 v[108:111], v[132:135], v[210:213], v[108:111]
	v_mfma_f32_16x16x32_bf16 v[104:107], v[140:143], v[210:213], v[104:107]
	v_mfma_f32_16x16x32_bf16 v[92:95], v[132:135], v[218:221], v[92:95]
	v_mfma_f32_16x16x32_bf16 v[88:91], v[140:143], v[218:221], v[88:91]
	v_mfma_f32_16x16x32_bf16 v[76:79], v[132:135], v[226:229], v[76:79]
	v_mfma_f32_16x16x32_bf16 v[72:75], v[140:143], v[226:229], v[72:75]
	s_setprio 0
	s_setprio 1
	v_mfma_f32_16x16x32_bf16 v[116:119], v[144:147], v[176:179], v[116:119]
	v_mfma_f32_16x16x32_bf16 v[112:115], v[152:155], v[176:179], v[112:115]
	v_mfma_f32_16x16x32_bf16 v[100:103], v[144:147], v[190:193], v[100:103]
	v_mfma_f32_16x16x32_bf16 v[96:99], v[152:155], v[190:193], v[96:99]
	v_mfma_f32_16x16x32_bf16 v[84:87], v[144:147], v[214:217], v[84:87]
	v_mfma_f32_16x16x32_bf16 v[80:83], v[152:155], v[214:217], v[80:83]
	v_mfma_f32_16x16x32_bf16 v[68:71], v[144:147], v[222:225], v[68:71]
	v_mfma_f32_16x16x32_bf16 v[64:67], v[152:155], v[222:225], v[64:67]
	v_mfma_f32_16x16x32_bf16 v[116:119], v[148:151], v[184:187], v[116:119]
	v_mfma_f32_16x16x32_bf16 v[112:115], v[156:159], v[184:187], v[112:115]
	v_mfma_f32_16x16x32_bf16 v[100:103], v[148:151], v[210:213], v[100:103]
	v_mfma_f32_16x16x32_bf16 v[96:99], v[156:159], v[210:213], v[96:99]
	v_mfma_f32_16x16x32_bf16 v[84:87], v[148:151], v[218:221], v[84:87]
	v_mfma_f32_16x16x32_bf16 v[80:83], v[156:159], v[218:221], v[80:83]
	v_mfma_f32_16x16x32_bf16 v[68:71], v[148:151], v[226:229], v[68:71]
	v_mfma_f32_16x16x32_bf16 v[64:67], v[156:159], v[226:229], v[64:67]
	s_setprio 0
	s_barrier
	s_add_i32 s84, s73, s62
	v_lshl_add_u64 v[180:181], s[12:13], 0, v[162:163]
	s_mov_b32 m0, s84
	ds_read_b128 v[176:179], v207 offset:16384
	ds_read_b128 v[184:187], v207 offset:17408
	ds_read_b128 v[190:193], v207 offset:18432
	ds_read_b128 v[210:213], v207 offset:19456
	ds_read_b128 v[214:217], v207 offset:20480
	ds_read_b128 v[218:221], v207 offset:21504
	ds_read_b128 v[222:225], v207 offset:22528
	ds_read_b128 v[226:229], v207 offset:23552
	global_load_lds_dwordx4 v[180:181], off
	s_add_i32 m0, s84, 0x2000
	s_add_u32 s84, s12, 0x80000
	v_lshl_add_u64 v[194:195], s[12:13], 0, v[166:167]
	s_addc_u32 s85, s13, 0
	s_add_i32 s86, s74, s62
	global_load_lds_dwordx4 v[194:195], off
	s_nop 0
	s_mov_b32 m0, s86
	v_lshl_add_u64 v[202:203], s[58:59], 0, v[164:165]
	global_load_lds_dwordx4 v162, s[84:85]
	s_nop 0
	s_add_i32 m0, s86, 0x2000
	s_nop 0
	global_load_lds_dwordx4 v166, s[84:85]
	v_lshl_add_u64 v[198:199], s[58:59], 0, v[160:161]
	s_mov_b32 m0, s63
	s_nop 0
	global_load_lds_dwordx4 v[198:199], off
	s_mov_b32 m0, s64
	s_nop 0
	global_load_lds_dwordx4 v[202:203], off
	s_waitcnt vmcnt(8)
	s_waitcnt lgkmcnt(0)
	s_barrier
; #define PG8_STAGE(bufoff, gbase, voff) do { _Pragma("unroll") for (int _i = 0; _i < 2; ++_i) \
;         __builtin_amdgcn_global_load_lds((const unsigned*)((const char*)(gbase) + (voff)[_i]), (PG8_LAS unsigned*)(lds + (bufoff) + ldsw + _i * 8192), 16, 0, 0); } while (0)
; #define PG8_LDA(dst, b, h) do { _Pragma("unroll") for (int m = 0; m < 4; ++m) _Pragma("unroll") for (int k = 0; k < 2; ++k) dst[m][k] = *(const PG8_LAS bf16x8*)(lds + PG8_SA(b, h) + aoff + m * 2048 + k * 1024); } while (0)
; #define PG8_LDB(dst, b, h) do { _Pragma("unroll") for (int n = 0; n < 2; ++n) _Pragma("unroll") for (int k = 0; k < 2; ++k) dst[n][k] = *(const PG8_LAS bf16x8*)(lds + PG8_SB(b, h) + boff + n * 2048 + k * 1024); } while (0)
; #define PG8_MMA(ai, bj, At, Bt) do { __builtin_amdgcn_s_setprio(1); _Pragma("unroll") for (int m = 0; m < 4; ++m) _Pragma("unroll") for (int n = 0; n < 2; ++n) _Pragma("unroll") for (int k = 0; k < 2; ++k) \
;         acc[ai][bj][m][n] = __builtin_amdgcn_mfma_f32_16x16x32_bf16(Bt[n][k], At[m][k], acc[ai][bj][m][n], 0, 0, 0); __builtin_amdgcn_s_setprio(0); } while (0)
; #define PG8_WAIT_V(n) asm volatile("s_waitcnt vmcnt(" #n ")" ::: "memory")
; #define PG8_WAIT_L(n) asm volatile("s_waitcnt lgkmcnt(" #n ")" ::: "memory")
; #define PG8_BAR __builtin_amdgcn_s_barrier()
; #define PG8_SCHED __builtin_amdgcn_sched_barrier(0)
; template <class Epi, class Sched, bool ALIGN_EPI = false, bool SP2 = false>
; __device__ __forceinline__ void gemm_phase(PG8_LAS unsigned char* lds, const Gemm g, const Sched& S, const Epi& E) {
;     ...
;             PG8_WAIT_V(8); PG8_WAIT_L(0); PG8_BAR; PG8_MMA(1, 0, At, B0); PG8_MMA(1, 1, At, B1); PG8_BAR; PG8_SCHED;
;             PG8_LDB(B0, 1, 0); PG8_LDB(B1, 1, 1); PG8_SCHED; PG8_LDA(At, 1, 0); PG8_STAGE(PG8_SA(0, 1), a2 + hstep, voffA);
;             PG8_WAIT_V(8); PG8_WAIT_L(0); PG8_BAR; PG8_MMA(0, 0, At, B0); PG8_MMA(0, 1, At, B1); PG8_BAR; PG8_SCHED;
	s_setprio 1
	s_waitcnt lgkmcnt(0)
	v_mfma_f32_16x16x32_bf16 v[60:63], v[128:131], v[176:179], v[60:63]
	v_mfma_f32_16x16x32_bf16 v[56:59], v[136:139], v[176:179], v[56:59]
	v_mfma_f32_16x16x32_bf16 v[44:47], v[128:131], v[190:193], v[44:47]
	v_mfma_f32_16x16x32_bf16 v[40:43], v[136:139], v[190:193], v[40:43]
	v_mfma_f32_16x16x32_bf16 v[28:31], v[128:131], v[214:217], v[28:31]
	v_mfma_f32_16x16x32_bf16 v[24:27], v[136:139], v[214:217], v[24:27]
	v_mfma_f32_16x16x32_bf16 v[12:15], v[128:131], v[222:225], v[12:15]
	v_mfma_f32_16x16x32_bf16 v[8:11], v[136:139], v[222:225], v[8:11]
	v_mfma_f32_16x16x32_bf16 v[60:63], v[132:135], v[184:187], v[60:63]
	v_mfma_f32_16x16x32_bf16 v[56:59], v[140:143], v[184:187], v[56:59]
	v_mfma_f32_16x16x32_bf16 v[44:47], v[132:135], v[210:213], v[44:47]
	v_mfma_f32_16x16x32_bf16 v[40:43], v[140:143], v[210:213], v[40:43]
	v_mfma_f32_16x16x32_bf16 v[28:31], v[132:135], v[218:221], v[28:31]
	v_mfma_f32_16x16x32_bf16 v[24:27], v[140:143], v[218:221], v[24:27]
	v_mfma_f32_16x16x32_bf16 v[12:15], v[132:135], v[226:229], v[12:15]
	v_mfma_f32_16x16x32_bf16 v[8:11], v[140:143], v[226:229], v[8:11]
	s_setprio 0
	s_setprio 1
	v_mfma_f32_16x16x32_bf16 v[52:55], v[144:147], v[176:179], v[52:55]
	v_mfma_f32_16x16x32_bf16 v[48:51], v[152:155], v[176:179], v[48:51]
	v_mfma_f32_16x16x32_bf16 v[36:39], v[144:147], v[190:193], v[36:39]
	v_mfma_f32_16x16x32_bf16 v[32:35], v[152:155], v[190:193], v[32:35]
	v_mfma_f32_16x16x32_bf16 v[20:23], v[144:147], v[214:217], v[20:23]
	v_mfma_f32_16x16x32_bf16 v[16:19], v[152:155], v[214:217], v[16:19]
	v_mfma_f32_16x16x32_bf16 v[4:7], v[144:147], v[222:225], v[4:7]
	v_mfma_f32_16x16x32_bf16 v[0:3], v[152:155], v[222:225], v[0:3]
	v_mfma_f32_16x16x32_bf16 v[52:55], v[148:151], v[184:187], v[52:55]
	v_mfma_f32_16x16x32_bf16 v[48:51], v[156:159], v[184:187], v[48:51]
	v_mfma_f32_16x16x32_bf16 v[36:39], v[148:151], v[210:213], v[36:39]
	v_mfma_f32_16x16x32_bf16 v[32:35], v[156:159], v[210:213], v[32:35]
	v_mfma_f32_16x16x32_bf16 v[20:23], v[148:151], v[218:221], v[20:23]
	v_mfma_f32_16x16x32_bf16 v[16:19], v[156:159], v[218:221], v[16:19]
	v_mfma_f32_16x16x32_bf16 v[4:7], v[148:151], v[226:229], v[4:7]
	v_mfma_f32_16x16x32_bf16 v[0:3], v[156:159], v[226:229], v[0:3]
	s_setprio 0
	s_barrier
	s_add_i32 s84, 0, 0x18000
	s_add_i32 s85, 0, 0x1c000
	v_add_u32_e32 v140, s84, v189
	v_add_u32_e32 v156, s85, v189
	ds_read_b128 v[128:131], v140
	ds_read_b128 v[132:135], v140 offset:1024
	ds_read_b128 v[136:139], v140 offset:2048
	ds_read_b128 v[140:143], v140 offset:3072
	ds_read_b128 v[144:147], v156
	ds_read_b128 v[148:151], v156 offset:1024
	ds_read_b128 v[152:155], v156 offset:2048
	ds_read_b128 v[156:159], v156 offset:3072
	s_add_u32 s58, s58, 0x80000
	s_addc_u32 s59, s59, 0
	s_mov_b32 m0, s65
	s_nop 0
	ds_read_b128 v[176:179], v207 offset:32768
	ds_read_b128 v[184:187], v207 offset:33792
	ds_read_b128 v[190:193], v207 offset:34816
	ds_read_b128 v[210:213], v207 offset:35840
	ds_read_b128 v[214:217], v207 offset:36864
	ds_read_b128 v[218:221], v207 offset:37888
	ds_read_b128 v[222:225], v207 offset:38912
	ds_read_b128 v[226:229], v207 offset:39936
	global_load_lds_dwordx4 v160, s[58:59]
	s_nop 0
	s_mov_b32 m0, s67
	s_nop 0
	global_load_lds_dwordx4 v164, s[58:59]
	s_waitcnt vmcnt(8)
	s_waitcnt lgkmcnt(0)
	s_barrier
	s_setprio 1
	s_waitcnt lgkmcnt(0)
	v_mfma_f32_16x16x32_bf16 v[124:127], v[128:131], v[176:179], v[124:127]
	v_mfma_f32_16x16x32_bf16 v[120:123], v[136:139], v[176:179], v[120:123]
	v_mfma_f32_16x16x32_bf16 v[108:111], v[128:131], v[190:193], v[108:111]
	v_mfma_f32_16x16x32_bf16 v[104:107], v[136:139], v[190:193], v[104:107]
	v_mfma_f32_16x16x32_bf16 v[92:95], v[128:131], v[214:217], v[92:95]
	v_mfma_f32_16x16x32_bf16 v[88:91], v[136:139], v[214:217], v[88:91]
	v_mfma_f32_16x16x32_bf16 v[76:79], v[128:131], v[222:225], v[76:79]
	v_mfma_f32_16x16x32_bf16 v[72:75], v[136:139], v[222:225], v[72:75]
	v_mfma_f32_16x16x32_bf16 v[124:127], v[132:135], v[184:187], v[124:127]
	v_mfma_f32_16x16x32_bf16 v[120:123], v[140:143], v[184:187], v[120:123]
	v_mfma_f32_16x16x32_bf16 v[108:111], v[132:135], v[210:213], v[108:111]
	v_mfma_f32_16x16x32_bf16 v[104:107], v[140:143], v[210:213], v[104:107]
	v_mfma_f32_16x16x32_bf16 v[92:95], v[132:135], v[218:221], v[92:95]
	v_mfma_f32_16x16x32_bf16 v[88:91], v[140:143], v[218:221], v[88:91]
	v_mfma_f32_16x16x32_bf16 v[76:79], v[132:135], v[226:229], v[76:79]
	v_mfma_f32_16x16x32_bf16 v[72:75], v[140:143], v[226:229], v[72:75]
	s_setprio 0
	s_setprio 1
	v_mfma_f32_16x16x32_bf16 v[116:119], v[144:147], v[176:179], v[116:119]
	v_mfma_f32_16x16x32_bf16 v[112:115], v[152:155], v[176:179], v[112:115]
	v_mfma_f32_16x16x32_bf16 v[100:103], v[144:147], v[190:193], v[100:103]
	v_mfma_f32_16x16x32_bf16 v[96:99], v[152:155], v[190:193], v[96:99]
	v_mfma_f32_16x16x32_bf16 v[84:87], v[144:147], v[214:217], v[84:87]
	v_mfma_f32_16x16x32_bf16 v[80:83], v[152:155], v[214:217], v[80:83]
	v_mfma_f32_16x16x32_bf16 v[68:71], v[144:147], v[222:225], v[68:71]
	v_mfma_f32_16x16x32_bf16 v[64:67], v[152:155], v[222:225], v[64:67]
	v_mfma_f32_16x16x32_bf16 v[116:119], v[148:151], v[184:187], v[116:119]
	v_mfma_f32_16x16x32_bf16 v[112:115], v[156:159], v[184:187], v[112:115]
	v_mfma_f32_16x16x32_bf16 v[100:103], v[148:151], v[210:213], v[100:103]
	v_mfma_f32_16x16x32_bf16 v[96:99], v[156:159], v[210:213], v[96:99]
	v_mfma_f32_16x16x32_bf16 v[84:87], v[148:151], v[218:221], v[84:87]
	v_mfma_f32_16x16x32_bf16 v[80:83], v[156:159], v[218:221], v[80:83]
	v_mfma_f32_16x16x32_bf16 v[68:71], v[148:151], v[226:229], v[68:71]
	v_mfma_f32_16x16x32_bf16 v[64:67], v[156:159], v[226:229], v[64:67]
	s_setprio 0
	s_barrier
; #define PG8_STAGE(bufoff, gbase, voff) do { _Pragma("unroll") for (int _i = 0; _i < 2; ++_i) \
;         __builtin_amdgcn_global_load_lds((const unsigned*)((const char*)(gbase) + (voff)[_i]), (PG8_LAS unsigned*)(lds + (bufoff) + ldsw + _i * 8192), 16, 0, 0); } while (0)
; #define PG8_LDA(dst, b, h) do { _Pragma("unroll") for (int m = 0; m < 4; ++m) _Pragma("unroll") for (int k = 0; k < 2; ++k) dst[m][k] = *(const PG8_LAS bf16x8*)(lds + PG8_SA(b, h) + aoff + m * 2048 + k * 1024); } while (0)
; #define PG8_MMA(ai, bj, At, Bt) do { __builtin_amdgcn_s_setprio(1); _Pragma("unroll") for (int m = 0; m < 4; ++m) _Pragma("unroll") for (int n = 0; n < 2; ++n) _Pragma("unroll") for (int k = 0; k < 2; ++k) \
;         acc[ai][bj][m][n] = __builtin_amdgcn_mfma_f32_16x16x32_bf16(Bt[n][k], At[m][k], acc[ai][bj][m][n], 0, 0, 0); __builtin_amdgcn_s_setprio(0); } while (0)
; #define PG8_WAIT_V(n) asm volatile("s_waitcnt vmcnt(" #n ")" ::: "memory")
; #define PG8_WAIT_L(n) asm volatile("s_waitcnt lgkmcnt(" #n ")" ::: "memory")
; #define PG8_BAR __builtin_amdgcn_s_barrier()
; #define PG8_SCHED __builtin_amdgcn_sched_barrier(0)
; template <class Epi, class Sched, bool ALIGN_EPI = false, bool SP2 = false>
; __device__ __forceinline__ void gemm_phase(PG8_LAS unsigned char* lds, const Gemm g, const Sched& S, const Epi& E) {
;     ...
;             PG8_LDA(At, 1, 1); PG8_STAGE(PG8_SB(1, 0), b3, voffB); PG8_STAGE(PG8_SB(1, 1), b3 + hstep, voffB); PG8_STAGE(PG8_SA(1, 0), a3, voffA);
;             PG8_WAIT_V(8); PG8_WAIT_L(0); PG8_BAR; PG8_MMA(1, 0, At, B0); PG8_MMA(1, 1, At, B1); PG8_BAR; PG8_SCHED;
;     ...
;         if constexpr (ALIGN_EPI) { if (wr == 0) PG8_BAR; }
	s_add_i32 s58, s84, s62
	v_lshl_add_u64 v[180:181], v[180:181], 0, s[38:39]
	s_mov_b32 m0, s58
	ds_read_b128 v[176:179], v207 offset:49152
	ds_read_b128 v[184:187], v207 offset:50176
	ds_read_b128 v[190:193], v207 offset:51200
	ds_read_b128 v[210:213], v207 offset:52224
	ds_read_b128 v[214:217], v207 offset:53248
	ds_read_b128 v[218:221], v207 offset:54272
	ds_read_b128 v[222:225], v207 offset:55296
	ds_read_b128 v[226:229], v207 offset:56320
	global_load_lds_dwordx4 v[180:181], off
	s_add_i32 m0, s58, 0x2000
	s_add_u32 s12, s12, 0x80080
	v_lshl_add_u64 v[180:181], v[194:195], 0, s[38:39]
	s_addc_u32 s13, s13, 0
	s_add_i32 s58, s85, s62
	global_load_lds_dwordx4 v[180:181], off
	s_nop 0
	s_mov_b32 m0, s58
	s_nop 0
	global_load_lds_dwordx4 v162, s[12:13]
	s_nop 0
	s_add_i32 m0, s58, 0x2000
	s_nop 0
	global_load_lds_dwordx4 v166, s[12:13]
	v_lshl_add_u64 v[180:181], v[198:199], 0, s[38:39]
	s_mov_b32 m0, s69
	s_nop 0
	global_load_lds_dwordx4 v[180:181], off
	v_lshl_add_u64 v[180:181], v[202:203], 0, s[38:39]
	s_mov_b32 m0, s70
	s_nop 0
	global_load_lds_dwordx4 v[180:181], off
	s_waitcnt vmcnt(8)
	s_waitcnt lgkmcnt(0)
	s_barrier
	s_setprio 1
	s_waitcnt lgkmcnt(0)
	v_mfma_f32_16x16x32_bf16 v[60:63], v[128:131], v[176:179], v[60:63]
	v_mfma_f32_16x16x32_bf16 v[56:59], v[136:139], v[176:179], v[56:59]
	v_mfma_f32_16x16x32_bf16 v[44:47], v[128:131], v[190:193], v[44:47]
	v_mfma_f32_16x16x32_bf16 v[40:43], v[136:139], v[190:193], v[40:43]
	v_mfma_f32_16x16x32_bf16 v[28:31], v[128:131], v[214:217], v[28:31]
	v_mfma_f32_16x16x32_bf16 v[24:27], v[136:139], v[214:217], v[24:27]
	v_mfma_f32_16x16x32_bf16 v[12:15], v[128:131], v[222:225], v[12:15]
	v_mfma_f32_16x16x32_bf16 v[8:11], v[136:139], v[222:225], v[8:11]
	v_mfma_f32_16x16x32_bf16 v[60:63], v[132:135], v[184:187], v[60:63]
	v_mfma_f32_16x16x32_bf16 v[56:59], v[140:143], v[184:187], v[56:59]
	v_mfma_f32_16x16x32_bf16 v[44:47], v[132:135], v[210:213], v[44:47]
	v_mfma_f32_16x16x32_bf16 v[40:43], v[140:143], v[210:213], v[40:43]
	v_mfma_f32_16x16x32_bf16 v[28:31], v[132:135], v[218:221], v[28:31]
	v_mfma_f32_16x16x32_bf16 v[24:27], v[140:143], v[218:221], v[24:27]
	v_mfma_f32_16x16x32_bf16 v[12:15], v[132:135], v[226:229], v[12:15]
	v_mfma_f32_16x16x32_bf16 v[8:11], v[140:143], v[226:229], v[8:11]
	s_setprio 0
	s_setprio 1
	v_mfma_f32_16x16x32_bf16 v[52:55], v[144:147], v[176:179], v[52:55]
	v_mfma_f32_16x16x32_bf16 v[48:51], v[152:155], v[176:179], v[48:51]
	v_mfma_f32_16x16x32_bf16 v[36:39], v[144:147], v[190:193], v[36:39]
	v_mfma_f32_16x16x32_bf16 v[32:35], v[152:155], v[190:193], v[32:35]
	v_mfma_f32_16x16x32_bf16 v[20:23], v[144:147], v[214:217], v[20:23]
	v_mfma_f32_16x16x32_bf16 v[16:19], v[152:155], v[214:217], v[16:19]
	v_mfma_f32_16x16x32_bf16 v[4:7], v[144:147], v[222:225], v[4:7]
	v_mfma_f32_16x16x32_bf16 v[0:3], v[152:155], v[222:225], v[0:3]
	v_mfma_f32_16x16x32_bf16 v[52:55], v[148:151], v[184:187], v[52:55]
	v_mfma_f32_16x16x32_bf16 v[48:51], v[156:159], v[184:187], v[48:51]
	v_mfma_f32_16x16x32_bf16 v[36:39], v[148:151], v[210:213], v[36:39]
	v_mfma_f32_16x16x32_bf16 v[32:35], v[156:159], v[210:213], v[32:35]
	v_mfma_f32_16x16x32_bf16 v[20:23], v[148:151], v[218:221], v[20:23]
	v_mfma_f32_16x16x32_bf16 v[16:19], v[156:159], v[218:221], v[16:19]
	v_mfma_f32_16x16x32_bf16 v[4:7], v[148:151], v[226:229], v[4:7]
	v_mfma_f32_16x16x32_bf16 v[0:3], v[156:159], v[226:229], v[0:3]
	s_setprio 0
	s_barrier
	s_add_i32 s83, s83, 2
	s_add_u32 s10, s10, 0x100
	s_addc_u32 s11, s11, 0
	s_add_u32 s81, s81, 0x100
	s_addc_u32 s82, s82, 0
	s_cmp_gt_u32 s83, 29
	s_cbranch_scc0 .LBB0_1034
	s_and_b64 vcc, exec, s[40:41]
	s_cbranch_vccz .LBB0_1037
	s_barrier

; #define PG8_STAGE(bufoff, gbase, voff) do { _Pragma("unroll") for (int _i = 0; _i < 2; ++_i) \
;         __builtin_amdgcn_global_load_lds((const unsigned*)((const char*)(gbase) + (voff)[_i]), (PG8_LAS unsigned*)(lds + (bufoff) + ldsw + _i * 8192), 16, 0, 0); } while (0)
; #define PG8_LDA(dst, b, h) do { _Pragma("unroll") for (int m = 0; m < 4; ++m) _Pragma("unroll") for (int k = 0; k < 2; ++k) dst[m][k] = *(const PG8_LAS bf16x8*)(lds + PG8_SA(b, h) + aoff + m * 2048 + k * 1024); } while (0)
; #define PG8_LDB(dst, b, h) do { _Pragma("unroll") for (int n = 0; n < 2; ++n) _Pragma("unroll") for (int k = 0; k < 2; ++k) dst[n][k] = *(const PG8_LAS bf16x8*)(lds + PG8_SB(b, h) + boff + n * 2048 + k * 1024); } while (0)
; #define PG8_MMA(ai, bj, At, Bt) do { __builtin_amdgcn_s_setprio(1); _Pragma("unroll") for (int m = 0; m < 4; ++m) _Pragma("unroll") for (int n = 0; n < 2; ++n) _Pragma("unroll") for (int k = 0; k < 2; ++k) \
;         acc[ai][bj][m][n] = __builtin_amdgcn_mfma_f32_16x16x32_bf16(Bt[n][k], At[m][k], acc[ai][bj][m][n], 0, 0, 0); __builtin_amdgcn_s_setprio(0); } while (0)
; #define PG8_WAIT_V(n) asm volatile("s_waitcnt vmcnt(" #n ")" ::: "memory")
; #define PG8_BAR __builtin_amdgcn_s_barrier()
; template <class Epi, class Sched, bool ALIGN_EPI = false, bool SP2 = false>
; __device__ __forceinline__ void gemm_phase(PG8_LAS unsigned char* lds, const Gemm g, const Sched& S, const Epi& E) {
;     ...
;         for (int t = 0; t < nt; t += 2) {
;             const bool last = (t == nt - 2);
;             const char* a1 = cA + (size_t)(t + 1) * kstep;
;             const char* a2 = last ? nA : cA + (size_t)(t + 2) * kstep; const char* b2 = last ? nB : cB + (size_t)(t + 2) * kstep;
;             const char* a3 = a2 + kstep; const char* b3 = b2 + kstep;
;             if (last && has_next) S.a_ready(nxt);
;             if constexpr (SP2) {
;             PG8_LDB(B0, 0, 0); PG8_LDB(B1, 0, 1); PG8_SCHED; PG8_LDA(At, 0, 0); PG8_STAGE(PG8_SA(1, 1), a1 + hstep, voffA);
;             PG8_WAIT_V(8); PG8_WAIT_L(0); PG8_BAR; PG8_MMA(0, 0, At, B0); PG8_MMA(0, 1, At, B1); PG8_BAR; PG8_SCHED;
;             PG8_LDA(At, 0, 1); PG8_STAGE(PG8_SB(0, 0), b2, voffB); PG8_STAGE(PG8_SB(0, 1), b2 + hstep, voffB); PG8_STAGE(PG8_SA(0, 0), a2, voffA);
;             PG8_WAIT_V(8); PG8_WAIT_L(0); PG8_BAR; PG8_MMA(1, 0, At, B0); PG8_MMA(1, 1, At, B1); PG8_BAR; PG8_SCHED;
.LBB0_1114:
	ds_read_b128 v[96:99], v197
	ds_read_b128 v[100:103], v197 offset:1024
	ds_read_b128 v[104:107], v197 offset:2048
	ds_read_b128 v[112:115], v197 offset:3072
	ds_read_b128 v[144:147], v198
	ds_read_b128 v[148:151], v198 offset:1024
	ds_read_b128 v[152:155], v198 offset:2048
	ds_read_b128 v[172:175], v198 offset:3072
	s_add_u32 s50, s48, 0xffe00080
	s_addc_u32 s51, s49, -1
	s_cmpk_eq_i32 s73, 0x7c
	s_cselect_b32 s53, s43, s51
	s_cselect_b32 s52, s69, s50
	s_cselect_b32 s51, s41, s72
	s_cselect_b32 s50, s70, s71
	s_nop 0
	s_add_i32 m0, s56, 0xc000
	ds_read_b128 v[176:179], v199
	ds_read_b128 v[180:183], v199 offset:1024
	ds_read_b128 v[184:187], v199 offset:2048
	ds_read_b128 v[188:191], v199 offset:3072
	ds_read_b128 v[202:205], v199 offset:4096
	ds_read_b128 v[206:209], v199 offset:5120
	ds_read_b128 v[210:213], v199 offset:6144
	ds_read_b128 v[214:217], v199 offset:7168
	global_load_lds_dwordx4 v164, s[48:49]
	s_nop 0
	s_add_i32 m0, s56, 0xe000
	s_nop 0
	global_load_lds_dwordx4 v166, s[48:49]
	s_waitcnt vmcnt(8)
	s_waitcnt lgkmcnt(0)
	s_barrier
	s_setprio 1
	s_waitcnt lgkmcnt(0)
	v_mfma_f32_16x16x32_bf16 v[140:143], v[96:99], v[176:179], v[140:143]
	v_mfma_f32_16x16x32_bf16 v[136:139], v[104:107], v[176:179], v[136:139]
	v_mfma_f32_16x16x32_bf16 v[124:127], v[96:99], v[184:187], v[124:127]
	v_mfma_f32_16x16x32_bf16 v[120:123], v[104:107], v[184:187], v[120:123]
	v_mfma_f32_16x16x32_bf16 v[92:95], v[96:99], v[202:205], v[92:95]
	v_mfma_f32_16x16x32_bf16 v[88:91], v[104:107], v[202:205], v[88:91]
	v_mfma_f32_16x16x32_bf16 v[76:79], v[96:99], v[210:213], v[76:79]
	v_mfma_f32_16x16x32_bf16 v[72:75], v[104:107], v[210:213], v[72:75]
	v_mfma_f32_16x16x32_bf16 v[140:143], v[100:103], v[180:183], v[140:143]
	v_mfma_f32_16x16x32_bf16 v[136:139], v[112:115], v[180:183], v[136:139]
	v_mfma_f32_16x16x32_bf16 v[124:127], v[100:103], v[188:191], v[124:127]
	v_mfma_f32_16x16x32_bf16 v[120:123], v[112:115], v[188:191], v[120:123]
	v_mfma_f32_16x16x32_bf16 v[92:95], v[100:103], v[206:209], v[92:95]
	v_mfma_f32_16x16x32_bf16 v[88:91], v[112:115], v[206:209], v[88:91]
	v_mfma_f32_16x16x32_bf16 v[76:79], v[100:103], v[214:217], v[76:79]
	v_mfma_f32_16x16x32_bf16 v[72:75], v[112:115], v[214:217], v[72:75]
	s_setprio 0
	s_setprio 1
	v_mfma_f32_16x16x32_bf16 v[132:135], v[144:147], v[176:179], v[132:135]
	v_mfma_f32_16x16x32_bf16 v[128:131], v[152:155], v[176:179], v[128:131]
	v_mfma_f32_16x16x32_bf16 v[116:119], v[144:147], v[184:187], v[116:119]
	v_mfma_f32_16x16x32_bf16 v[108:111], v[152:155], v[184:187], v[108:111]
	v_mfma_f32_16x16x32_bf16 v[84:87], v[144:147], v[202:205], v[84:87]
	v_mfma_f32_16x16x32_bf16 v[80:83], v[152:155], v[202:205], v[80:83]
	v_mfma_f32_16x16x32_bf16 v[68:71], v[144:147], v[210:213], v[68:71]
	v_mfma_f32_16x16x32_bf16 v[64:67], v[152:155], v[210:213], v[64:67]
	v_mfma_f32_16x16x32_bf16 v[132:135], v[148:151], v[180:183], v[132:135]
	v_mfma_f32_16x16x32_bf16 v[128:131], v[172:175], v[180:183], v[128:131]
	v_mfma_f32_16x16x32_bf16 v[116:119], v[148:151], v[188:191], v[116:119]
	v_mfma_f32_16x16x32_bf16 v[108:111], v[172:175], v[188:191], v[108:111]
	v_mfma_f32_16x16x32_bf16 v[84:87], v[148:151], v[206:209], v[84:87]
	v_mfma_f32_16x16x32_bf16 v[80:83], v[172:175], v[206:209], v[80:83]
	v_mfma_f32_16x16x32_bf16 v[68:71], v[148:151], v[214:217], v[68:71]
	v_mfma_f32_16x16x32_bf16 v[64:67], v[172:175], v[214:217], v[64:67]
	s_setprio 0
	s_barrier
	s_add_i32 s74, s65, s55
	v_lshl_add_u64 v[192:193], s[50:51], 0, v[158:159]
	s_mov_b32 m0, s74
	ds_read_b128 v[176:179], v199 offset:16384
	ds_read_b128 v[180:183], v199 offset:17408
	ds_read_b128 v[184:187], v199 offset:18432
	ds_read_b128 v[188:191], v199 offset:19456
	ds_read_b128 v[202:205], v199 offset:20480
	ds_read_b128 v[206:209], v199 offset:21504
	ds_read_b128 v[210:213], v199 offset:22528
	ds_read_b128 v[214:217], v199 offset:23552
	global_load_lds_dwordx4 v[192:193], off
	s_add_i32 m0, s74, 0x2000
	s_add_u32 s74, s50, 0x200000
	v_lshl_add_u64 v[218:219], s[50:51], 0, v[162:163]
	s_addc_u32 s75, s51, 0
	s_add_i32 s76, s67, s55
	global_load_lds_dwordx4 v[218:219], off
	s_nop 0
	s_mov_b32 m0, s76
	v_lshl_add_u64 v[222:223], s[52:53], 0, v[160:161]
	global_load_lds_dwordx4 v158, s[74:75]
	s_nop 0
	s_add_i32 m0, s76, 0x2000
	s_nop 0
	global_load_lds_dwordx4 v162, s[74:75]
	v_lshl_add_u64 v[220:221], s[52:53], 0, v[156:157]
	s_mov_b32 m0, s56
	s_nop 0
	global_load_lds_dwordx4 v[220:221], off
	s_mov_b32 m0, s57
	s_nop 0
	global_load_lds_dwordx4 v[222:223], off
	s_waitcnt vmcnt(8)
	s_waitcnt lgkmcnt(0)
	s_barrier
; #define PG8_STAGE(bufoff, gbase, voff) do { _Pragma("unroll") for (int _i = 0; _i < 2; ++_i) \
;         __builtin_amdgcn_global_load_lds((const unsigned*)((const char*)(gbase) + (voff)[_i]), (PG8_LAS unsigned*)(lds + (bufoff) + ldsw + _i * 8192), 16, 0, 0); } while (0)
; #define PG8_LDA(dst, b, h) do { _Pragma("unroll") for (int m = 0; m < 4; ++m) _Pragma("unroll") for (int k = 0; k < 2; ++k) dst[m][k] = *(const PG8_LAS bf16x8*)(lds + PG8_SA(b, h) + aoff + m * 2048 + k * 1024); } while (0)
; #define PG8_LDB(dst, b, h) do { _Pragma("unroll") for (int n = 0; n < 2; ++n) _Pragma("unroll") for (int k = 0; k < 2; ++k) dst[n][k] = *(const PG8_LAS bf16x8*)(lds + PG8_SB(b, h) + boff + n * 2048 + k * 1024); } while (0)
; #define PG8_MMA(ai, bj, At, Bt) do { __builtin_amdgcn_s_setprio(1); _Pragma("unroll") for (int m = 0; m < 4; ++m) _Pragma("unroll") for (int n = 0; n < 2; ++n) _Pragma("unroll") for (int k = 0; k < 2; ++k) \
;         acc[ai][bj][m][n] = __builtin_amdgcn_mfma_f32_16x16x32_bf16(Bt[n][k], At[m][k], acc[ai][bj][m][n], 0, 0, 0); __builtin_amdgcn_s_setprio(0); } while (0)
; #define PG8_WAIT_V(n) asm volatile("s_waitcnt vmcnt(" #n ")" ::: "memory")
; #define PG8_WAIT_L(n) asm volatile("s_waitcnt lgkmcnt(" #n ")" ::: "memory")
; #define PG8_BAR __builtin_amdgcn_s_barrier()
; #define PG8_SCHED __builtin_amdgcn_sched_barrier(0)
; template <class Epi, class Sched, bool ALIGN_EPI = false, bool SP2 = false>
; __device__ __forceinline__ void gemm_phase(PG8_LAS unsigned char* lds, const Gemm g, const Sched& S, const Epi& E) {
;     ...
;             PG8_WAIT_V(8); PG8_WAIT_L(0); PG8_BAR; PG8_MMA(1, 0, At, B0); PG8_MMA(1, 1, At, B1); PG8_BAR; PG8_SCHED;
;             PG8_LDB(B0, 1, 0); PG8_LDB(B1, 1, 1); PG8_SCHED; PG8_LDA(At, 1, 0); PG8_STAGE(PG8_SA(0, 1), a2 + hstep, voffA);
;             PG8_WAIT_V(8); PG8_WAIT_L(0); PG8_BAR; PG8_MMA(0, 0, At, B0); PG8_MMA(0, 1, At, B1); PG8_BAR; PG8_SCHED;
	s_setprio 1
	s_waitcnt lgkmcnt(0)
	v_mfma_f32_16x16x32_bf16 v[60:63], v[96:99], v[176:179], v[60:63]
	v_mfma_f32_16x16x32_bf16 v[56:59], v[104:107], v[176:179], v[56:59]
	v_mfma_f32_16x16x32_bf16 v[44:47], v[96:99], v[184:187], v[44:47]
	v_mfma_f32_16x16x32_bf16 v[40:43], v[104:107], v[184:187], v[40:43]
	v_mfma_f32_16x16x32_bf16 v[28:31], v[96:99], v[202:205], v[28:31]
	v_mfma_f32_16x16x32_bf16 v[24:27], v[104:107], v[202:205], v[24:27]
	v_mfma_f32_16x16x32_bf16 v[12:15], v[96:99], v[210:213], v[12:15]
	v_mfma_f32_16x16x32_bf16 v[8:11], v[104:107], v[210:213], v[8:11]
	v_mfma_f32_16x16x32_bf16 v[60:63], v[100:103], v[180:183], v[60:63]
	v_mfma_f32_16x16x32_bf16 v[56:59], v[112:115], v[180:183], v[56:59]
	v_mfma_f32_16x16x32_bf16 v[44:47], v[100:103], v[188:191], v[44:47]
	v_mfma_f32_16x16x32_bf16 v[40:43], v[112:115], v[188:191], v[40:43]
	v_mfma_f32_16x16x32_bf16 v[28:31], v[100:103], v[206:209], v[28:31]
	v_mfma_f32_16x16x32_bf16 v[24:27], v[112:115], v[206:209], v[24:27]
	v_mfma_f32_16x16x32_bf16 v[12:15], v[100:103], v[214:217], v[12:15]
	v_mfma_f32_16x16x32_bf16 v[8:11], v[112:115], v[214:217], v[8:11]
	s_setprio 0
	s_setprio 1
	v_mfma_f32_16x16x32_bf16 v[52:55], v[144:147], v[176:179], v[52:55]
	v_mfma_f32_16x16x32_bf16 v[48:51], v[152:155], v[176:179], v[48:51]
	v_mfma_f32_16x16x32_bf16 v[36:39], v[144:147], v[184:187], v[36:39]
	v_mfma_f32_16x16x32_bf16 v[32:35], v[152:155], v[184:187], v[32:35]
	v_mfma_f32_16x16x32_bf16 v[20:23], v[144:147], v[202:205], v[20:23]
	v_mfma_f32_16x16x32_bf16 v[16:19], v[152:155], v[202:205], v[16:19]
	v_mfma_f32_16x16x32_bf16 v[4:7], v[144:147], v[210:213], v[4:7]
	v_mfma_f32_16x16x32_bf16 v[0:3], v[152:155], v[210:213], v[0:3]
	v_mfma_f32_16x16x32_bf16 v[52:55], v[148:151], v[180:183], v[52:55]
	v_mfma_f32_16x16x32_bf16 v[48:51], v[172:175], v[180:183], v[48:51]
	v_mfma_f32_16x16x32_bf16 v[36:39], v[148:151], v[188:191], v[36:39]
	v_mfma_f32_16x16x32_bf16 v[32:35], v[172:175], v[188:191], v[32:35]
	v_mfma_f32_16x16x32_bf16 v[20:23], v[148:151], v[206:209], v[20:23]
	v_mfma_f32_16x16x32_bf16 v[16:19], v[172:175], v[206:209], v[16:19]
	v_mfma_f32_16x16x32_bf16 v[4:7], v[148:151], v[214:217], v[4:7]
	v_mfma_f32_16x16x32_bf16 v[0:3], v[172:175], v[214:217], v[0:3]
	s_setprio 0
	s_barrier
	s_add_i32 s74, 0, 0x18000
	s_add_i32 s75, 0, 0x1c000
	v_add_u32_e32 v112, s74, v195
	v_add_u32_e32 v172, s75, v195
	ds_read_b128 v[96:99], v112
	ds_read_b128 v[100:103], v112 offset:1024
	ds_read_b128 v[104:107], v112 offset:2048
	ds_read_b128 v[112:115], v112 offset:3072
	ds_read_b128 v[144:147], v172
	ds_read_b128 v[148:151], v172 offset:1024
	ds_read_b128 v[152:155], v172 offset:2048
	ds_read_b128 v[172:175], v172 offset:3072
	s_add_u32 s52, s52, 0x200000
	s_addc_u32 s53, s53, 0
	s_mov_b32 m0, s58
	s_nop 0
	ds_read_b128 v[176:179], v199 offset:32768
	ds_read_b128 v[180:183], v199 offset:33792
	ds_read_b128 v[184:187], v199 offset:34816
	ds_read_b128 v[188:191], v199 offset:35840
	ds_read_b128 v[202:205], v199 offset:36864
	ds_read_b128 v[206:209], v199 offset:37888
	ds_read_b128 v[210:213], v199 offset:38912
	ds_read_b128 v[214:217], v199 offset:39936
	global_load_lds_dwordx4 v156, s[52:53]
	s_nop 0
	s_mov_b32 m0, s59
	s_nop 0
	global_load_lds_dwordx4 v160, s[52:53]
	s_waitcnt vmcnt(8)
	s_waitcnt lgkmcnt(0)
	s_barrier
	s_setprio 1
	s_waitcnt lgkmcnt(0)
	v_mfma_f32_16x16x32_bf16 v[140:143], v[96:99], v[176:179], v[140:143]
	v_mfma_f32_16x16x32_bf16 v[136:139], v[104:107], v[176:179], v[136:139]
	v_mfma_f32_16x16x32_bf16 v[124:127], v[96:99], v[184:187], v[124:127]
	v_mfma_f32_16x16x32_bf16 v[120:123], v[104:107], v[184:187], v[120:123]
	v_mfma_f32_16x16x32_bf16 v[92:95], v[96:99], v[202:205], v[92:95]
	v_mfma_f32_16x16x32_bf16 v[88:91], v[104:107], v[202:205], v[88:91]
	v_mfma_f32_16x16x32_bf16 v[76:79], v[96:99], v[210:213], v[76:79]
	v_mfma_f32_16x16x32_bf16 v[72:75], v[104:107], v[210:213], v[72:75]
	v_mfma_f32_16x16x32_bf16 v[140:143], v[100:103], v[180:183], v[140:143]
	v_mfma_f32_16x16x32_bf16 v[136:139], v[112:115], v[180:183], v[136:139]
	v_mfma_f32_16x16x32_bf16 v[124:127], v[100:103], v[188:191], v[124:127]
	v_mfma_f32_16x16x32_bf16 v[120:123], v[112:115], v[188:191], v[120:123]
	v_mfma_f32_16x16x32_bf16 v[92:95], v[100:103], v[206:209], v[92:95]
	v_mfma_f32_16x16x32_bf16 v[88:91], v[112:115], v[206:209], v[88:91]
	v_mfma_f32_16x16x32_bf16 v[76:79], v[100:103], v[214:217], v[76:79]
	v_mfma_f32_16x16x32_bf16 v[72:75], v[112:115], v[214:217], v[72:75]
	s_setprio 0
	s_setprio 1
	v_mfma_f32_16x16x32_bf16 v[132:135], v[144:147], v[176:179], v[132:135]
	v_mfma_f32_16x16x32_bf16 v[128:131], v[152:155], v[176:179], v[128:131]
	v_mfma_f32_16x16x32_bf16 v[116:119], v[144:147], v[184:187], v[116:119]
	v_mfma_f32_16x16x32_bf16 v[108:111], v[152:155], v[184:187], v[108:111]
	v_mfma_f32_16x16x32_bf16 v[84:87], v[144:147], v[202:205], v[84:87]
	v_mfma_f32_16x16x32_bf16 v[80:83], v[152:155], v[202:205], v[80:83]
	v_mfma_f32_16x16x32_bf16 v[68:71], v[144:147], v[210:213], v[68:71]
	v_mfma_f32_16x16x32_bf16 v[64:67], v[152:155], v[210:213], v[64:67]
	v_mfma_f32_16x16x32_bf16 v[132:135], v[148:151], v[180:183], v[132:135]
	v_mfma_f32_16x16x32_bf16 v[128:131], v[172:175], v[180:183], v[128:131]
	v_mfma_f32_16x16x32_bf16 v[116:119], v[148:151], v[188:191], v[116:119]
	v_mfma_f32_16x16x32_bf16 v[108:111], v[172:175], v[188:191], v[108:111]
	v_mfma_f32_16x16x32_bf16 v[84:87], v[148:151], v[206:209], v[84:87]
	v_mfma_f32_16x16x32_bf16 v[80:83], v[172:175], v[206:209], v[80:83]
	v_mfma_f32_16x16x32_bf16 v[68:71], v[148:151], v[214:217], v[68:71]
	v_mfma_f32_16x16x32_bf16 v[64:67], v[172:175], v[214:217], v[64:67]
	s_setprio 0
	s_barrier
; #define PG8_STAGE(bufoff, gbase, voff) do { _Pragma("unroll") for (int _i = 0; _i < 2; ++_i) \
;         __builtin_amdgcn_global_load_lds((const unsigned*)((const char*)(gbase) + (voff)[_i]), (PG8_LAS unsigned*)(lds + (bufoff) + ldsw + _i * 8192), 16, 0, 0); } while (0)
; #define PG8_LDA(dst, b, h) do { _Pragma("unroll") for (int m = 0; m < 4; ++m) _Pragma("unroll") for (int k = 0; k < 2; ++k) dst[m][k] = *(const PG8_LAS bf16x8*)(lds + PG8_SA(b, h) + aoff + m * 2048 + k * 1024); } while (0)
; #define PG8_MMA(ai, bj, At, Bt) do { __builtin_amdgcn_s_setprio(1); _Pragma("unroll") for (int m = 0; m < 4; ++m) _Pragma("unroll") for (int n = 0; n < 2; ++n) _Pragma("unroll") for (int k = 0; k < 2; ++k) \
;         acc[ai][bj][m][n] = __builtin_amdgcn_mfma_f32_16x16x32_bf16(Bt[n][k], At[m][k], acc[ai][bj][m][n], 0, 0, 0); __builtin_amdgcn_s_setprio(0); } while (0)
; #define PG8_WAIT_V(n) asm volatile("s_waitcnt vmcnt(" #n ")" ::: "memory")
; #define PG8_WAIT_L(n) asm volatile("s_waitcnt lgkmcnt(" #n ")" ::: "memory")
; #define PG8_BAR __builtin_amdgcn_s_barrier()
; #define PG8_SCHED __builtin_amdgcn_sched_barrier(0)
; template <class Epi, class Sched, bool ALIGN_EPI = false, bool SP2 = false>
; __device__ __forceinline__ void gemm_phase(PG8_LAS unsigned char* lds, const Gemm g, const Sched& S, const Epi& E) {
;     ...
;             PG8_LDA(At, 1, 1); PG8_STAGE(PG8_SB(1, 0), b3, voffB); PG8_STAGE(PG8_SB(1, 1), b3 + hstep, voffB); PG8_STAGE(PG8_SA(1, 0), a3, voffA);
;             PG8_WAIT_V(8); PG8_WAIT_L(0); PG8_BAR; PG8_MMA(1, 0, At, B0); PG8_MMA(1, 1, At, B1); PG8_BAR; PG8_SCHED;
;     ...
;         if constexpr (ALIGN_EPI) { if (wr == 0) PG8_BAR; }
	s_add_i32 s52, s74, s55
	v_lshl_add_u64 v[192:193], v[192:193], 0, s[30:31]
	s_mov_b32 m0, s52
	ds_read_b128 v[176:179], v199 offset:49152
	ds_read_b128 v[180:183], v199 offset:50176
	ds_read_b128 v[184:187], v199 offset:51200
	ds_read_b128 v[188:191], v199 offset:52224
	ds_read_b128 v[202:205], v199 offset:53248
	ds_read_b128 v[206:209], v199 offset:54272
	ds_read_b128 v[210:213], v199 offset:55296
	ds_read_b128 v[214:217], v199 offset:56320
	global_load_lds_dwordx4 v[192:193], off
	s_add_i32 m0, s52, 0x2000
	s_add_u32 s50, s50, 0x200080
	v_lshl_add_u64 v[192:193], v[218:219], 0, s[30:31]
	s_addc_u32 s51, s51, 0
	s_add_i32 s52, s75, s55
	global_load_lds_dwordx4 v[192:193], off
	s_nop 0
	s_mov_b32 m0, s52
	s_nop 0
	global_load_lds_dwordx4 v158, s[50:51]
	s_nop 0
	s_add_i32 m0, s52, 0x2000
	s_nop 0
	global_load_lds_dwordx4 v162, s[50:51]
	v_lshl_add_u64 v[192:193], v[220:221], 0, s[30:31]
	s_mov_b32 m0, s61
	s_nop 0
	global_load_lds_dwordx4 v[192:193], off
	v_lshl_add_u64 v[192:193], v[222:223], 0, s[30:31]
	s_mov_b32 m0, s62
	s_nop 0
	global_load_lds_dwordx4 v[192:193], off
	s_waitcnt vmcnt(8)
	s_waitcnt lgkmcnt(0)
	s_barrier
	s_setprio 1
	s_waitcnt lgkmcnt(0)
	v_mfma_f32_16x16x32_bf16 v[60:63], v[96:99], v[176:179], v[60:63]
	v_mfma_f32_16x16x32_bf16 v[56:59], v[104:107], v[176:179], v[56:59]
	v_mfma_f32_16x16x32_bf16 v[44:47], v[96:99], v[184:187], v[44:47]
	v_mfma_f32_16x16x32_bf16 v[40:43], v[104:107], v[184:187], v[40:43]
	v_mfma_f32_16x16x32_bf16 v[28:31], v[96:99], v[202:205], v[28:31]
	v_mfma_f32_16x16x32_bf16 v[24:27], v[104:107], v[202:205], v[24:27]
	v_mfma_f32_16x16x32_bf16 v[12:15], v[96:99], v[210:213], v[12:15]
	v_mfma_f32_16x16x32_bf16 v[8:11], v[104:107], v[210:213], v[8:11]
	v_mfma_f32_16x16x32_bf16 v[60:63], v[100:103], v[180:183], v[60:63]
	v_mfma_f32_16x16x32_bf16 v[56:59], v[112:115], v[180:183], v[56:59]
	v_mfma_f32_16x16x32_bf16 v[44:47], v[100:103], v[188:191], v[44:47]
	v_mfma_f32_16x16x32_bf16 v[40:43], v[112:115], v[188:191], v[40:43]
	v_mfma_f32_16x16x32_bf16 v[28:31], v[100:103], v[206:209], v[28:31]
	v_mfma_f32_16x16x32_bf16 v[24:27], v[112:115], v[206:209], v[24:27]
	v_mfma_f32_16x16x32_bf16 v[12:15], v[100:103], v[214:217], v[12:15]
	v_mfma_f32_16x16x32_bf16 v[8:11], v[112:115], v[214:217], v[8:11]
	s_setprio 0
	s_setprio 1
	v_mfma_f32_16x16x32_bf16 v[52:55], v[144:147], v[176:179], v[52:55]
	v_mfma_f32_16x16x32_bf16 v[48:51], v[152:155], v[176:179], v[48:51]
	v_mfma_f32_16x16x32_bf16 v[36:39], v[144:147], v[184:187], v[36:39]
	v_mfma_f32_16x16x32_bf16 v[32:35], v[152:155], v[184:187], v[32:35]
	v_mfma_f32_16x16x32_bf16 v[20:23], v[144:147], v[202:205], v[20:23]
	v_mfma_f32_16x16x32_bf16 v[16:19], v[152:155], v[202:205], v[16:19]
	v_mfma_f32_16x16x32_bf16 v[4:7], v[144:147], v[210:213], v[4:7]
	v_mfma_f32_16x16x32_bf16 v[0:3], v[152:155], v[210:213], v[0:3]
	v_mfma_f32_16x16x32_bf16 v[52:55], v[148:151], v[180:183], v[52:55]
	v_mfma_f32_16x16x32_bf16 v[48:51], v[172:175], v[180:183], v[48:51]
	v_mfma_f32_16x16x32_bf16 v[36:39], v[148:151], v[188:191], v[36:39]
	v_mfma_f32_16x16x32_bf16 v[32:35], v[172:175], v[188:191], v[32:35]
	v_mfma_f32_16x16x32_bf16 v[20:23], v[148:151], v[206:209], v[20:23]
	v_mfma_f32_16x16x32_bf16 v[16:19], v[172:175], v[206:209], v[16:19]
	v_mfma_f32_16x16x32_bf16 v[4:7], v[148:151], v[214:217], v[4:7]
	v_mfma_f32_16x16x32_bf16 v[0:3], v[172:175], v[214:217], v[0:3]
	s_setprio 0
	s_barrier
	s_add_i32 s73, s73, 2
	s_add_u32 s48, s48, 0x100
	s_addc_u32 s49, s49, 0
	s_add_u32 s71, s71, 0x100
	s_addc_u32 s72, s72, 0
	s_cmpk_gt_u32 s73, 0x7d
	s_cbranch_scc0 .LBB0_1114
	s_and_b64 vcc, exec, s[34:35]
	s_cbranch_vccz .LBB0_1117
	s_barrier
